# K-loop load segments issue their fragment ds_reads first, then the SALU / m0 / LDS-DMA part; loop-control SALU moved from after the loop-back barrier into the last MFMA block's shadow
# baseline (speedup 1.0000x reference)
; #define PG8_STAGE(bufoff, gbase, voff) do { _Pragma("unroll") for (int _i = 0; _i < 2; ++_i) \
;         __builtin_amdgcn_global_load_lds((const unsigned*)((const char*)(gbase) + (voff)[_i]), (PG8_LAS unsigned*)(lds + (bufoff) + ldsw + _i * 8192), 16, 0, 0); } while (0)
; #define PG8_LDA(dst, b, h) do { _Pragma("unroll") for (int m = 0; m < 4; ++m) _Pragma("unroll") for (int k = 0; k < 2; ++k) dst[m][k] = *(const PG8_LAS bf16x8*)(lds + PG8_SA(b, h) + aoff + m * 2048 + k * 1024); } while (0)
; #define PG8_LDB(dst, b, h) do { _Pragma("unroll") for (int n = 0; n < 2; ++n) _Pragma("unroll") for (int k = 0; k < 2; ++k) dst[n][k] = *(const PG8_LAS bf16x8*)(lds + PG8_SB(b, h) + boff + n * 2048 + k * 1024); } while (0)
; #define PG8_WAIT_V(n) asm volatile("s_waitcnt vmcnt(" #n ")" ::: "memory")
; #define PG8_WAIT_L(n) asm volatile("s_waitcnt lgkmcnt(" #n ")" ::: "memory")
; #define PG8_BAR __builtin_amdgcn_s_barrier()
; #define PG8_SCHED __builtin_amdgcn_sched_barrier(0)
; template <class Epi, class Sched, bool ALIGN_EPI = false, bool SP2 = false>
; __device__ __forceinline__ void gemm_phase(PG8_LAS unsigned char* lds, const Gemm g, const Sched& S, const Epi& E) {
;     ...
;         const char* nA = has_next ? (const char*)g.A + (size_t)nxt.pm * tstep : cA; const char* nB = has_next ? (const char*)g.Bt + (size_t)nxt.pn * tstep : cB;
;         for (int t = 0; t < nt; t += 2) {
;             const bool last = (t == nt - 2);
;             const char* a1 = cA + (size_t)(t + 1) * kstep;
;             const char* a2 = last ? nA : cA + (size_t)(t + 2) * kstep; const char* b2 = last ? nB : cB + (size_t)(t + 2) * kstep;
;             const char* a3 = a2 + kstep; const char* b3 = b2 + kstep;
;             if (last && has_next) S.a_ready(nxt);
;             if constexpr (SP2) {
;             PG8_LDB(B0, 0, 0); PG8_LDB(B1, 0, 1); PG8_SCHED; PG8_LDA(At, 0, 0); PG8_STAGE(PG8_SA(1, 1), a1 + hstep, voffA);
;             PG8_WAIT_V(8); PG8_WAIT_L(0); PG8_BAR; PG8_MMA(0, 0, At, B0); PG8_MMA(0, 1, At, B1); PG8_BAR; PG8_SCHED;
;             PG8_LDA(At, 0, 1); PG8_STAGE(PG8_SB(0, 0), b2, voffB); PG8_STAGE(PG8_SB(0, 1), b2 + hstepB, voffB); PG8_STAGE(PG8_SA(0, 0), a2, voffA);
;             PG8_WAIT_V(8); PG8_WAIT_L(0); PG8_BAR; PG8_MMA(1, 0, At, B0); PG8_MMA(1, 1, At, B1); PG8_BAR; PG8_SCHED;
.LBB0_169:
	s_add_u32 s93, s46, 0x100
	s_addc_u32 s94, s47, 0
	s_ashr_i32 s69, s68, 31
	s_lshl_b64 s[4:5], s[68:69], 20
	s_add_u32 s76, s52, s4
	s_addc_u32 s77, s53, s5
	s_and_b64 s[4:5], s[38:39], exec
	s_cselect_b32 s4, s77, s71
	s_cselect_b32 s5, s76, s70
	s_ashr_i32 s63, s62, 31
	s_lshl_b64 s[6:7], s[62:63], 20
	v_readlane_b32 s8, v249, 19
	v_readlane_b32 s9, v249, 20
	s_add_u32 s72, s8, s6
	s_addc_u32 s73, s9, s7
	s_and_b64 s[6:7], s[38:39], exec
	s_cselect_b32 s6, s73, s47
	s_cselect_b32 s7, s72, s46
	s_add_u32 s8, s70, 0x80080
	s_addc_u32 s9, s71, 0
	v_lshl_add_u64 v[144:145], s[8:9], 0, v[140:141]
	v_lshl_add_u64 v[146:147], s[8:9], 0, v[142:143]
	s_mov_b32 s8, -2
	s_mov_b64 s[46:47], 0
	v_add_u32_e32 v186, 0x10000, v139
	v_add_u32_e32 v187, 0x14000, v139
	v_add_u32_e32 v198, 0x18000, v139
	v_add_u32_e32 v199, 0x1c000, v139
	s_add_u32 s9, s70, s46
	s_addc_u32 s10, s71, s47
	s_add_u32 s9, s9, 0x100
	s_addc_u32 s10, s10, 0
	s_add_u32 s100, s9, 0x7ff80
	s_addc_u32 s101, s10, 0
	s_add_u32 s11, s93, s46
	s_addc_u32 s12, s94, s47
	s_add_i32 s13, 0, 0x10000
	s_cmpk_eq_i32 s46, 0xf00
	s_cselect_b32 s85, s4, s10
	s_cselect_b32 s84, s5, s9
	s_cselect_b32 s81, s6, s12
	s_cselect_b32 s80, s7, s11
	s_add_i32 s9, 0, 0x14000
	ds_read_b128 v[148:151], v186
	ds_read_b128 v[152:155], v186 offset:1024
	ds_read_b128 v[156:159], v186 offset:2048
	ds_read_b128 v[160:163], v186 offset:3072
	ds_read_b128 v[166:169], v187
	ds_read_b128 v[170:173], v187 offset:1024
	ds_read_b128 v[174:177], v187 offset:2048
	ds_read_b128 v[178:181], v187 offset:3072
	s_add_i32 m0, s1, 0xc000
	ds_read_b128 v[182:185], v165
	ds_read_b128 v[206:209], v165 offset:1024
	ds_read_b128 v[210:213], v165 offset:2048
	ds_read_b128 v[214:217], v165 offset:3072
	ds_read_b128 v[218:221], v165 offset:4096
	ds_read_b128 v[236:239], v165 offset:5120
	ds_read_b128 v[240:243], v165 offset:6144
	ds_read_b128 v[244:247], v165 offset:7168
	global_load_lds_dwordx4 v140, s[100:101]
	s_add_i32 m0, s1, 0xe000
	s_nop 0
	global_load_lds_dwordx4 v142, s[100:101]
	s_waitcnt vmcnt(8)
	s_waitcnt lgkmcnt(0)
	s_barrier
	v_mfma_f32_16x16x32_bf16 v[126:129], v[148:151], v[182:185], 0
	v_mfma_f32_16x16x32_bf16 v[122:125], v[156:159], v[182:185], 0
	v_mfma_f32_16x16x32_bf16 v[118:121], v[148:151], v[210:213], 0
	v_mfma_f32_16x16x32_bf16 v[114:117], v[156:159], v[210:213], 0
	v_mfma_f32_16x16x32_bf16 v[110:113], v[148:151], v[218:221], 0
	v_mfma_f32_16x16x32_bf16 v[106:109], v[156:159], v[218:221], 0
	v_mfma_f32_16x16x32_bf16 v[102:105], v[148:151], v[240:243], 0
	v_mfma_f32_16x16x32_bf16 v[98:101], v[156:159], v[240:243], 0
	v_mfma_f32_16x16x32_bf16 v[126:129], v[152:155], v[206:209], v[126:129]
	v_mfma_f32_16x16x32_bf16 v[122:125], v[160:163], v[206:209], v[122:125]
	v_mfma_f32_16x16x32_bf16 v[118:121], v[152:155], v[214:217], v[118:121]
	v_mfma_f32_16x16x32_bf16 v[114:117], v[160:163], v[214:217], v[114:117]
	v_mfma_f32_16x16x32_bf16 v[110:113], v[152:155], v[236:239], v[110:113]
	v_mfma_f32_16x16x32_bf16 v[106:109], v[160:163], v[236:239], v[106:109]
	v_mfma_f32_16x16x32_bf16 v[102:105], v[152:155], v[244:247], v[102:105]
	v_mfma_f32_16x16x32_bf16 v[98:101], v[160:163], v[244:247], v[98:101]
	v_mfma_f32_16x16x32_bf16 v[94:97], v[166:169], v[182:185], 0
	v_mfma_f32_16x16x32_bf16 v[90:93], v[174:177], v[182:185], 0
	v_mfma_f32_16x16x32_bf16 v[86:89], v[166:169], v[210:213], 0
	v_mfma_f32_16x16x32_bf16 v[82:85], v[174:177], v[210:213], 0
	v_mfma_f32_16x16x32_bf16 v[78:81], v[166:169], v[218:221], 0
	v_mfma_f32_16x16x32_bf16 v[74:77], v[174:177], v[218:221], 0
	v_mfma_f32_16x16x32_bf16 v[70:73], v[166:169], v[240:243], 0
	v_mfma_f32_16x16x32_bf16 v[66:69], v[174:177], v[240:243], 0
	v_mfma_f32_16x16x32_bf16 v[94:97], v[170:173], v[206:209], v[94:97]
	v_mfma_f32_16x16x32_bf16 v[90:93], v[178:181], v[206:209], v[90:93]
	v_mfma_f32_16x16x32_bf16 v[86:89], v[170:173], v[214:217], v[86:89]
	v_mfma_f32_16x16x32_bf16 v[82:85], v[178:181], v[214:217], v[82:85]
	v_mfma_f32_16x16x32_bf16 v[78:81], v[170:173], v[236:239], v[78:81]
	v_mfma_f32_16x16x32_bf16 v[74:77], v[178:181], v[236:239], v[74:77]
	v_mfma_f32_16x16x32_bf16 v[70:73], v[170:173], v[244:247], v[70:73]
	v_mfma_f32_16x16x32_bf16 v[66:69], v[178:181], v[244:247], v[66:69]
	s_barrier
	ds_read_b128 v[182:185], v165 offset:16384
	ds_read_b128 v[206:209], v165 offset:17408
	ds_read_b128 v[210:213], v165 offset:18432
	ds_read_b128 v[214:217], v165 offset:19456
	ds_read_b128 v[218:221], v165 offset:20480
	ds_read_b128 v[236:239], v165 offset:21504
	ds_read_b128 v[240:243], v165 offset:22528
	ds_read_b128 v[244:247], v165 offset:23552
	s_add_i32 s10, s13, s0
	s_mov_b32 m0, s10
	s_nop 0
	global_load_lds_dwordx4 v132, s[80:81]
	s_add_i32 m0, s10, 0x2000
	s_add_u32 s10, s80, 0x20000
	s_addc_u32 s11, s81, 0
	s_add_i32 s9, s9, s0
	global_load_lds_dwordx4 v136, s[80:81]
	s_mov_b32 m0, s9
	s_nop 0
	global_load_lds_dwordx4 v132, s[10:11]
	s_add_i32 m0, s9, 0x2000
	s_nop 0
	global_load_lds_dwordx4 v136, s[10:11]
	s_mov_b32 m0, s1
	s_nop 0
	global_load_lds_dwordx4 v130, s[84:85]
	s_mov_b32 m0, s25
	s_nop 0
	global_load_lds_dwordx4 v134, s[84:85]
	s_waitcnt vmcnt(8)
	s_waitcnt lgkmcnt(0)
	s_barrier
; #define PG8_STAGE(bufoff, gbase, voff) do { _Pragma("unroll") for (int _i = 0; _i < 2; ++_i) \
;         __builtin_amdgcn_global_load_lds((const unsigned*)((const char*)(gbase) + (voff)[_i]), (PG8_LAS unsigned*)(lds + (bufoff) + ldsw + _i * 8192), 16, 0, 0); } while (0)
; #define PG8_LDA(dst, b, h) do { _Pragma("unroll") for (int m = 0; m < 4; ++m) _Pragma("unroll") for (int k = 0; k < 2; ++k) dst[m][k] = *(const PG8_LAS bf16x8*)(lds + PG8_SA(b, h) + aoff + m * 2048 + k * 1024); } while (0)
; #define PG8_LDB(dst, b, h) do { _Pragma("unroll") for (int n = 0; n < 2; ++n) _Pragma("unroll") for (int k = 0; k < 2; ++k) dst[n][k] = *(const PG8_LAS bf16x8*)(lds + PG8_SB(b, h) + boff + n * 2048 + k * 1024); } while (0)
; #define PG8_MMA(ai, bj, At, Bt) do { __builtin_amdgcn_s_setprio(1); _Pragma("unroll") for (int m = 0; m < 4; ++m) _Pragma("unroll") for (int n = 0; n < 2; ++n) _Pragma("unroll") for (int k = 0; k < 2; ++k) \
;         acc[ai][bj][m][n] = __builtin_amdgcn_mfma_f32_16x16x32_bf16(Bt[n][k], At[m][k], acc[ai][bj][m][n], 0, 0, 0); __builtin_amdgcn_s_setprio(0); } while (0)
; #define PG8_WAIT_V(n) asm volatile("s_waitcnt vmcnt(" #n ")" ::: "memory")
; #define PG8_WAIT_L(n) asm volatile("s_waitcnt lgkmcnt(" #n ")" ::: "memory")
; #define PG8_BAR __builtin_amdgcn_s_barrier()
; #define PG8_SCHED __builtin_amdgcn_sched_barrier(0)
; template <class Epi, class Sched, bool ALIGN_EPI = false, bool SP2 = false>
; __device__ __forceinline__ void gemm_phase(PG8_LAS unsigned char* lds, const Gemm g, const Sched& S, const Epi& E) {
;     ...
;             PG8_WAIT_V(8); PG8_WAIT_L(0); PG8_BAR; PG8_MMA(1, 0, At, B0); PG8_MMA(1, 1, At, B1); PG8_BAR; PG8_SCHED;
;             PG8_LDB(B0, 1, 0); PG8_LDB(B1, 1, 1); PG8_SCHED; PG8_LDA(At, 1, 0); PG8_STAGE(PG8_SA(0, 1), a2 + hstep, voffA);
;             PG8_WAIT_V(8); PG8_WAIT_L(0); PG8_BAR; PG8_MMA(0, 0, At, B0); PG8_MMA(0, 1, At, B1); PG8_BAR; PG8_SCHED;
	v_mfma_f32_16x16x32_bf16 v[62:65], v[148:151], v[182:185], 0
	v_mfma_f32_16x16x32_bf16 v[58:61], v[156:159], v[182:185], 0
	v_mfma_f32_16x16x32_bf16 v[54:57], v[148:151], v[210:213], 0
	v_mfma_f32_16x16x32_bf16 v[50:53], v[156:159], v[210:213], 0
	v_mfma_f32_16x16x32_bf16 v[46:49], v[148:151], v[218:221], 0
	v_mfma_f32_16x16x32_bf16 v[42:45], v[156:159], v[218:221], 0
	v_mfma_f32_16x16x32_bf16 v[38:41], v[148:151], v[240:243], 0
	v_mfma_f32_16x16x32_bf16 v[34:37], v[156:159], v[240:243], 0
	v_mfma_f32_16x16x32_bf16 v[62:65], v[152:155], v[206:209], v[62:65]
	v_mfma_f32_16x16x32_bf16 v[58:61], v[160:163], v[206:209], v[58:61]
	v_mfma_f32_16x16x32_bf16 v[54:57], v[152:155], v[214:217], v[54:57]
	v_mfma_f32_16x16x32_bf16 v[50:53], v[160:163], v[214:217], v[50:53]
	v_mfma_f32_16x16x32_bf16 v[46:49], v[152:155], v[236:239], v[46:49]
	v_mfma_f32_16x16x32_bf16 v[42:45], v[160:163], v[236:239], v[42:45]
	v_mfma_f32_16x16x32_bf16 v[38:41], v[152:155], v[244:247], v[38:41]
	v_mfma_f32_16x16x32_bf16 v[34:37], v[160:163], v[244:247], v[34:37]
	v_mfma_f32_16x16x32_bf16 v[30:33], v[166:169], v[182:185], 0
	v_mfma_f32_16x16x32_bf16 v[26:29], v[174:177], v[182:185], 0
	v_mfma_f32_16x16x32_bf16 v[22:25], v[166:169], v[210:213], 0
	v_mfma_f32_16x16x32_bf16 v[18:21], v[174:177], v[210:213], 0
	v_mfma_f32_16x16x32_bf16 v[14:17], v[166:169], v[218:221], 0
	v_mfma_f32_16x16x32_bf16 v[10:13], v[174:177], v[218:221], 0
	v_mfma_f32_16x16x32_bf16 v[6:9], v[166:169], v[240:243], 0
	v_mfma_f32_16x16x32_bf16 v[2:5], v[174:177], v[240:243], 0
	v_mfma_f32_16x16x32_bf16 v[30:33], v[170:173], v[206:209], v[30:33]
	v_mfma_f32_16x16x32_bf16 v[26:29], v[178:181], v[206:209], v[26:29]
	v_mfma_f32_16x16x32_bf16 v[22:25], v[170:173], v[214:217], v[22:25]
	v_mfma_f32_16x16x32_bf16 v[18:21], v[178:181], v[214:217], v[18:21]
	v_mfma_f32_16x16x32_bf16 v[14:17], v[170:173], v[236:239], v[14:17]
	v_mfma_f32_16x16x32_bf16 v[10:13], v[178:181], v[236:239], v[10:13]
	v_mfma_f32_16x16x32_bf16 v[6:9], v[170:173], v[244:247], v[6:9]
	v_mfma_f32_16x16x32_bf16 v[2:5], v[178:181], v[244:247], v[2:5]
	s_barrier
	ds_read_b128 v[148:151], v198
	ds_read_b128 v[152:155], v198 offset:1024
	ds_read_b128 v[156:159], v198 offset:2048
	ds_read_b128 v[160:163], v198 offset:3072
	ds_read_b128 v[166:169], v199
	ds_read_b128 v[170:173], v199 offset:1024
	ds_read_b128 v[174:177], v199 offset:2048
	ds_read_b128 v[178:181], v199 offset:3072
	ds_read_b128 v[182:185], v165 offset:32768
	ds_read_b128 v[206:209], v165 offset:33792
	ds_read_b128 v[210:213], v165 offset:34816
	ds_read_b128 v[214:217], v165 offset:35840
	ds_read_b128 v[218:221], v165 offset:36864
	ds_read_b128 v[236:239], v165 offset:37888
	ds_read_b128 v[240:243], v165 offset:38912
	ds_read_b128 v[244:247], v165 offset:39936
	s_add_i32 s9, 0, 0x18000
	s_add_i32 s12, 0, 0x1c000
	s_add_u32 s10, s84, 0x80000
	s_addc_u32 s11, s85, 0
	s_mov_b32 m0, s42
	s_nop 0
	global_load_lds_dwordx4 v130, s[10:11]
	s_mov_b32 m0, s51
	s_nop 0
	global_load_lds_dwordx4 v134, s[10:11]
	s_waitcnt vmcnt(8)
	s_waitcnt lgkmcnt(0)
	s_barrier
	v_mfma_f32_16x16x32_bf16 v[126:129], v[148:151], v[182:185], v[126:129]
	v_mfma_f32_16x16x32_bf16 v[122:125], v[156:159], v[182:185], v[122:125]
	v_mfma_f32_16x16x32_bf16 v[118:121], v[148:151], v[210:213], v[118:121]
	v_mfma_f32_16x16x32_bf16 v[114:117], v[156:159], v[210:213], v[114:117]
	v_mfma_f32_16x16x32_bf16 v[110:113], v[148:151], v[218:221], v[110:113]
	v_mfma_f32_16x16x32_bf16 v[106:109], v[156:159], v[218:221], v[106:109]
	v_mfma_f32_16x16x32_bf16 v[102:105], v[148:151], v[240:243], v[102:105]
	v_mfma_f32_16x16x32_bf16 v[98:101], v[156:159], v[240:243], v[98:101]
	v_mfma_f32_16x16x32_bf16 v[126:129], v[152:155], v[206:209], v[126:129]
	v_mfma_f32_16x16x32_bf16 v[122:125], v[160:163], v[206:209], v[122:125]
	v_mfma_f32_16x16x32_bf16 v[118:121], v[152:155], v[214:217], v[118:121]
	v_mfma_f32_16x16x32_bf16 v[114:117], v[160:163], v[214:217], v[114:117]
	v_mfma_f32_16x16x32_bf16 v[110:113], v[152:155], v[236:239], v[110:113]
	v_mfma_f32_16x16x32_bf16 v[106:109], v[160:163], v[236:239], v[106:109]
	v_mfma_f32_16x16x32_bf16 v[102:105], v[152:155], v[244:247], v[102:105]
	v_mfma_f32_16x16x32_bf16 v[98:101], v[160:163], v[244:247], v[98:101]
	v_mfma_f32_16x16x32_bf16 v[94:97], v[166:169], v[182:185], v[94:97]
	v_mfma_f32_16x16x32_bf16 v[90:93], v[174:177], v[182:185], v[90:93]
	v_mfma_f32_16x16x32_bf16 v[86:89], v[166:169], v[210:213], v[86:89]
	v_mfma_f32_16x16x32_bf16 v[82:85], v[174:177], v[210:213], v[82:85]
	v_mfma_f32_16x16x32_bf16 v[78:81], v[166:169], v[218:221], v[78:81]
	v_mfma_f32_16x16x32_bf16 v[74:77], v[174:177], v[218:221], v[74:77]
	v_mfma_f32_16x16x32_bf16 v[70:73], v[166:169], v[240:243], v[70:73]
	v_mfma_f32_16x16x32_bf16 v[66:69], v[174:177], v[240:243], v[66:69]
	v_mfma_f32_16x16x32_bf16 v[94:97], v[170:173], v[206:209], v[94:97]
	v_mfma_f32_16x16x32_bf16 v[90:93], v[178:181], v[206:209], v[90:93]
	v_mfma_f32_16x16x32_bf16 v[86:89], v[170:173], v[214:217], v[86:89]
	v_mfma_f32_16x16x32_bf16 v[82:85], v[178:181], v[214:217], v[82:85]
	v_mfma_f32_16x16x32_bf16 v[78:81], v[170:173], v[236:239], v[78:81]
	v_mfma_f32_16x16x32_bf16 v[74:77], v[178:181], v[236:239], v[74:77]
	v_mfma_f32_16x16x32_bf16 v[70:73], v[170:173], v[244:247], v[70:73]
	v_mfma_f32_16x16x32_bf16 v[66:69], v[178:181], v[244:247], v[66:69]
	s_barrier
; #define PG8_STAGE(bufoff, gbase, voff) do { _Pragma("unroll") for (int _i = 0; _i < 2; ++_i) \
;         __builtin_amdgcn_global_load_lds((const unsigned*)((const char*)(gbase) + (voff)[_i]), (PG8_LAS unsigned*)(lds + (bufoff) + ldsw + _i * 8192), 16, 0, 0); } while (0)
; #define PG8_LDA(dst, b, h) do { _Pragma("unroll") for (int m = 0; m < 4; ++m) _Pragma("unroll") for (int k = 0; k < 2; ++k) dst[m][k] = *(const PG8_LAS bf16x8*)(lds + PG8_SA(b, h) + aoff + m * 2048 + k * 1024); } while (0)
; #define PG8_LDB(dst, b, h) do { _Pragma("unroll") for (int n = 0; n < 2; ++n) _Pragma("unroll") for (int k = 0; k < 2; ++k) dst[n][k] = *(const PG8_LAS bf16x8*)(lds + PG8_SB(b, h) + boff + n * 2048 + k * 1024); } while (0)
; #define PG8_MMA(ai, bj, At, Bt) do { __builtin_amdgcn_s_setprio(1); _Pragma("unroll") for (int m = 0; m < 4; ++m) _Pragma("unroll") for (int n = 0; n < 2; ++n) _Pragma("unroll") for (int k = 0; k < 2; ++k) \
;         acc[ai][bj][m][n] = __builtin_amdgcn_mfma_f32_16x16x32_bf16(Bt[n][k], At[m][k], acc[ai][bj][m][n], 0, 0, 0); __builtin_amdgcn_s_setprio(0); } while (0)
; #define PG8_WAIT_V(n) asm volatile("s_waitcnt vmcnt(" #n ")" ::: "memory")
; template <class Epi, class Sched, bool ALIGN_EPI = false, bool SP2 = false>
; __device__ __forceinline__ void gemm_phase(PG8_LAS unsigned char* lds, const Gemm g, const Sched& S, const Epi& E) {
;     ...
;             PG8_LDB(B0, 0, 0); PG8_LDB(B1, 0, 1); PG8_SCHED; PG8_LDA(At, 0, 0); PG8_STAGE(PG8_SA(1, 1), a1 + hstep, voffA);
;             PG8_WAIT_V(8); PG8_WAIT_L(0); PG8_BAR; PG8_MMA(0, 0, At, B0); PG8_MMA(0, 1, At, B1); PG8_BAR; PG8_SCHED;
;             PG8_LDA(At, 0, 1); PG8_STAGE(PG8_SB(0, 0), b2, voffB); PG8_STAGE(PG8_SB(0, 1), b2 + hstepB, voffB); PG8_STAGE(PG8_SA(0, 0), a2, voffA);
;             PG8_WAIT_V(8); PG8_WAIT_L(0); PG8_BAR; PG8_MMA(1, 0, At, B0); PG8_MMA(1, 1, At, B1); PG8_BAR; PG8_SCHED;
;             PG8_LDB(B0, 1, 0); PG8_LDB(B1, 1, 1); PG8_SCHED; PG8_LDA(At, 1, 0); PG8_STAGE(PG8_SA(0, 1), a2 + hstep, voffA);
;             PG8_WAIT_V(8); PG8_WAIT_L(0); PG8_BAR; PG8_MMA(0, 0, At, B0); PG8_MMA(0, 1, At, B1); PG8_BAR; PG8_SCHED;
;             PG8_LDA(At, 1, 1); PG8_STAGE(PG8_SB(1, 0), b3, voffB); PG8_STAGE(PG8_SB(1, 1), b3 + hstepB, voffB); PG8_STAGE(PG8_SA(1, 0), a3, voffA);
;             PG8_WAIT_V(8); PG8_WAIT_L(0); PG8_BAR; PG8_MMA(1, 0, At, B0); PG8_MMA(1, 1, At, B1); PG8_BAR; PG8_SCHED;
	ds_read_b128 v[182:185], v165 offset:49152
	ds_read_b128 v[206:209], v165 offset:50176
	ds_read_b128 v[210:213], v165 offset:51200
	ds_read_b128 v[214:217], v165 offset:52224
	ds_read_b128 v[218:221], v165 offset:53248
	ds_read_b128 v[236:239], v165 offset:54272
	ds_read_b128 v[240:243], v165 offset:55296
	ds_read_b128 v[244:247], v165 offset:56320
	s_add_i32 s9, s9, s0
	s_mov_b32 m0, s9
	s_add_u32 s100, s80, s60
	s_addc_u32 s101, s81, s61
	global_load_lds_dwordx4 v132, s[100:101]
	s_add_i32 m0, s9, 0x2000
	s_add_u32 s10, s80, 0x20080
	s_addc_u32 s11, s81, 0
	s_add_i32 s9, s12, s0
	global_load_lds_dwordx4 v136, s[100:101]
	s_mov_b32 m0, s9
	s_nop 0
	global_load_lds_dwordx4 v132, s[10:11]
	s_add_i32 m0, s9, 0x2000
	s_nop 0
	global_load_lds_dwordx4 v136, s[10:11]
	s_mov_b32 m0, s66
	s_add_u32 s100, s84, s60
	s_addc_u32 s101, s85, s61
	global_load_lds_dwordx4 v130, s[100:101]
	s_mov_b32 m0, s67
	s_nop 0
	global_load_lds_dwordx4 v134, s[100:101]
	s_waitcnt vmcnt(8)
	s_waitcnt lgkmcnt(0)
	s_barrier
	v_mfma_f32_16x16x32_bf16 v[62:65], v[148:151], v[182:185], v[62:65]
	v_mfma_f32_16x16x32_bf16 v[58:61], v[156:159], v[182:185], v[58:61]
	v_mfma_f32_16x16x32_bf16 v[54:57], v[148:151], v[210:213], v[54:57]
	v_mfma_f32_16x16x32_bf16 v[50:53], v[156:159], v[210:213], v[50:53]
	v_mfma_f32_16x16x32_bf16 v[46:49], v[148:151], v[218:221], v[46:49]
	v_mfma_f32_16x16x32_bf16 v[42:45], v[156:159], v[218:221], v[42:45]
	v_mfma_f32_16x16x32_bf16 v[38:41], v[148:151], v[240:243], v[38:41]
	v_mfma_f32_16x16x32_bf16 v[34:37], v[156:159], v[240:243], v[34:37]
	v_mfma_f32_16x16x32_bf16 v[62:65], v[152:155], v[206:209], v[62:65]
	v_mfma_f32_16x16x32_bf16 v[58:61], v[160:163], v[206:209], v[58:61]
	v_mfma_f32_16x16x32_bf16 v[54:57], v[152:155], v[214:217], v[54:57]
	v_mfma_f32_16x16x32_bf16 v[50:53], v[160:163], v[214:217], v[50:53]
	v_mfma_f32_16x16x32_bf16 v[46:49], v[152:155], v[236:239], v[46:49]
	v_mfma_f32_16x16x32_bf16 v[42:45], v[160:163], v[236:239], v[42:45]
	v_mfma_f32_16x16x32_bf16 v[38:41], v[152:155], v[244:247], v[38:41]
	v_mfma_f32_16x16x32_bf16 v[34:37], v[160:163], v[244:247], v[34:37]
	v_mfma_f32_16x16x32_bf16 v[30:33], v[166:169], v[182:185], v[30:33]
	v_mfma_f32_16x16x32_bf16 v[26:29], v[174:177], v[182:185], v[26:29]
	v_mfma_f32_16x16x32_bf16 v[22:25], v[166:169], v[210:213], v[22:25]
	v_mfma_f32_16x16x32_bf16 v[18:21], v[174:177], v[210:213], v[18:21]
	v_mfma_f32_16x16x32_bf16 v[14:17], v[166:169], v[218:221], v[14:17]
	v_mfma_f32_16x16x32_bf16 v[10:13], v[174:177], v[218:221], v[10:13]
	s_add_i32 s8, s8, 2
	v_mfma_f32_16x16x32_bf16 v[6:9], v[166:169], v[240:243], v[6:9]
	s_add_u32 s46, s46, 0x100
	s_addc_u32 s47, s47, 0
	v_mfma_f32_16x16x32_bf16 v[2:5], v[174:177], v[240:243], v[2:5]
	s_cmp_gt_u32 s8, 29
	v_mfma_f32_16x16x32_bf16 v[30:33], v[170:173], v[206:209], v[30:33]
	v_mfma_f32_16x16x32_bf16 v[26:29], v[178:181], v[206:209], v[26:29]
	v_mfma_f32_16x16x32_bf16 v[22:25], v[170:173], v[214:217], v[22:25]
	v_mfma_f32_16x16x32_bf16 v[18:21], v[178:181], v[214:217], v[18:21]
	v_mfma_f32_16x16x32_bf16 v[14:17], v[170:173], v[236:239], v[14:17]
	v_mfma_f32_16x16x32_bf16 v[10:13], v[178:181], v[236:239], v[10:13]
	v_mfma_f32_16x16x32_bf16 v[6:9], v[170:173], v[244:247], v[6:9]
	v_mfma_f32_16x16x32_bf16 v[2:5], v[178:181], v[244:247], v[2:5]
	s_barrier
.LBB0_170:
	ds_read_b128 v[148:151], v186
	ds_read_b128 v[152:155], v186 offset:1024
	ds_read_b128 v[156:159], v186 offset:2048
	ds_read_b128 v[160:163], v186 offset:3072
	ds_read_b128 v[166:169], v187
	ds_read_b128 v[170:173], v187 offset:1024
	ds_read_b128 v[174:177], v187 offset:2048
	ds_read_b128 v[178:181], v187 offset:3072
	ds_read_b128 v[182:185], v165
	ds_read_b128 v[206:209], v165 offset:1024
	ds_read_b128 v[210:213], v165 offset:2048
	ds_read_b128 v[214:217], v165 offset:3072
	ds_read_b128 v[218:221], v165 offset:4096
	ds_read_b128 v[236:239], v165 offset:5120
	ds_read_b128 v[240:243], v165 offset:6144
	ds_read_b128 v[244:247], v165 offset:7168
	s_add_u32 s9, s70, s46
	s_addc_u32 s10, s71, s47
	s_add_u32 s9, s9, 0x100
	s_addc_u32 s10, s10, 0
	s_add_u32 s100, s9, 0x7ff80
	s_addc_u32 s101, s10, 0
	s_add_u32 s11, s93, s46
	s_addc_u32 s12, s94, s47
	s_add_i32 s13, 0, 0x10000
	s_cmpk_eq_i32 s46, 0xf00
	s_cselect_b32 s85, s4, s10
	s_cselect_b32 s84, s5, s9
	s_cselect_b32 s81, s6, s12
	s_cselect_b32 s80, s7, s11
	s_add_i32 s9, 0, 0x14000
	s_add_i32 m0, s1, 0xc000
	s_nop 0
	global_load_lds_dwordx4 v140, s[100:101]
	s_add_i32 m0, s1, 0xe000
	s_nop 0
	global_load_lds_dwordx4 v142, s[100:101]
	s_waitcnt vmcnt(8)
	s_waitcnt lgkmcnt(0)
	s_barrier
; #define PG8_STAGE(bufoff, gbase, voff) do { _Pragma("unroll") for (int _i = 0; _i < 2; ++_i) \
;         __builtin_amdgcn_global_load_lds((const unsigned*)((const char*)(gbase) + (voff)[_i]), (PG8_LAS unsigned*)(lds + (bufoff) + ldsw + _i * 8192), 16, 0, 0); } while (0)
; #define PG8_LDA(dst, b, h) do { _Pragma("unroll") for (int m = 0; m < 4; ++m) _Pragma("unroll") for (int k = 0; k < 2; ++k) dst[m][k] = *(const PG8_LAS bf16x8*)(lds + PG8_SA(b, h) + aoff + m * 2048 + k * 1024); } while (0)
; #define PG8_MMA(ai, bj, At, Bt) do { __builtin_amdgcn_s_setprio(1); _Pragma("unroll") for (int m = 0; m < 4; ++m) _Pragma("unroll") for (int n = 0; n < 2; ++n) _Pragma("unroll") for (int k = 0; k < 2; ++k) \
;         acc[ai][bj][m][n] = __builtin_amdgcn_mfma_f32_16x16x32_bf16(Bt[n][k], At[m][k], acc[ai][bj][m][n], 0, 0, 0); __builtin_amdgcn_s_setprio(0); } while (0)
; #define PG8_WAIT_V(n) asm volatile("s_waitcnt vmcnt(" #n ")" ::: "memory")
; #define PG8_WAIT_L(n) asm volatile("s_waitcnt lgkmcnt(" #n ")" ::: "memory")
; #define PG8_BAR __builtin_amdgcn_s_barrier()
; #define PG8_SCHED __builtin_amdgcn_sched_barrier(0)
; template <class Epi, class Sched, bool ALIGN_EPI = false, bool SP2 = false>
; __device__ __forceinline__ void gemm_phase(PG8_LAS unsigned char* lds, const Gemm g, const Sched& S, const Epi& E) {
;     ...
;             PG8_WAIT_V(8); PG8_WAIT_L(0); PG8_BAR; PG8_MMA(0, 0, At, B0); PG8_MMA(0, 1, At, B1); PG8_BAR; PG8_SCHED;
;             PG8_LDA(At, 0, 1); PG8_STAGE(PG8_SB(0, 0), b2, voffB); PG8_STAGE(PG8_SB(0, 1), b2 + hstepB, voffB); PG8_STAGE(PG8_SA(0, 0), a2, voffA);
;             PG8_WAIT_V(8); PG8_WAIT_L(0); PG8_BAR; PG8_MMA(1, 0, At, B0); PG8_MMA(1, 1, At, B1); PG8_BAR; PG8_SCHED;
	v_mfma_f32_16x16x32_bf16 v[126:129], v[148:151], v[182:185], v[126:129]
	v_mfma_f32_16x16x32_bf16 v[122:125], v[156:159], v[182:185], v[122:125]
	v_mfma_f32_16x16x32_bf16 v[118:121], v[148:151], v[210:213], v[118:121]
	v_mfma_f32_16x16x32_bf16 v[114:117], v[156:159], v[210:213], v[114:117]
	v_mfma_f32_16x16x32_bf16 v[110:113], v[148:151], v[218:221], v[110:113]
	v_mfma_f32_16x16x32_bf16 v[106:109], v[156:159], v[218:221], v[106:109]
	v_mfma_f32_16x16x32_bf16 v[102:105], v[148:151], v[240:243], v[102:105]
	v_mfma_f32_16x16x32_bf16 v[98:101], v[156:159], v[240:243], v[98:101]
	v_mfma_f32_16x16x32_bf16 v[126:129], v[152:155], v[206:209], v[126:129]
	v_mfma_f32_16x16x32_bf16 v[122:125], v[160:163], v[206:209], v[122:125]
	v_mfma_f32_16x16x32_bf16 v[118:121], v[152:155], v[214:217], v[118:121]
	v_mfma_f32_16x16x32_bf16 v[114:117], v[160:163], v[214:217], v[114:117]
	v_mfma_f32_16x16x32_bf16 v[110:113], v[152:155], v[236:239], v[110:113]
	v_mfma_f32_16x16x32_bf16 v[106:109], v[160:163], v[236:239], v[106:109]
	v_mfma_f32_16x16x32_bf16 v[102:105], v[152:155], v[244:247], v[102:105]
	v_mfma_f32_16x16x32_bf16 v[98:101], v[160:163], v[244:247], v[98:101]
	v_mfma_f32_16x16x32_bf16 v[94:97], v[166:169], v[182:185], v[94:97]
	v_mfma_f32_16x16x32_bf16 v[90:93], v[174:177], v[182:185], v[90:93]
	v_mfma_f32_16x16x32_bf16 v[86:89], v[166:169], v[210:213], v[86:89]
	v_mfma_f32_16x16x32_bf16 v[82:85], v[174:177], v[210:213], v[82:85]
	v_mfma_f32_16x16x32_bf16 v[78:81], v[166:169], v[218:221], v[78:81]
	v_mfma_f32_16x16x32_bf16 v[74:77], v[174:177], v[218:221], v[74:77]
	v_mfma_f32_16x16x32_bf16 v[70:73], v[166:169], v[240:243], v[70:73]
	v_mfma_f32_16x16x32_bf16 v[66:69], v[174:177], v[240:243], v[66:69]
	v_mfma_f32_16x16x32_bf16 v[94:97], v[170:173], v[206:209], v[94:97]
	v_mfma_f32_16x16x32_bf16 v[90:93], v[178:181], v[206:209], v[90:93]
	v_mfma_f32_16x16x32_bf16 v[86:89], v[170:173], v[214:217], v[86:89]
	v_mfma_f32_16x16x32_bf16 v[82:85], v[178:181], v[214:217], v[82:85]
	v_mfma_f32_16x16x32_bf16 v[78:81], v[170:173], v[236:239], v[78:81]
	v_mfma_f32_16x16x32_bf16 v[74:77], v[178:181], v[236:239], v[74:77]
	v_mfma_f32_16x16x32_bf16 v[70:73], v[170:173], v[244:247], v[70:73]
	v_mfma_f32_16x16x32_bf16 v[66:69], v[178:181], v[244:247], v[66:69]
	s_barrier
	ds_read_b128 v[182:185], v165 offset:16384
	ds_read_b128 v[206:209], v165 offset:17408
	ds_read_b128 v[210:213], v165 offset:18432
	ds_read_b128 v[214:217], v165 offset:19456
	ds_read_b128 v[218:221], v165 offset:20480
	ds_read_b128 v[236:239], v165 offset:21504
	ds_read_b128 v[240:243], v165 offset:22528
	ds_read_b128 v[244:247], v165 offset:23552
	s_add_i32 s10, s13, s0
	s_mov_b32 m0, s10
	s_nop 0
	global_load_lds_dwordx4 v132, s[80:81]
	s_add_i32 m0, s10, 0x2000
	s_add_u32 s10, s80, 0x20000
	s_addc_u32 s11, s81, 0
	s_add_i32 s9, s9, s0
	global_load_lds_dwordx4 v136, s[80:81]
	s_mov_b32 m0, s9
	s_nop 0
	global_load_lds_dwordx4 v132, s[10:11]
	s_add_i32 m0, s9, 0x2000
	s_nop 0
	global_load_lds_dwordx4 v136, s[10:11]
	s_mov_b32 m0, s1
	s_nop 0
	global_load_lds_dwordx4 v130, s[84:85]
	s_mov_b32 m0, s25
	s_nop 0
	global_load_lds_dwordx4 v134, s[84:85]
	s_waitcnt vmcnt(8)
	s_waitcnt lgkmcnt(0)
	s_barrier
	v_mfma_f32_16x16x32_bf16 v[62:65], v[148:151], v[182:185], v[62:65]
	v_mfma_f32_16x16x32_bf16 v[58:61], v[156:159], v[182:185], v[58:61]
	v_mfma_f32_16x16x32_bf16 v[54:57], v[148:151], v[210:213], v[54:57]
	v_mfma_f32_16x16x32_bf16 v[50:53], v[156:159], v[210:213], v[50:53]
	v_mfma_f32_16x16x32_bf16 v[46:49], v[148:151], v[218:221], v[46:49]
	v_mfma_f32_16x16x32_bf16 v[42:45], v[156:159], v[218:221], v[42:45]
	v_mfma_f32_16x16x32_bf16 v[38:41], v[148:151], v[240:243], v[38:41]
	v_mfma_f32_16x16x32_bf16 v[34:37], v[156:159], v[240:243], v[34:37]
	v_mfma_f32_16x16x32_bf16 v[62:65], v[152:155], v[206:209], v[62:65]
	v_mfma_f32_16x16x32_bf16 v[58:61], v[160:163], v[206:209], v[58:61]
	v_mfma_f32_16x16x32_bf16 v[54:57], v[152:155], v[214:217], v[54:57]
	v_mfma_f32_16x16x32_bf16 v[50:53], v[160:163], v[214:217], v[50:53]
	v_mfma_f32_16x16x32_bf16 v[46:49], v[152:155], v[236:239], v[46:49]
	v_mfma_f32_16x16x32_bf16 v[42:45], v[160:163], v[236:239], v[42:45]
	v_mfma_f32_16x16x32_bf16 v[38:41], v[152:155], v[244:247], v[38:41]
	v_mfma_f32_16x16x32_bf16 v[34:37], v[160:163], v[244:247], v[34:37]
	v_mfma_f32_16x16x32_bf16 v[30:33], v[166:169], v[182:185], v[30:33]
	v_mfma_f32_16x16x32_bf16 v[26:29], v[174:177], v[182:185], v[26:29]
	v_mfma_f32_16x16x32_bf16 v[22:25], v[166:169], v[210:213], v[22:25]
	v_mfma_f32_16x16x32_bf16 v[18:21], v[174:177], v[210:213], v[18:21]
	v_mfma_f32_16x16x32_bf16 v[14:17], v[166:169], v[218:221], v[14:17]
	v_mfma_f32_16x16x32_bf16 v[10:13], v[174:177], v[218:221], v[10:13]
	v_mfma_f32_16x16x32_bf16 v[6:9], v[166:169], v[240:243], v[6:9]
	v_mfma_f32_16x16x32_bf16 v[2:5], v[174:177], v[240:243], v[2:5]
	v_mfma_f32_16x16x32_bf16 v[30:33], v[170:173], v[206:209], v[30:33]
	v_mfma_f32_16x16x32_bf16 v[26:29], v[178:181], v[206:209], v[26:29]
	v_mfma_f32_16x16x32_bf16 v[22:25], v[170:173], v[214:217], v[22:25]
	v_mfma_f32_16x16x32_bf16 v[18:21], v[178:181], v[214:217], v[18:21]
	v_mfma_f32_16x16x32_bf16 v[14:17], v[170:173], v[236:239], v[14:17]
	v_mfma_f32_16x16x32_bf16 v[10:13], v[178:181], v[236:239], v[10:13]
	v_mfma_f32_16x16x32_bf16 v[6:9], v[170:173], v[244:247], v[6:9]
	v_mfma_f32_16x16x32_bf16 v[2:5], v[178:181], v[244:247], v[2:5]
	s_barrier
; #define PG8_STAGE(bufoff, gbase, voff) do { _Pragma("unroll") for (int _i = 0; _i < 2; ++_i) \
;         __builtin_amdgcn_global_load_lds((const unsigned*)((const char*)(gbase) + (voff)[_i]), (PG8_LAS unsigned*)(lds + (bufoff) + ldsw + _i * 8192), 16, 0, 0); } while (0)
; #define PG8_LDA(dst, b, h) do { _Pragma("unroll") for (int m = 0; m < 4; ++m) _Pragma("unroll") for (int k = 0; k < 2; ++k) dst[m][k] = *(const PG8_LAS bf16x8*)(lds + PG8_SA(b, h) + aoff + m * 2048 + k * 1024); } while (0)
; #define PG8_LDB(dst, b, h) do { _Pragma("unroll") for (int n = 0; n < 2; ++n) _Pragma("unroll") for (int k = 0; k < 2; ++k) dst[n][k] = *(const PG8_LAS bf16x8*)(lds + PG8_SB(b, h) + boff + n * 2048 + k * 1024); } while (0)
; #define PG8_MMA(ai, bj, At, Bt) do { __builtin_amdgcn_s_setprio(1); _Pragma("unroll") for (int m = 0; m < 4; ++m) _Pragma("unroll") for (int n = 0; n < 2; ++n) _Pragma("unroll") for (int k = 0; k < 2; ++k) \
;         acc[ai][bj][m][n] = __builtin_amdgcn_mfma_f32_16x16x32_bf16(Bt[n][k], At[m][k], acc[ai][bj][m][n], 0, 0, 0); __builtin_amdgcn_s_setprio(0); } while (0)
; #define PG8_WAIT_V(n) asm volatile("s_waitcnt vmcnt(" #n ")" ::: "memory")
; #define PG8_WAIT_L(n) asm volatile("s_waitcnt lgkmcnt(" #n ")" ::: "memory")
; #define PG8_BAR __builtin_amdgcn_s_barrier()
; #define PG8_SCHED __builtin_amdgcn_sched_barrier(0)
; template <class Epi, class Sched, bool ALIGN_EPI = false, bool SP2 = false>
; __device__ __forceinline__ void gemm_phase(PG8_LAS unsigned char* lds, const Gemm g, const Sched& S, const Epi& E) {
;     ...
;             PG8_LDB(B0, 1, 0); PG8_LDB(B1, 1, 1); PG8_SCHED; PG8_LDA(At, 1, 0); PG8_STAGE(PG8_SA(0, 1), a2 + hstep, voffA);
;             PG8_WAIT_V(8); PG8_WAIT_L(0); PG8_BAR; PG8_MMA(0, 0, At, B0); PG8_MMA(0, 1, At, B1); PG8_BAR; PG8_SCHED;
;             PG8_LDA(At, 1, 1); PG8_STAGE(PG8_SB(1, 0), b3, voffB); PG8_STAGE(PG8_SB(1, 1), b3 + hstepB, voffB); PG8_STAGE(PG8_SA(1, 0), a3, voffA);
;             PG8_WAIT_V(8); PG8_WAIT_L(0); PG8_BAR; PG8_MMA(1, 0, At, B0); PG8_MMA(1, 1, At, B1); PG8_BAR; PG8_SCHED;
;     ...
;         if constexpr (ALIGN_EPI) { if (wr == 0) PG8_BAR; }
	ds_read_b128 v[148:151], v198
	ds_read_b128 v[152:155], v198 offset:1024
	ds_read_b128 v[156:159], v198 offset:2048
	ds_read_b128 v[160:163], v198 offset:3072
	ds_read_b128 v[166:169], v199
	ds_read_b128 v[170:173], v199 offset:1024
	ds_read_b128 v[174:177], v199 offset:2048
	ds_read_b128 v[178:181], v199 offset:3072
	ds_read_b128 v[182:185], v165 offset:32768
	ds_read_b128 v[206:209], v165 offset:33792
	ds_read_b128 v[210:213], v165 offset:34816
	ds_read_b128 v[214:217], v165 offset:35840
	ds_read_b128 v[218:221], v165 offset:36864
	ds_read_b128 v[236:239], v165 offset:37888
	ds_read_b128 v[240:243], v165 offset:38912
	ds_read_b128 v[244:247], v165 offset:39936
	s_add_i32 s9, 0, 0x18000
	s_add_i32 s12, 0, 0x1c000
	s_add_u32 s10, s84, 0x80000
	s_addc_u32 s11, s85, 0
	s_mov_b32 m0, s42
	s_nop 0
	global_load_lds_dwordx4 v130, s[10:11]
	s_mov_b32 m0, s51
	s_nop 0
	global_load_lds_dwordx4 v134, s[10:11]
	s_waitcnt vmcnt(8)
	s_waitcnt lgkmcnt(0)
	s_barrier
	v_mfma_f32_16x16x32_bf16 v[126:129], v[148:151], v[182:185], v[126:129]
	v_mfma_f32_16x16x32_bf16 v[122:125], v[156:159], v[182:185], v[122:125]
	v_mfma_f32_16x16x32_bf16 v[118:121], v[148:151], v[210:213], v[118:121]
	v_mfma_f32_16x16x32_bf16 v[114:117], v[156:159], v[210:213], v[114:117]
	v_mfma_f32_16x16x32_bf16 v[110:113], v[148:151], v[218:221], v[110:113]
	v_mfma_f32_16x16x32_bf16 v[106:109], v[156:159], v[218:221], v[106:109]
	v_mfma_f32_16x16x32_bf16 v[102:105], v[148:151], v[240:243], v[102:105]
	v_mfma_f32_16x16x32_bf16 v[98:101], v[156:159], v[240:243], v[98:101]
	v_mfma_f32_16x16x32_bf16 v[126:129], v[152:155], v[206:209], v[126:129]
	v_mfma_f32_16x16x32_bf16 v[122:125], v[160:163], v[206:209], v[122:125]
	v_mfma_f32_16x16x32_bf16 v[118:121], v[152:155], v[214:217], v[118:121]
	v_mfma_f32_16x16x32_bf16 v[114:117], v[160:163], v[214:217], v[114:117]
	v_mfma_f32_16x16x32_bf16 v[110:113], v[152:155], v[236:239], v[110:113]
	v_mfma_f32_16x16x32_bf16 v[106:109], v[160:163], v[236:239], v[106:109]
	v_mfma_f32_16x16x32_bf16 v[102:105], v[152:155], v[244:247], v[102:105]
	v_mfma_f32_16x16x32_bf16 v[98:101], v[160:163], v[244:247], v[98:101]
	v_mfma_f32_16x16x32_bf16 v[94:97], v[166:169], v[182:185], v[94:97]
	v_mfma_f32_16x16x32_bf16 v[90:93], v[174:177], v[182:185], v[90:93]
	v_mfma_f32_16x16x32_bf16 v[86:89], v[166:169], v[210:213], v[86:89]
	v_mfma_f32_16x16x32_bf16 v[82:85], v[174:177], v[210:213], v[82:85]
	v_mfma_f32_16x16x32_bf16 v[78:81], v[166:169], v[218:221], v[78:81]
	v_mfma_f32_16x16x32_bf16 v[74:77], v[174:177], v[218:221], v[74:77]
	v_mfma_f32_16x16x32_bf16 v[70:73], v[166:169], v[240:243], v[70:73]
	v_mfma_f32_16x16x32_bf16 v[66:69], v[174:177], v[240:243], v[66:69]
	v_mfma_f32_16x16x32_bf16 v[94:97], v[170:173], v[206:209], v[94:97]
	v_mfma_f32_16x16x32_bf16 v[90:93], v[178:181], v[206:209], v[90:93]
	v_mfma_f32_16x16x32_bf16 v[86:89], v[170:173], v[214:217], v[86:89]
	v_mfma_f32_16x16x32_bf16 v[82:85], v[178:181], v[214:217], v[82:85]
	v_mfma_f32_16x16x32_bf16 v[78:81], v[170:173], v[236:239], v[78:81]
	v_mfma_f32_16x16x32_bf16 v[74:77], v[178:181], v[236:239], v[74:77]
	v_mfma_f32_16x16x32_bf16 v[70:73], v[170:173], v[244:247], v[70:73]
	v_mfma_f32_16x16x32_bf16 v[66:69], v[178:181], v[244:247], v[66:69]
	s_barrier
	ds_read_b128 v[182:185], v165 offset:49152
	ds_read_b128 v[206:209], v165 offset:50176
	ds_read_b128 v[210:213], v165 offset:51200
	ds_read_b128 v[214:217], v165 offset:52224
	ds_read_b128 v[218:221], v165 offset:53248
	ds_read_b128 v[236:239], v165 offset:54272
	ds_read_b128 v[240:243], v165 offset:55296
	ds_read_b128 v[244:247], v165 offset:56320
	s_add_i32 s9, s9, s0
	s_mov_b32 m0, s9
	s_add_u32 s100, s80, s60
	s_addc_u32 s101, s81, s61
	global_load_lds_dwordx4 v132, s[100:101]
	s_add_i32 m0, s9, 0x2000
	s_add_u32 s10, s80, 0x20080
	s_addc_u32 s11, s81, 0
	s_add_i32 s9, s12, s0
	global_load_lds_dwordx4 v136, s[100:101]
	s_mov_b32 m0, s9
	s_nop 0
	global_load_lds_dwordx4 v132, s[10:11]
	s_add_i32 m0, s9, 0x2000
	s_nop 0
	global_load_lds_dwordx4 v136, s[10:11]
	s_mov_b32 m0, s66
	s_add_u32 s100, s84, s60
	s_addc_u32 s101, s85, s61
	global_load_lds_dwordx4 v130, s[100:101]
	s_mov_b32 m0, s67
	s_nop 0
	global_load_lds_dwordx4 v134, s[100:101]
	s_waitcnt vmcnt(8)
	s_waitcnt lgkmcnt(0)
	s_barrier
	v_mfma_f32_16x16x32_bf16 v[62:65], v[148:151], v[182:185], v[62:65]
	v_mfma_f32_16x16x32_bf16 v[58:61], v[156:159], v[182:185], v[58:61]
	v_mfma_f32_16x16x32_bf16 v[54:57], v[148:151], v[210:213], v[54:57]
	v_mfma_f32_16x16x32_bf16 v[50:53], v[156:159], v[210:213], v[50:53]
	v_mfma_f32_16x16x32_bf16 v[46:49], v[148:151], v[218:221], v[46:49]
	v_mfma_f32_16x16x32_bf16 v[42:45], v[156:159], v[218:221], v[42:45]
	v_mfma_f32_16x16x32_bf16 v[38:41], v[148:151], v[240:243], v[38:41]
	v_mfma_f32_16x16x32_bf16 v[34:37], v[156:159], v[240:243], v[34:37]
	v_mfma_f32_16x16x32_bf16 v[62:65], v[152:155], v[206:209], v[62:65]
	v_mfma_f32_16x16x32_bf16 v[58:61], v[160:163], v[206:209], v[58:61]
	v_mfma_f32_16x16x32_bf16 v[54:57], v[152:155], v[214:217], v[54:57]
	v_mfma_f32_16x16x32_bf16 v[50:53], v[160:163], v[214:217], v[50:53]
	v_mfma_f32_16x16x32_bf16 v[46:49], v[152:155], v[236:239], v[46:49]
	v_mfma_f32_16x16x32_bf16 v[42:45], v[160:163], v[236:239], v[42:45]
	v_mfma_f32_16x16x32_bf16 v[38:41], v[152:155], v[244:247], v[38:41]
	v_mfma_f32_16x16x32_bf16 v[34:37], v[160:163], v[244:247], v[34:37]
	v_mfma_f32_16x16x32_bf16 v[30:33], v[166:169], v[182:185], v[30:33]
	v_mfma_f32_16x16x32_bf16 v[26:29], v[174:177], v[182:185], v[26:29]
	v_mfma_f32_16x16x32_bf16 v[22:25], v[166:169], v[210:213], v[22:25]
	v_mfma_f32_16x16x32_bf16 v[18:21], v[174:177], v[210:213], v[18:21]
	v_mfma_f32_16x16x32_bf16 v[14:17], v[166:169], v[218:221], v[14:17]
	v_mfma_f32_16x16x32_bf16 v[10:13], v[174:177], v[218:221], v[10:13]
	s_add_i32 s8, s8, 2
	v_mfma_f32_16x16x32_bf16 v[6:9], v[166:169], v[240:243], v[6:9]
	s_add_u32 s46, s46, 0x100
	s_addc_u32 s47, s47, 0
	v_mfma_f32_16x16x32_bf16 v[2:5], v[174:177], v[240:243], v[2:5]
	s_cmp_gt_u32 s8, 29
	v_mfma_f32_16x16x32_bf16 v[30:33], v[170:173], v[206:209], v[30:33]
	v_mfma_f32_16x16x32_bf16 v[26:29], v[178:181], v[206:209], v[26:29]
	v_mfma_f32_16x16x32_bf16 v[22:25], v[170:173], v[214:217], v[22:25]
	v_mfma_f32_16x16x32_bf16 v[18:21], v[178:181], v[214:217], v[18:21]
	v_mfma_f32_16x16x32_bf16 v[14:17], v[170:173], v[236:239], v[14:17]
	v_mfma_f32_16x16x32_bf16 v[10:13], v[178:181], v[236:239], v[10:13]
	v_mfma_f32_16x16x32_bf16 v[6:9], v[170:173], v[244:247], v[6:9]
	v_mfma_f32_16x16x32_bf16 v[2:5], v[178:181], v[244:247], v[2:5]
	s_barrier
	s_cbranch_scc0 .LBB0_170
	s_and_b64 vcc, exec, s[54:55]
	s_cbranch_vccz .LBB0_173
	s_barrier

; #define PG8_STAGE(bufoff, gbase, voff) do { _Pragma("unroll") for (int _i = 0; _i < 2; ++_i) \
;         __builtin_amdgcn_global_load_lds((const unsigned*)((const char*)(gbase) + (voff)[_i]), (PG8_LAS unsigned*)(lds + (bufoff) + ldsw + _i * 8192), 16, 0, 0); } while (0)
; #define PG8_LDA(dst, b, h) do { _Pragma("unroll") for (int m = 0; m < 4; ++m) _Pragma("unroll") for (int k = 0; k < 2; ++k) dst[m][k] = *(const PG8_LAS bf16x8*)(lds + PG8_SA(b, h) + aoff + m * 2048 + k * 1024); } while (0)
; #define PG8_LDB(dst, b, h) do { _Pragma("unroll") for (int n = 0; n < 2; ++n) _Pragma("unroll") for (int k = 0; k < 2; ++k) dst[n][k] = *(const PG8_LAS bf16x8*)(lds + PG8_SB(b, h) + boff + n * 2048 + k * 1024); } while (0)
; #define PG8_MMA(ai, bj, At, Bt) do { __builtin_amdgcn_s_setprio(1); _Pragma("unroll") for (int m = 0; m < 4; ++m) _Pragma("unroll") for (int n = 0; n < 2; ++n) _Pragma("unroll") for (int k = 0; k < 2; ++k) \
;         acc[ai][bj][m][n] = __builtin_amdgcn_mfma_f32_16x16x32_bf16(Bt[n][k], At[m][k], acc[ai][bj][m][n], 0, 0, 0); __builtin_amdgcn_s_setprio(0); } while (0)
; #define PG8_WAIT_V(n) asm volatile("s_waitcnt vmcnt(" #n ")" ::: "memory")
; #define PG8_WAIT_L(n) asm volatile("s_waitcnt lgkmcnt(" #n ")" ::: "memory")
; #define PG8_BAR __builtin_amdgcn_s_barrier()
; template <class Epi, class Sched, bool ALIGN_EPI = false, bool SP2 = false>
; __device__ __forceinline__ void gemm_phase(PG8_LAS unsigned char* lds, const Gemm g, const Sched& S, const Epi& E) {
;     ...
;             const char* a1 = cA + (size_t)(t + 1) * kstep;
;             const char* a2 = last ? nA : cA + (size_t)(t + 2) * kstep; const char* b2 = last ? nB : cB + (size_t)(t + 2) * kstep;
;             const char* a3 = a2 + kstep; const char* b3 = b2 + kstep;
;             if (last && has_next) S.a_ready(nxt);
;             if constexpr (SP2) {
;             PG8_LDB(B0, 0, 0); PG8_LDB(B1, 0, 1); PG8_SCHED; PG8_LDA(At, 0, 0); PG8_STAGE(PG8_SA(1, 1), a1 + hstep, voffA);
;             PG8_WAIT_V(8); PG8_WAIT_L(0); PG8_BAR; PG8_MMA(0, 0, At, B0); PG8_MMA(0, 1, At, B1); PG8_BAR; PG8_SCHED;
;             PG8_LDA(At, 0, 1); PG8_STAGE(PG8_SB(0, 0), b2, voffB); PG8_STAGE(PG8_SB(0, 1), b2 + hstepB, voffB); PG8_STAGE(PG8_SA(0, 0), a2, voffA);
;             PG8_WAIT_V(8); PG8_WAIT_L(0); PG8_BAR; PG8_MMA(1, 0, At, B0); PG8_MMA(1, 1, At, B1); PG8_BAR; PG8_SCHED;
.LBB0_788:
	ds_read_b128 v[34:37], v186
	ds_read_b128 v[38:41], v186 offset:1024
	ds_read_b128 v[50:53], v186 offset:2048
	ds_read_b128 v[54:57], v186 offset:3072
	ds_read_b128 v[114:117], v187
	ds_read_b128 v[126:129], v187 offset:1024
	ds_read_b128 v[138:141], v187 offset:2048
	ds_read_b128 v[150:153], v187 offset:3072
	ds_read_b128 v[154:157], v217
	ds_read_b128 v[158:161], v217 offset:1024
	ds_read_b128 v[170:173], v217 offset:2048
	ds_read_b128 v[206:209], v217 offset:3072
	ds_read_b128 v[210:213], v217 offset:4096
	ds_read_b128 v[218:221], v217 offset:5120
	ds_read_b128 v[236:239], v217 offset:6144
	ds_read_b128 v[240:243], v217 offset:7168
	s_add_u32 s9, s68, 0xfffe0080
	s_addc_u32 s10, s69, -1
	s_add_i32 s11, 0, 0x10000
	s_cmp_eq_u32 s8, 4
	s_cselect_b32 s77, s36, s10
	s_cselect_b32 s76, s37, s9
	s_cselect_b32 s73, s4, s7
	s_cselect_b32 s72, s5, s6
	s_add_i32 s9, 0, 0x14000
	s_add_i32 m0, s66, 0xc000
	s_nop 0
	global_load_lds_dwordx4 v180, s[68:69]
	s_add_i32 m0, s66, 0xe000
	s_nop 0
	global_load_lds_dwordx4 v182, s[68:69]
	s_waitcnt vmcnt(8)
	s_waitcnt lgkmcnt(0)
	s_barrier
	v_mfma_f32_16x16x32_bf16 v[166:169], v[34:37], v[154:157], v[166:169]
	v_mfma_f32_16x16x32_bf16 v[162:165], v[50:53], v[154:157], v[162:165]
	v_mfma_f32_16x16x32_bf16 v[134:137], v[34:37], v[170:173], v[134:137]
	v_mfma_f32_16x16x32_bf16 v[130:133], v[50:53], v[170:173], v[130:133]
	v_mfma_f32_16x16x32_bf16 v[110:113], v[34:37], v[210:213], v[110:113]
	v_mfma_f32_16x16x32_bf16 v[106:109], v[50:53], v[210:213], v[106:109]
	v_mfma_f32_16x16x32_bf16 v[94:97], v[34:37], v[236:239], v[94:97]
	v_mfma_f32_16x16x32_bf16 v[90:93], v[50:53], v[236:239], v[90:93]
	v_mfma_f32_16x16x32_bf16 v[166:169], v[38:41], v[158:161], v[166:169]
	v_mfma_f32_16x16x32_bf16 v[162:165], v[54:57], v[158:161], v[162:165]
	v_mfma_f32_16x16x32_bf16 v[134:137], v[38:41], v[206:209], v[134:137]
	v_mfma_f32_16x16x32_bf16 v[130:133], v[54:57], v[206:209], v[130:133]
	v_mfma_f32_16x16x32_bf16 v[110:113], v[38:41], v[218:221], v[110:113]
	v_mfma_f32_16x16x32_bf16 v[106:109], v[54:57], v[218:221], v[106:109]
	v_mfma_f32_16x16x32_bf16 v[94:97], v[38:41], v[240:243], v[94:97]
	v_mfma_f32_16x16x32_bf16 v[90:93], v[54:57], v[240:243], v[90:93]
	v_mfma_f32_16x16x32_bf16 v[146:149], v[114:117], v[154:157], v[146:149]
	v_mfma_f32_16x16x32_bf16 v[142:145], v[138:141], v[154:157], v[142:145]
	v_mfma_f32_16x16x32_bf16 v[122:125], v[114:117], v[170:173], v[122:125]
	v_mfma_f32_16x16x32_bf16 v[118:121], v[138:141], v[170:173], v[118:121]
	v_mfma_f32_16x16x32_bf16 v[102:105], v[114:117], v[210:213], v[102:105]
	v_mfma_f32_16x16x32_bf16 v[98:101], v[138:141], v[210:213], v[98:101]
	v_mfma_f32_16x16x32_bf16 v[86:89], v[114:117], v[236:239], v[86:89]
	v_mfma_f32_16x16x32_bf16 v[82:85], v[138:141], v[236:239], v[82:85]
	v_mfma_f32_16x16x32_bf16 v[146:149], v[126:129], v[158:161], v[146:149]
	v_mfma_f32_16x16x32_bf16 v[142:145], v[150:153], v[158:161], v[142:145]
	v_mfma_f32_16x16x32_bf16 v[122:125], v[126:129], v[206:209], v[122:125]
	v_mfma_f32_16x16x32_bf16 v[118:121], v[150:153], v[206:209], v[118:121]
	v_mfma_f32_16x16x32_bf16 v[102:105], v[126:129], v[218:221], v[102:105]
	v_mfma_f32_16x16x32_bf16 v[98:101], v[150:153], v[218:221], v[98:101]
	v_mfma_f32_16x16x32_bf16 v[86:89], v[126:129], v[240:243], v[86:89]
	v_mfma_f32_16x16x32_bf16 v[82:85], v[150:153], v[240:243], v[82:85]
	s_barrier
	ds_read_b128 v[154:157], v217 offset:16384
	ds_read_b128 v[158:161], v217 offset:17408
	ds_read_b128 v[170:173], v217 offset:18432
	ds_read_b128 v[206:209], v217 offset:19456
	ds_read_b128 v[210:213], v217 offset:20480
	ds_read_b128 v[218:221], v217 offset:21504
	ds_read_b128 v[236:239], v217 offset:22528
	ds_read_b128 v[240:243], v217 offset:23552
	s_add_i32 s10, s11, s25
	s_mov_b32 m0, s10
	s_nop 0
	global_load_lds_dwordx4 v190, s[72:73]
	s_add_i32 m0, s10, 0x2000
	s_add_u32 s10, s72, 0x8000
	s_addc_u32 s11, s73, 0
	s_add_i32 s9, s9, s25
	global_load_lds_dwordx4 v174, s[72:73]
	s_mov_b32 m0, s9
	s_nop 0
	global_load_lds_dwordx4 v190, s[10:11]
	s_add_i32 m0, s9, 0x2000
	s_nop 0
	global_load_lds_dwordx4 v174, s[10:11]
	s_mov_b32 m0, s66
	s_nop 0
	global_load_lds_dwordx4 v178, s[76:77]
	s_mov_b32 m0, s67
	s_nop 0
	global_load_lds_dwordx4 v176, s[76:77]
	s_waitcnt vmcnt(8)
	s_waitcnt lgkmcnt(0)
	s_barrier
	v_mfma_f32_16x16x32_bf16 v[78:81], v[34:37], v[154:157], v[78:81]
	v_mfma_f32_16x16x32_bf16 v[74:77], v[50:53], v[154:157], v[74:77]
	v_mfma_f32_16x16x32_bf16 v[62:65], v[34:37], v[170:173], v[62:65]
	v_mfma_f32_16x16x32_bf16 v[58:61], v[50:53], v[170:173], v[58:61]
	v_mfma_f32_16x16x32_bf16 v[30:33], v[34:37], v[210:213], v[30:33]
	v_mfma_f32_16x16x32_bf16 v[26:29], v[50:53], v[210:213], v[26:29]
	v_mfma_f32_16x16x32_bf16 v[14:17], v[34:37], v[236:239], v[14:17]
	v_mfma_f32_16x16x32_bf16 v[10:13], v[50:53], v[236:239], v[10:13]
	v_mfma_f32_16x16x32_bf16 v[78:81], v[38:41], v[158:161], v[78:81]
	v_mfma_f32_16x16x32_bf16 v[74:77], v[54:57], v[158:161], v[74:77]
	v_mfma_f32_16x16x32_bf16 v[62:65], v[38:41], v[206:209], v[62:65]
	v_mfma_f32_16x16x32_bf16 v[58:61], v[54:57], v[206:209], v[58:61]
	v_mfma_f32_16x16x32_bf16 v[30:33], v[38:41], v[218:221], v[30:33]
	v_mfma_f32_16x16x32_bf16 v[26:29], v[54:57], v[218:221], v[26:29]
	v_mfma_f32_16x16x32_bf16 v[14:17], v[38:41], v[240:243], v[14:17]
	v_mfma_f32_16x16x32_bf16 v[10:13], v[54:57], v[240:243], v[10:13]
	v_mfma_f32_16x16x32_bf16 v[46:49], v[114:117], v[170:173], v[46:49]
	v_mfma_f32_16x16x32_bf16 v[42:45], v[138:141], v[170:173], v[42:45]
	v_mfma_f32_16x16x32_bf16 v[22:25], v[114:117], v[210:213], v[22:25]
	v_mfma_f32_16x16x32_bf16 v[18:21], v[138:141], v[210:213], v[18:21]
	v_mfma_f32_16x16x32_bf16 v[6:9], v[114:117], v[236:239], v[6:9]
	v_mfma_f32_16x16x32_bf16 v[2:5], v[138:141], v[236:239], v[2:5]
	v_mfma_f32_16x16x32_bf16 v[34:37], v[114:117], v[154:157], v[70:73]
	v_mfma_f32_16x16x32_bf16 v[38:41], v[138:141], v[154:157], v[66:69]
	v_mfma_f32_16x16x32_bf16 v[46:49], v[126:129], v[206:209], v[46:49]
	v_mfma_f32_16x16x32_bf16 v[42:45], v[150:153], v[206:209], v[42:45]
	v_mfma_f32_16x16x32_bf16 v[22:25], v[126:129], v[218:221], v[22:25]
	v_mfma_f32_16x16x32_bf16 v[18:21], v[150:153], v[218:221], v[18:21]
	v_mfma_f32_16x16x32_bf16 v[6:9], v[126:129], v[240:243], v[6:9]
	v_mfma_f32_16x16x32_bf16 v[2:5], v[150:153], v[240:243], v[2:5]
	v_mfma_f32_16x16x32_bf16 v[34:37], v[126:129], v[158:161], v[34:37]
	v_mfma_f32_16x16x32_bf16 v[38:41], v[150:153], v[158:161], v[38:41]
	s_barrier
; #define PG8_STAGE(bufoff, gbase, voff) do { _Pragma("unroll") for (int _i = 0; _i < 2; ++_i) \
;         __builtin_amdgcn_global_load_lds((const unsigned*)((const char*)(gbase) + (voff)[_i]), (PG8_LAS unsigned*)(lds + (bufoff) + ldsw + _i * 8192), 16, 0, 0); } while (0)
; #define PG8_LDA(dst, b, h) do { _Pragma("unroll") for (int m = 0; m < 4; ++m) _Pragma("unroll") for (int k = 0; k < 2; ++k) dst[m][k] = *(const PG8_LAS bf16x8*)(lds + PG8_SA(b, h) + aoff + m * 2048 + k * 1024); } while (0)
; #define PG8_LDB(dst, b, h) do { _Pragma("unroll") for (int n = 0; n < 2; ++n) _Pragma("unroll") for (int k = 0; k < 2; ++k) dst[n][k] = *(const PG8_LAS bf16x8*)(lds + PG8_SB(b, h) + boff + n * 2048 + k * 1024); } while (0)
; #define PG8_MMA(ai, bj, At, Bt) do { __builtin_amdgcn_s_setprio(1); _Pragma("unroll") for (int m = 0; m < 4; ++m) _Pragma("unroll") for (int n = 0; n < 2; ++n) _Pragma("unroll") for (int k = 0; k < 2; ++k) \
;         acc[ai][bj][m][n] = __builtin_amdgcn_mfma_f32_16x16x32_bf16(Bt[n][k], At[m][k], acc[ai][bj][m][n], 0, 0, 0); __builtin_amdgcn_s_setprio(0); } while (0)
; #define PG8_WAIT_V(n) asm volatile("s_waitcnt vmcnt(" #n ")" ::: "memory")
; #define PG8_WAIT_L(n) asm volatile("s_waitcnt lgkmcnt(" #n ")" ::: "memory")
; #define PG8_BAR __builtin_amdgcn_s_barrier()
; #define PG8_SCHED __builtin_amdgcn_sched_barrier(0)
; template <class Epi, class Sched, bool ALIGN_EPI = false, bool SP2 = false>
; __device__ __forceinline__ void gemm_phase(PG8_LAS unsigned char* lds, const Gemm g, const Sched& S, const Epi& E) {
;     ...
;             PG8_LDB(B0, 1, 0); PG8_LDB(B1, 1, 1); PG8_SCHED; PG8_LDA(At, 1, 0); PG8_STAGE(PG8_SA(0, 1), a2 + hstep, voffA);
;             PG8_WAIT_V(8); PG8_WAIT_L(0); PG8_BAR; PG8_MMA(0, 0, At, B0); PG8_MMA(0, 1, At, B1); PG8_BAR; PG8_SCHED;
;             PG8_LDA(At, 1, 1); PG8_STAGE(PG8_SB(1, 0), b3, voffB); PG8_STAGE(PG8_SB(1, 1), b3 + hstepB, voffB); PG8_STAGE(PG8_SA(1, 0), a3, voffA);
;             PG8_WAIT_V(8); PG8_WAIT_L(0); PG8_BAR; PG8_MMA(1, 0, At, B0); PG8_MMA(1, 1, At, B1); PG8_BAR; PG8_SCHED;
	ds_read_b128 v[50:53], v198
	ds_read_b128 v[54:57], v198 offset:1024
	ds_read_b128 v[66:69], v198 offset:2048
	ds_read_b128 v[70:73], v198 offset:3072
	ds_read_b128 v[114:117], v199
	ds_read_b128 v[126:129], v199 offset:1024
	ds_read_b128 v[138:141], v199 offset:2048
	ds_read_b128 v[150:153], v199 offset:3072
	ds_read_b128 v[154:157], v217 offset:32768
	ds_read_b128 v[158:161], v217 offset:33792
	ds_read_b128 v[170:173], v217 offset:34816
	ds_read_b128 v[206:209], v217 offset:35840
	ds_read_b128 v[210:213], v217 offset:36864
	ds_read_b128 v[218:221], v217 offset:37888
	ds_read_b128 v[236:239], v217 offset:38912
	ds_read_b128 v[240:243], v217 offset:39936
	s_add_i32 s9, 0, 0x18000
	s_add_i32 s12, 0, 0x1c000
	s_add_u32 s10, s76, 0x20000
	s_addc_u32 s11, s77, 0
	s_mov_b32 m0, s80
	s_nop 0
	global_load_lds_dwordx4 v178, s[10:11]
	s_mov_b32 m0, s81
	s_nop 0
	global_load_lds_dwordx4 v176, s[10:11]
	s_waitcnt vmcnt(8)
	s_waitcnt lgkmcnt(0)
	s_barrier
	v_mfma_f32_16x16x32_bf16 v[166:169], v[50:53], v[154:157], v[166:169]
	v_mfma_f32_16x16x32_bf16 v[162:165], v[66:69], v[154:157], v[162:165]
	v_mfma_f32_16x16x32_bf16 v[134:137], v[50:53], v[170:173], v[134:137]
	v_mfma_f32_16x16x32_bf16 v[130:133], v[66:69], v[170:173], v[130:133]
	v_mfma_f32_16x16x32_bf16 v[110:113], v[50:53], v[210:213], v[110:113]
	v_mfma_f32_16x16x32_bf16 v[106:109], v[66:69], v[210:213], v[106:109]
	v_mfma_f32_16x16x32_bf16 v[94:97], v[50:53], v[236:239], v[94:97]
	v_mfma_f32_16x16x32_bf16 v[90:93], v[66:69], v[236:239], v[90:93]
	v_mfma_f32_16x16x32_bf16 v[166:169], v[54:57], v[158:161], v[166:169]
	v_mfma_f32_16x16x32_bf16 v[162:165], v[70:73], v[158:161], v[162:165]
	v_mfma_f32_16x16x32_bf16 v[134:137], v[54:57], v[206:209], v[134:137]
	v_mfma_f32_16x16x32_bf16 v[130:133], v[70:73], v[206:209], v[130:133]
	v_mfma_f32_16x16x32_bf16 v[110:113], v[54:57], v[218:221], v[110:113]
	v_mfma_f32_16x16x32_bf16 v[106:109], v[70:73], v[218:221], v[106:109]
	v_mfma_f32_16x16x32_bf16 v[94:97], v[54:57], v[240:243], v[94:97]
	v_mfma_f32_16x16x32_bf16 v[90:93], v[70:73], v[240:243], v[90:93]
	v_mfma_f32_16x16x32_bf16 v[146:149], v[114:117], v[154:157], v[146:149]
	v_mfma_f32_16x16x32_bf16 v[142:145], v[138:141], v[154:157], v[142:145]
	v_mfma_f32_16x16x32_bf16 v[122:125], v[114:117], v[170:173], v[122:125]
	v_mfma_f32_16x16x32_bf16 v[118:121], v[138:141], v[170:173], v[118:121]
	v_mfma_f32_16x16x32_bf16 v[102:105], v[114:117], v[210:213], v[102:105]
	v_mfma_f32_16x16x32_bf16 v[98:101], v[138:141], v[210:213], v[98:101]
	v_mfma_f32_16x16x32_bf16 v[86:89], v[114:117], v[236:239], v[86:89]
	v_mfma_f32_16x16x32_bf16 v[82:85], v[138:141], v[236:239], v[82:85]
	v_mfma_f32_16x16x32_bf16 v[146:149], v[126:129], v[158:161], v[146:149]
	v_mfma_f32_16x16x32_bf16 v[142:145], v[150:153], v[158:161], v[142:145]
	v_mfma_f32_16x16x32_bf16 v[122:125], v[126:129], v[206:209], v[122:125]
	v_mfma_f32_16x16x32_bf16 v[118:121], v[150:153], v[206:209], v[118:121]
	v_mfma_f32_16x16x32_bf16 v[102:105], v[126:129], v[218:221], v[102:105]
	v_mfma_f32_16x16x32_bf16 v[98:101], v[150:153], v[218:221], v[98:101]
	v_mfma_f32_16x16x32_bf16 v[86:89], v[126:129], v[240:243], v[86:89]
	v_mfma_f32_16x16x32_bf16 v[82:85], v[150:153], v[240:243], v[82:85]
	s_barrier
	ds_read_b128 v[154:157], v217 offset:49152
	ds_read_b128 v[158:161], v217 offset:50176
	ds_read_b128 v[170:173], v217 offset:51200
	ds_read_b128 v[206:209], v217 offset:52224
	ds_read_b128 v[210:213], v217 offset:53248
	ds_read_b128 v[218:221], v217 offset:54272
	ds_read_b128 v[236:239], v217 offset:55296
	ds_read_b128 v[240:243], v217 offset:56320
	s_add_i32 s9, s9, s25
	s_mov_b32 m0, s9
	s_add_u32 s100, s72, s60
	s_addc_u32 s101, s73, s61
	global_load_lds_dwordx4 v190, s[100:101]
	s_add_i32 m0, s9, 0x2000
	s_add_u32 s10, s72, 0x8080
	s_addc_u32 s11, s73, 0
	s_add_i32 s9, s12, s25
	global_load_lds_dwordx4 v174, s[100:101]
	s_mov_b32 m0, s9
	s_nop 0
	global_load_lds_dwordx4 v190, s[10:11]
	s_add_i32 m0, s9, 0x2000
	s_nop 0
	global_load_lds_dwordx4 v174, s[10:11]
	s_mov_b32 m0, s82
	s_add_u32 s100, s76, s60
	s_addc_u32 s101, s77, s61
	global_load_lds_dwordx4 v178, s[100:101]
	s_mov_b32 m0, s92
	s_nop 0
	global_load_lds_dwordx4 v176, s[100:101]
	s_waitcnt vmcnt(8)
	s_waitcnt lgkmcnt(0)
	s_barrier
	v_mfma_f32_16x16x32_bf16 v[78:81], v[50:53], v[154:157], v[78:81]
	v_mfma_f32_16x16x32_bf16 v[74:77], v[66:69], v[154:157], v[74:77]
	v_mfma_f32_16x16x32_bf16 v[62:65], v[50:53], v[170:173], v[62:65]
	v_mfma_f32_16x16x32_bf16 v[58:61], v[66:69], v[170:173], v[58:61]
	v_mfma_f32_16x16x32_bf16 v[30:33], v[50:53], v[210:213], v[30:33]
	v_mfma_f32_16x16x32_bf16 v[26:29], v[66:69], v[210:213], v[26:29]
	v_mfma_f32_16x16x32_bf16 v[14:17], v[50:53], v[236:239], v[14:17]
	v_mfma_f32_16x16x32_bf16 v[10:13], v[66:69], v[236:239], v[10:13]
	v_mfma_f32_16x16x32_bf16 v[78:81], v[54:57], v[158:161], v[78:81]
	v_mfma_f32_16x16x32_bf16 v[74:77], v[70:73], v[158:161], v[74:77]
	v_mfma_f32_16x16x32_bf16 v[62:65], v[54:57], v[206:209], v[62:65]
	v_mfma_f32_16x16x32_bf16 v[58:61], v[70:73], v[206:209], v[58:61]
	v_mfma_f32_16x16x32_bf16 v[30:33], v[54:57], v[218:221], v[30:33]
	v_mfma_f32_16x16x32_bf16 v[26:29], v[70:73], v[218:221], v[26:29]
	v_mfma_f32_16x16x32_bf16 v[14:17], v[54:57], v[240:243], v[14:17]
	v_mfma_f32_16x16x32_bf16 v[10:13], v[70:73], v[240:243], v[10:13]
	v_mfma_f32_16x16x32_bf16 v[34:37], v[114:117], v[154:157], v[34:37]
	v_mfma_f32_16x16x32_bf16 v[70:73], v[126:129], v[158:161], v[34:37]
	v_mfma_f32_16x16x32_bf16 v[34:37], v[138:141], v[154:157], v[38:41]
	v_mfma_f32_16x16x32_bf16 v[66:69], v[150:153], v[158:161], v[34:37]
	v_mfma_f32_16x16x32_bf16 v[34:37], v[114:117], v[170:173], v[46:49]
	v_mfma_f32_16x16x32_bf16 v[46:49], v[126:129], v[206:209], v[34:37]
	s_add_i32 s8, s8, 2
	v_mfma_f32_16x16x32_bf16 v[34:37], v[138:141], v[170:173], v[42:45]
	s_add_u32 s68, s68, 0x100
	s_addc_u32 s69, s69, 0
	v_mfma_f32_16x16x32_bf16 v[22:25], v[114:117], v[210:213], v[22:25]
	s_add_u32 s6, s6, 0x100
	s_addc_u32 s7, s7, 0
	v_mfma_f32_16x16x32_bf16 v[18:21], v[138:141], v[210:213], v[18:21]
	s_cmp_gt_u32 s8, 5
	v_mfma_f32_16x16x32_bf16 v[6:9], v[114:117], v[236:239], v[6:9]
	v_mfma_f32_16x16x32_bf16 v[2:5], v[138:141], v[236:239], v[2:5]
	v_mfma_f32_16x16x32_bf16 v[42:45], v[150:153], v[206:209], v[34:37]
	v_mfma_f32_16x16x32_bf16 v[22:25], v[126:129], v[218:221], v[22:25]
	v_mfma_f32_16x16x32_bf16 v[18:21], v[150:153], v[218:221], v[18:21]
	v_mfma_f32_16x16x32_bf16 v[6:9], v[126:129], v[240:243], v[6:9]
	v_mfma_f32_16x16x32_bf16 v[2:5], v[150:153], v[240:243], v[2:5]
	s_barrier
	s_cbranch_scc0 .LBB0_788
	s_and_b64 vcc, exec, s[46:47]
	s_cbranch_vccz .LBB0_791
	s_barrier

; #define PG8_STAGE(bufoff, gbase, voff) do { _Pragma("unroll") for (int _i = 0; _i < 2; ++_i) \
;         __builtin_amdgcn_global_load_lds((const unsigned*)((const char*)(gbase) + (voff)[_i]), (PG8_LAS unsigned*)(lds + (bufoff) + ldsw + _i * 8192), 16, 0, 0); } while (0)
; #define PG8_LDA(dst, b, h) do { _Pragma("unroll") for (int m = 0; m < 4; ++m) _Pragma("unroll") for (int k = 0; k < 2; ++k) dst[m][k] = *(const PG8_LAS bf16x8*)(lds + PG8_SA(b, h) + aoff + m * 2048 + k * 1024); } while (0)
; #define PG8_LDB(dst, b, h) do { _Pragma("unroll") for (int n = 0; n < 2; ++n) _Pragma("unroll") for (int k = 0; k < 2; ++k) dst[n][k] = *(const PG8_LAS bf16x8*)(lds + PG8_SB(b, h) + boff + n * 2048 + k * 1024); } while (0)
; #define PG8_WAIT_V(n) asm volatile("s_waitcnt vmcnt(" #n ")" ::: "memory")
; #define PG8_WAIT_L(n) asm volatile("s_waitcnt lgkmcnt(" #n ")" ::: "memory")
; #define PG8_BAR __builtin_amdgcn_s_barrier()
; #define PG8_SCHED __builtin_amdgcn_sched_barrier(0)
; template <class Epi, class Sched, bool ALIGN_EPI = false, bool SP2 = false>
; __device__ __forceinline__ void gemm_phase(PG8_LAS unsigned char* lds, const Gemm g, const Sched& S, const Epi& E) {
;     ...
;         const bool has_next = S.next(ui + 1, nxt);
;         const char* nA = has_next ? (const char*)g.A + (size_t)nxt.pm * tstep : cA; const char* nB = has_next ? (const char*)g.Bt + (size_t)nxt.pn * tstep : cB;
;         for (int t = 0; t < nt; t += 2) {
;             const bool last = (t == nt - 2);
;             const char* a1 = cA + (size_t)(t + 1) * kstep;
;             const char* a2 = last ? nA : cA + (size_t)(t + 2) * kstep; const char* b2 = last ? nB : cB + (size_t)(t + 2) * kstep;
;             const char* a3 = a2 + kstep; const char* b3 = b2 + kstep;
;             if (last && has_next) S.a_ready(nxt);
;             if constexpr (SP2) {
;             PG8_LDB(B0, 0, 0); PG8_LDB(B1, 0, 1); PG8_SCHED; PG8_LDA(At, 0, 0); PG8_STAGE(PG8_SA(1, 1), a1 + hstep, voffA);
;             PG8_WAIT_V(8); PG8_WAIT_L(0); PG8_BAR; PG8_MMA(0, 0, At, B0); PG8_MMA(0, 1, At, B1); PG8_BAR; PG8_SCHED;
;             PG8_LDA(At, 0, 1); PG8_STAGE(PG8_SB(0, 0), b2, voffB); PG8_STAGE(PG8_SB(0, 1), b2 + hstepB, voffB); PG8_STAGE(PG8_SA(0, 0), a2, voffA);
;             PG8_WAIT_V(8); PG8_WAIT_L(0); PG8_BAR; PG8_MMA(1, 0, At, B0); PG8_MMA(1, 1, At, B1); PG8_BAR; PG8_SCHED;
.LBB0_926:
	s_ashr_i32 s73, s72, 31
	s_lshl_b64 s[4:5], s[72:73], 20
	v_readlane_b32 s6, v249, 9
	v_readlane_b32 s7, v249, 10
	s_add_u32 s76, s6, s4
	s_addc_u32 s77, s7, s5
	s_and_b64 s[4:5], s[92:93], exec
	s_cselect_b32 s36, s77, s39
	s_cselect_b32 s37, s76, s38
	s_ashr_i32 s69, s68, 31
	s_lshl_b64 s[4:5], s[68:69], 20
	v_readlane_b32 s6, v249, 17
	v_readlane_b32 s7, v249, 18
	s_add_u32 s80, s6, s4
	s_addc_u32 s81, s7, s5
	s_and_b64 s[4:5], s[92:93], exec
	s_cselect_b32 s4, s81, s47
	s_cselect_b32 s5, s80, s46
	s_add_u32 s38, s38, 0x80080
	s_addc_u32 s39, s39, 0
	s_add_u32 s6, s46, 0x100
	v_mov_b32_e32 v2, 0
	s_addc_u32 s7, s47, 0
	s_mov_b32 s8, -2
	v_mov_b32_e32 v3, v2
	v_mov_b32_e32 v4, v2
	v_mov_b32_e32 v5, v2
	v_mov_b32_e32 v6, v2
	v_mov_b32_e32 v7, v2
	v_mov_b32_e32 v8, v2
	v_mov_b32_e32 v9, v2
	v_mov_b32_e32 v18, v2
	v_mov_b32_e32 v19, v2
	v_mov_b32_e32 v20, v2
	v_mov_b32_e32 v21, v2
	v_mov_b32_e32 v22, v2
	v_mov_b32_e32 v23, v2
	v_mov_b32_e32 v24, v2
	v_mov_b32_e32 v25, v2
	v_mov_b32_e32 v34, v2
	s_waitcnt lgkmcnt(0)
	v_add_u32_e32 v186, 0x10000, v193
	v_add_u32_e32 v187, 0x14000, v193
	v_add_u32_e32 v198, 0x18000, v193
	v_add_u32_e32 v199, 0x1c000, v193
	s_add_u32 s9, s38, 0xfff80080
	s_addc_u32 s10, s39, -1
	s_add_i32 s11, 0, 0x10000
	s_cmp_eq_u32 s8, 28
	s_cselect_b32 s95, s36, s10
	s_cselect_b32 s94, s37, s9
	s_cselect_b32 s47, s4, s7
	s_cselect_b32 s46, s5, s6
	s_add_i32 s9, 0, 0x14000
	ds_read_b128 v[66:69], v186
	ds_read_b128 v[70:73], v186 offset:1024
	ds_read_b128 v[78:81], v186 offset:2048
	ds_read_b128 v[86:89], v186 offset:3072
	ds_read_b128 v[146:149], v187
	ds_read_b128 v[150:153], v187 offset:1024
	ds_read_b128 v[154:157], v187 offset:2048
	ds_read_b128 v[158:161], v187 offset:3072
	s_add_i32 m0, s66, 0xc000
	ds_read_b128 v[162:165], v236
	ds_read_b128 v[166:169], v236 offset:1024
	ds_read_b128 v[170:173], v236 offset:2048
	ds_read_b128 v[174:177], v236 offset:3072
	ds_read_b128 v[178:181], v236 offset:4096
	ds_read_b128 v[182:185], v236 offset:5120
	ds_read_b128 v[216:219], v236 offset:6144
	ds_read_b128 v[220:223], v236 offset:7168
	global_load_lds_dwordx4 v212, s[38:39]
	s_add_i32 m0, s66, 0xe000
	s_nop 0
	global_load_lds_dwordx4 v214, s[38:39]
	s_waitcnt vmcnt(8)
	s_waitcnt lgkmcnt(0)
	s_barrier
	v_mfma_f32_16x16x32_bf16 v[142:145], v[66:69], v[162:165], 0
	v_mfma_f32_16x16x32_bf16 v[138:141], v[78:81], v[162:165], 0
	v_mfma_f32_16x16x32_bf16 v[126:129], v[66:69], v[170:173], 0
	v_mfma_f32_16x16x32_bf16 v[122:125], v[78:81], v[170:173], 0
	v_mfma_f32_16x16x32_bf16 v[110:113], v[66:69], v[178:181], 0
	v_mfma_f32_16x16x32_bf16 v[106:109], v[78:81], v[178:181], 0
	v_mfma_f32_16x16x32_bf16 v[94:97], v[66:69], v[216:219], 0
	v_mfma_f32_16x16x32_bf16 v[90:93], v[78:81], v[216:219], 0
	v_mfma_f32_16x16x32_bf16 v[142:145], v[70:73], v[166:169], v[142:145]
	v_mfma_f32_16x16x32_bf16 v[138:141], v[86:89], v[166:169], v[138:141]
	v_mfma_f32_16x16x32_bf16 v[126:129], v[70:73], v[174:177], v[126:129]
	v_mfma_f32_16x16x32_bf16 v[122:125], v[86:89], v[174:177], v[122:125]
	v_mfma_f32_16x16x32_bf16 v[110:113], v[70:73], v[182:185], v[110:113]
	v_mfma_f32_16x16x32_bf16 v[106:109], v[86:89], v[182:185], v[106:109]
	v_mfma_f32_16x16x32_bf16 v[94:97], v[70:73], v[220:223], v[94:97]
	v_mfma_f32_16x16x32_bf16 v[90:93], v[86:89], v[220:223], v[90:93]
	v_mfma_f32_16x16x32_bf16 v[134:137], v[146:149], v[162:165], 0
	v_mfma_f32_16x16x32_bf16 v[130:133], v[154:157], v[162:165], 0
	v_mfma_f32_16x16x32_bf16 v[118:121], v[146:149], v[170:173], 0
	v_mfma_f32_16x16x32_bf16 v[114:117], v[154:157], v[170:173], 0
	v_mfma_f32_16x16x32_bf16 v[102:105], v[146:149], v[178:181], 0
	v_mfma_f32_16x16x32_bf16 v[98:101], v[154:157], v[178:181], 0
	v_mfma_f32_16x16x32_bf16 v[82:85], v[146:149], v[216:219], 0
	v_mfma_f32_16x16x32_bf16 v[74:77], v[154:157], v[216:219], 0
	v_mfma_f32_16x16x32_bf16 v[134:137], v[150:153], v[166:169], v[134:137]
	v_mfma_f32_16x16x32_bf16 v[130:133], v[158:161], v[166:169], v[130:133]
	v_mfma_f32_16x16x32_bf16 v[118:121], v[150:153], v[174:177], v[118:121]
	v_mfma_f32_16x16x32_bf16 v[114:117], v[158:161], v[174:177], v[114:117]
	v_mfma_f32_16x16x32_bf16 v[102:105], v[150:153], v[182:185], v[102:105]
	v_mfma_f32_16x16x32_bf16 v[98:101], v[158:161], v[182:185], v[98:101]
	v_mfma_f32_16x16x32_bf16 v[82:85], v[150:153], v[220:223], v[82:85]
	v_mfma_f32_16x16x32_bf16 v[74:77], v[158:161], v[220:223], v[74:77]
	s_barrier
	ds_read_b128 v[162:165], v236 offset:16384
	ds_read_b128 v[166:169], v236 offset:17408
	ds_read_b128 v[170:173], v236 offset:18432
	ds_read_b128 v[174:177], v236 offset:19456
	ds_read_b128 v[178:181], v236 offset:20480
	ds_read_b128 v[182:185], v236 offset:21504
	ds_read_b128 v[216:219], v236 offset:22528
	ds_read_b128 v[220:223], v236 offset:23552
	s_add_i32 s10, s11, s25
	s_mov_b32 m0, s10
	s_nop 0
	global_load_lds_dwordx4 v190, s[46:47]
	s_add_i32 m0, s10, 0x2000
	s_add_u32 s10, s46, 0x20000
	s_addc_u32 s11, s47, 0
	s_add_i32 s9, s9, s25
	global_load_lds_dwordx4 v206, s[46:47]
	s_mov_b32 m0, s9
	s_nop 0
	global_load_lds_dwordx4 v190, s[10:11]
	s_add_i32 m0, s9, 0x2000
	s_nop 0
	global_load_lds_dwordx4 v206, s[10:11]
	s_mov_b32 m0, s66
	s_nop 0
	global_load_lds_dwordx4 v210, s[94:95]
	s_mov_b32 m0, s67
	s_nop 0
	global_load_lds_dwordx4 v208, s[94:95]
	s_waitcnt vmcnt(8)
	s_waitcnt lgkmcnt(0)
	s_barrier
; #define PG8_STAGE(bufoff, gbase, voff) do { _Pragma("unroll") for (int _i = 0; _i < 2; ++_i) \
;         __builtin_amdgcn_global_load_lds((const unsigned*)((const char*)(gbase) + (voff)[_i]), (PG8_LAS unsigned*)(lds + (bufoff) + ldsw + _i * 8192), 16, 0, 0); } while (0)
; #define PG8_LDA(dst, b, h) do { _Pragma("unroll") for (int m = 0; m < 4; ++m) _Pragma("unroll") for (int k = 0; k < 2; ++k) dst[m][k] = *(const PG8_LAS bf16x8*)(lds + PG8_SA(b, h) + aoff + m * 2048 + k * 1024); } while (0)
; #define PG8_LDB(dst, b, h) do { _Pragma("unroll") for (int n = 0; n < 2; ++n) _Pragma("unroll") for (int k = 0; k < 2; ++k) dst[n][k] = *(const PG8_LAS bf16x8*)(lds + PG8_SB(b, h) + boff + n * 2048 + k * 1024); } while (0)
; #define PG8_MMA(ai, bj, At, Bt) do { __builtin_amdgcn_s_setprio(1); _Pragma("unroll") for (int m = 0; m < 4; ++m) _Pragma("unroll") for (int n = 0; n < 2; ++n) _Pragma("unroll") for (int k = 0; k < 2; ++k) \
;         acc[ai][bj][m][n] = __builtin_amdgcn_mfma_f32_16x16x32_bf16(Bt[n][k], At[m][k], acc[ai][bj][m][n], 0, 0, 0); __builtin_amdgcn_s_setprio(0); } while (0)
; #define PG8_WAIT_V(n) asm volatile("s_waitcnt vmcnt(" #n ")" ::: "memory")
; #define PG8_WAIT_L(n) asm volatile("s_waitcnt lgkmcnt(" #n ")" ::: "memory")
; #define PG8_BAR __builtin_amdgcn_s_barrier()
; #define PG8_SCHED __builtin_amdgcn_sched_barrier(0)
; template <class Epi, class Sched, bool ALIGN_EPI = false, bool SP2 = false>
; __device__ __forceinline__ void gemm_phase(PG8_LAS unsigned char* lds, const Gemm g, const Sched& S, const Epi& E) {
;     ...
;             PG8_WAIT_V(8); PG8_WAIT_L(0); PG8_BAR; PG8_MMA(1, 0, At, B0); PG8_MMA(1, 1, At, B1); PG8_BAR; PG8_SCHED;
;             PG8_LDB(B0, 1, 0); PG8_LDB(B1, 1, 1); PG8_SCHED; PG8_LDA(At, 1, 0); PG8_STAGE(PG8_SA(0, 1), a2 + hstep, voffA);
;             PG8_WAIT_V(8); PG8_WAIT_L(0); PG8_BAR; PG8_MMA(0, 0, At, B0); PG8_MMA(0, 1, At, B1); PG8_BAR; PG8_SCHED;
	v_mfma_f32_16x16x32_bf16 v[62:65], v[66:69], v[162:165], 0
	v_mfma_f32_16x16x32_bf16 v[58:61], v[78:81], v[162:165], 0
	v_mfma_f32_16x16x32_bf16 v[46:49], v[66:69], v[170:173], 0
	v_mfma_f32_16x16x32_bf16 v[42:45], v[78:81], v[170:173], 0
	v_mfma_f32_16x16x32_bf16 v[30:33], v[66:69], v[178:181], 0
	v_mfma_f32_16x16x32_bf16 v[26:29], v[78:81], v[178:181], 0
	v_mfma_f32_16x16x32_bf16 v[14:17], v[66:69], v[216:219], 0
	v_mfma_f32_16x16x32_bf16 v[10:13], v[78:81], v[216:219], 0
	v_mfma_f32_16x16x32_bf16 v[62:65], v[70:73], v[166:169], v[62:65]
	v_mfma_f32_16x16x32_bf16 v[58:61], v[86:89], v[166:169], v[58:61]
	v_mfma_f32_16x16x32_bf16 v[46:49], v[70:73], v[174:177], v[46:49]
	v_mfma_f32_16x16x32_bf16 v[42:45], v[86:89], v[174:177], v[42:45]
	v_mfma_f32_16x16x32_bf16 v[30:33], v[70:73], v[182:185], v[30:33]
	v_mfma_f32_16x16x32_bf16 v[26:29], v[86:89], v[182:185], v[26:29]
	v_mfma_f32_16x16x32_bf16 v[14:17], v[70:73], v[220:223], v[14:17]
	v_mfma_f32_16x16x32_bf16 v[10:13], v[86:89], v[220:223], v[10:13]
	v_mfma_f32_16x16x32_bf16 v[54:57], v[146:149], v[162:165], 0
	v_mfma_f32_16x16x32_bf16 v[50:53], v[154:157], v[162:165], 0
	v_mfma_f32_16x16x32_bf16 v[38:41], v[146:149], v[170:173], 0
	v_mfma_f32_16x16x32_bf16 v[34:37], v[154:157], v[170:173], 0
	v_mfma_f32_16x16x32_bf16 v[22:25], v[146:149], v[178:181], 0
	v_mfma_f32_16x16x32_bf16 v[18:21], v[154:157], v[178:181], 0
	v_mfma_f32_16x16x32_bf16 v[6:9], v[146:149], v[216:219], 0
	v_mfma_f32_16x16x32_bf16 v[2:5], v[154:157], v[216:219], 0
	v_mfma_f32_16x16x32_bf16 v[54:57], v[150:153], v[166:169], v[54:57]
	v_mfma_f32_16x16x32_bf16 v[50:53], v[158:161], v[166:169], v[50:53]
	v_mfma_f32_16x16x32_bf16 v[38:41], v[150:153], v[174:177], v[38:41]
	v_mfma_f32_16x16x32_bf16 v[34:37], v[158:161], v[174:177], v[34:37]
	v_mfma_f32_16x16x32_bf16 v[22:25], v[150:153], v[182:185], v[22:25]
	v_mfma_f32_16x16x32_bf16 v[18:21], v[158:161], v[182:185], v[18:21]
	v_mfma_f32_16x16x32_bf16 v[6:9], v[150:153], v[220:223], v[6:9]
	v_mfma_f32_16x16x32_bf16 v[2:5], v[158:161], v[220:223], v[2:5]
	s_barrier
	ds_read_b128 v[66:69], v198
	ds_read_b128 v[70:73], v198 offset:1024
	ds_read_b128 v[78:81], v198 offset:2048
	ds_read_b128 v[86:89], v198 offset:3072
	ds_read_b128 v[146:149], v199
	ds_read_b128 v[150:153], v199 offset:1024
	ds_read_b128 v[154:157], v199 offset:2048
	ds_read_b128 v[158:161], v199 offset:3072
	ds_read_b128 v[162:165], v236 offset:32768
	ds_read_b128 v[166:169], v236 offset:33792
	ds_read_b128 v[170:173], v236 offset:34816
	ds_read_b128 v[174:177], v236 offset:35840
	ds_read_b128 v[178:181], v236 offset:36864
	ds_read_b128 v[182:185], v236 offset:37888
	ds_read_b128 v[216:219], v236 offset:38912
	ds_read_b128 v[220:223], v236 offset:39936
	s_add_i32 s9, 0, 0x18000
	s_add_i32 s12, 0, 0x1c000
	s_add_u32 s10, s94, 0x80000
	s_addc_u32 s11, s95, 0
	s_mov_b32 m0, s59
	s_nop 0
	global_load_lds_dwordx4 v210, s[10:11]
	s_mov_b32 m0, s74
	s_nop 0
	global_load_lds_dwordx4 v208, s[10:11]
	s_waitcnt vmcnt(8)
	s_waitcnt lgkmcnt(0)
	s_barrier
	v_mfma_f32_16x16x32_bf16 v[142:145], v[66:69], v[162:165], v[142:145]
	v_mfma_f32_16x16x32_bf16 v[138:141], v[78:81], v[162:165], v[138:141]
	v_mfma_f32_16x16x32_bf16 v[126:129], v[66:69], v[170:173], v[126:129]
	v_mfma_f32_16x16x32_bf16 v[122:125], v[78:81], v[170:173], v[122:125]
	v_mfma_f32_16x16x32_bf16 v[110:113], v[66:69], v[178:181], v[110:113]
	v_mfma_f32_16x16x32_bf16 v[106:109], v[78:81], v[178:181], v[106:109]
	v_mfma_f32_16x16x32_bf16 v[94:97], v[66:69], v[216:219], v[94:97]
	v_mfma_f32_16x16x32_bf16 v[90:93], v[78:81], v[216:219], v[90:93]
	v_mfma_f32_16x16x32_bf16 v[142:145], v[70:73], v[166:169], v[142:145]
	v_mfma_f32_16x16x32_bf16 v[138:141], v[86:89], v[166:169], v[138:141]
	v_mfma_f32_16x16x32_bf16 v[126:129], v[70:73], v[174:177], v[126:129]
	v_mfma_f32_16x16x32_bf16 v[122:125], v[86:89], v[174:177], v[122:125]
	v_mfma_f32_16x16x32_bf16 v[110:113], v[70:73], v[182:185], v[110:113]
	v_mfma_f32_16x16x32_bf16 v[106:109], v[86:89], v[182:185], v[106:109]
	v_mfma_f32_16x16x32_bf16 v[94:97], v[70:73], v[220:223], v[94:97]
	v_mfma_f32_16x16x32_bf16 v[90:93], v[86:89], v[220:223], v[90:93]
	v_mfma_f32_16x16x32_bf16 v[134:137], v[146:149], v[162:165], v[134:137]
	v_mfma_f32_16x16x32_bf16 v[130:133], v[154:157], v[162:165], v[130:133]
	v_mfma_f32_16x16x32_bf16 v[118:121], v[146:149], v[170:173], v[118:121]
	v_mfma_f32_16x16x32_bf16 v[114:117], v[154:157], v[170:173], v[114:117]
	v_mfma_f32_16x16x32_bf16 v[102:105], v[146:149], v[178:181], v[102:105]
	v_mfma_f32_16x16x32_bf16 v[98:101], v[154:157], v[178:181], v[98:101]
	v_mfma_f32_16x16x32_bf16 v[82:85], v[146:149], v[216:219], v[82:85]
	v_mfma_f32_16x16x32_bf16 v[74:77], v[154:157], v[216:219], v[74:77]
	v_mfma_f32_16x16x32_bf16 v[134:137], v[150:153], v[166:169], v[134:137]
	v_mfma_f32_16x16x32_bf16 v[130:133], v[158:161], v[166:169], v[130:133]
	v_mfma_f32_16x16x32_bf16 v[118:121], v[150:153], v[174:177], v[118:121]
	v_mfma_f32_16x16x32_bf16 v[114:117], v[158:161], v[174:177], v[114:117]
	v_mfma_f32_16x16x32_bf16 v[102:105], v[150:153], v[182:185], v[102:105]
	v_mfma_f32_16x16x32_bf16 v[98:101], v[158:161], v[182:185], v[98:101]
	v_mfma_f32_16x16x32_bf16 v[82:85], v[150:153], v[220:223], v[82:85]
	v_mfma_f32_16x16x32_bf16 v[74:77], v[158:161], v[220:223], v[74:77]
	s_barrier
; #define PG8_STAGE(bufoff, gbase, voff) do { _Pragma("unroll") for (int _i = 0; _i < 2; ++_i) \
;         __builtin_amdgcn_global_load_lds((const unsigned*)((const char*)(gbase) + (voff)[_i]), (PG8_LAS unsigned*)(lds + (bufoff) + ldsw + _i * 8192), 16, 0, 0); } while (0)
; #define PG8_LDA(dst, b, h) do { _Pragma("unroll") for (int m = 0; m < 4; ++m) _Pragma("unroll") for (int k = 0; k < 2; ++k) dst[m][k] = *(const PG8_LAS bf16x8*)(lds + PG8_SA(b, h) + aoff + m * 2048 + k * 1024); } while (0)
; #define PG8_LDB(dst, b, h) do { _Pragma("unroll") for (int n = 0; n < 2; ++n) _Pragma("unroll") for (int k = 0; k < 2; ++k) dst[n][k] = *(const PG8_LAS bf16x8*)(lds + PG8_SB(b, h) + boff + n * 2048 + k * 1024); } while (0)
; #define PG8_MMA(ai, bj, At, Bt) do { __builtin_amdgcn_s_setprio(1); _Pragma("unroll") for (int m = 0; m < 4; ++m) _Pragma("unroll") for (int n = 0; n < 2; ++n) _Pragma("unroll") for (int k = 0; k < 2; ++k) \
;         acc[ai][bj][m][n] = __builtin_amdgcn_mfma_f32_16x16x32_bf16(Bt[n][k], At[m][k], acc[ai][bj][m][n], 0, 0, 0); __builtin_amdgcn_s_setprio(0); } while (0)
; #define PG8_WAIT_V(n) asm volatile("s_waitcnt vmcnt(" #n ")" ::: "memory")
; #define PG8_WAIT_L(n) asm volatile("s_waitcnt lgkmcnt(" #n ")" ::: "memory")
; #define PG8_BAR __builtin_amdgcn_s_barrier()
; template <class Epi, class Sched, bool ALIGN_EPI = false, bool SP2 = false>
; __device__ __forceinline__ void gemm_phase(PG8_LAS unsigned char* lds, const Gemm g, const Sched& S, const Epi& E) {
;     ...
;             const char* a1 = cA + (size_t)(t + 1) * kstep;
;             const char* a2 = last ? nA : cA + (size_t)(t + 2) * kstep; const char* b2 = last ? nB : cB + (size_t)(t + 2) * kstep;
;             const char* a3 = a2 + kstep; const char* b3 = b2 + kstep;
;             if (last && has_next) S.a_ready(nxt);
;             if constexpr (SP2) {
;             PG8_LDB(B0, 0, 0); PG8_LDB(B1, 0, 1); PG8_SCHED; PG8_LDA(At, 0, 0); PG8_STAGE(PG8_SA(1, 1), a1 + hstep, voffA);
;             PG8_WAIT_V(8); PG8_WAIT_L(0); PG8_BAR; PG8_MMA(0, 0, At, B0); PG8_MMA(0, 1, At, B1); PG8_BAR; PG8_SCHED;
;     ...
;             PG8_LDA(At, 1, 1); PG8_STAGE(PG8_SB(1, 0), b3, voffB); PG8_STAGE(PG8_SB(1, 1), b3 + hstepB, voffB); PG8_STAGE(PG8_SA(1, 0), a3, voffA);
;             PG8_WAIT_V(8); PG8_WAIT_L(0); PG8_BAR; PG8_MMA(1, 0, At, B0); PG8_MMA(1, 1, At, B1); PG8_BAR; PG8_SCHED;
	ds_read_b128 v[162:165], v236 offset:49152
	ds_read_b128 v[166:169], v236 offset:50176
	ds_read_b128 v[170:173], v236 offset:51200
	ds_read_b128 v[174:177], v236 offset:52224
	ds_read_b128 v[178:181], v236 offset:53248
	ds_read_b128 v[182:185], v236 offset:54272
	ds_read_b128 v[216:219], v236 offset:55296
	ds_read_b128 v[220:223], v236 offset:56320
	s_add_i32 s9, s9, s25
	s_mov_b32 m0, s9
	s_add_u32 s100, s46, s60
	s_addc_u32 s101, s47, s61
	global_load_lds_dwordx4 v190, s[100:101]
	s_add_i32 m0, s9, 0x2000
	s_add_u32 s10, s46, 0x20080
	s_addc_u32 s11, s47, 0
	s_add_i32 s9, s12, s25
	global_load_lds_dwordx4 v206, s[100:101]
	s_mov_b32 m0, s9
	s_nop 0
	global_load_lds_dwordx4 v190, s[10:11]
	s_add_i32 m0, s9, 0x2000
	s_nop 0
	global_load_lds_dwordx4 v206, s[10:11]
	s_mov_b32 m0, s75
	s_add_u32 s100, s94, s60
	s_addc_u32 s101, s95, s61
	global_load_lds_dwordx4 v210, s[100:101]
	s_mov_b32 m0, s0
	s_nop 0
	global_load_lds_dwordx4 v208, s[100:101]
	s_waitcnt vmcnt(8)
	s_waitcnt lgkmcnt(0)
	s_barrier
	v_mfma_f32_16x16x32_bf16 v[62:65], v[66:69], v[162:165], v[62:65]
	v_mfma_f32_16x16x32_bf16 v[58:61], v[78:81], v[162:165], v[58:61]
	v_mfma_f32_16x16x32_bf16 v[46:49], v[66:69], v[170:173], v[46:49]
	v_mfma_f32_16x16x32_bf16 v[42:45], v[78:81], v[170:173], v[42:45]
	v_mfma_f32_16x16x32_bf16 v[30:33], v[66:69], v[178:181], v[30:33]
	v_mfma_f32_16x16x32_bf16 v[26:29], v[78:81], v[178:181], v[26:29]
	v_mfma_f32_16x16x32_bf16 v[14:17], v[66:69], v[216:219], v[14:17]
	v_mfma_f32_16x16x32_bf16 v[10:13], v[78:81], v[216:219], v[10:13]
	v_mfma_f32_16x16x32_bf16 v[62:65], v[70:73], v[166:169], v[62:65]
	v_mfma_f32_16x16x32_bf16 v[58:61], v[86:89], v[166:169], v[58:61]
	v_mfma_f32_16x16x32_bf16 v[46:49], v[70:73], v[174:177], v[46:49]
	v_mfma_f32_16x16x32_bf16 v[42:45], v[86:89], v[174:177], v[42:45]
	v_mfma_f32_16x16x32_bf16 v[30:33], v[70:73], v[182:185], v[30:33]
	v_mfma_f32_16x16x32_bf16 v[26:29], v[86:89], v[182:185], v[26:29]
	v_mfma_f32_16x16x32_bf16 v[14:17], v[70:73], v[220:223], v[14:17]
	v_mfma_f32_16x16x32_bf16 v[10:13], v[86:89], v[220:223], v[10:13]
	v_mfma_f32_16x16x32_bf16 v[54:57], v[146:149], v[162:165], v[54:57]
	v_mfma_f32_16x16x32_bf16 v[50:53], v[154:157], v[162:165], v[50:53]
	v_mfma_f32_16x16x32_bf16 v[38:41], v[146:149], v[170:173], v[38:41]
	v_mfma_f32_16x16x32_bf16 v[34:37], v[154:157], v[170:173], v[34:37]
	v_mfma_f32_16x16x32_bf16 v[22:25], v[146:149], v[178:181], v[22:25]
	v_mfma_f32_16x16x32_bf16 v[18:21], v[154:157], v[178:181], v[18:21]
	s_add_i32 s8, s8, 2
	v_mfma_f32_16x16x32_bf16 v[6:9], v[146:149], v[216:219], v[6:9]
	s_add_u32 s38, s38, 0x100
	s_addc_u32 s39, s39, 0
	v_mfma_f32_16x16x32_bf16 v[2:5], v[154:157], v[216:219], v[2:5]
	s_add_u32 s6, s6, 0x100
	s_addc_u32 s7, s7, 0
	v_mfma_f32_16x16x32_bf16 v[54:57], v[150:153], v[166:169], v[54:57]
	s_cmp_gt_u32 s8, 29
	v_mfma_f32_16x16x32_bf16 v[50:53], v[158:161], v[166:169], v[50:53]
	v_mfma_f32_16x16x32_bf16 v[38:41], v[150:153], v[174:177], v[38:41]
	v_mfma_f32_16x16x32_bf16 v[34:37], v[158:161], v[174:177], v[34:37]
	v_mfma_f32_16x16x32_bf16 v[22:25], v[150:153], v[182:185], v[22:25]
	v_mfma_f32_16x16x32_bf16 v[18:21], v[158:161], v[182:185], v[18:21]
	v_mfma_f32_16x16x32_bf16 v[6:9], v[150:153], v[220:223], v[6:9]
	v_mfma_f32_16x16x32_bf16 v[2:5], v[158:161], v[220:223], v[2:5]
	s_barrier
.LBB0_927:
	ds_read_b128 v[66:69], v186
	ds_read_b128 v[70:73], v186 offset:1024
	ds_read_b128 v[78:81], v186 offset:2048
	ds_read_b128 v[86:89], v186 offset:3072
	ds_read_b128 v[146:149], v187
	ds_read_b128 v[150:153], v187 offset:1024
	ds_read_b128 v[154:157], v187 offset:2048
	ds_read_b128 v[158:161], v187 offset:3072
	ds_read_b128 v[162:165], v236
	ds_read_b128 v[166:169], v236 offset:1024
	ds_read_b128 v[170:173], v236 offset:2048
	ds_read_b128 v[174:177], v236 offset:3072
	ds_read_b128 v[178:181], v236 offset:4096
	ds_read_b128 v[182:185], v236 offset:5120
	ds_read_b128 v[216:219], v236 offset:6144
	ds_read_b128 v[220:223], v236 offset:7168
	s_add_u32 s9, s38, 0xfff80080
	s_addc_u32 s10, s39, -1
	s_add_i32 s11, 0, 0x10000
	s_cmp_eq_u32 s8, 28
	s_cselect_b32 s95, s36, s10
	s_cselect_b32 s94, s37, s9
	s_cselect_b32 s47, s4, s7
	s_cselect_b32 s46, s5, s6
	s_add_i32 s9, 0, 0x14000
	s_add_i32 m0, s66, 0xc000
	s_nop 0
	global_load_lds_dwordx4 v212, s[38:39]
	s_add_i32 m0, s66, 0xe000
	s_nop 0
	global_load_lds_dwordx4 v214, s[38:39]
	s_waitcnt vmcnt(8)
	s_waitcnt lgkmcnt(0)
	s_barrier
	v_mfma_f32_16x16x32_bf16 v[142:145], v[66:69], v[162:165], v[142:145]
	v_mfma_f32_16x16x32_bf16 v[138:141], v[78:81], v[162:165], v[138:141]
	v_mfma_f32_16x16x32_bf16 v[126:129], v[66:69], v[170:173], v[126:129]
	v_mfma_f32_16x16x32_bf16 v[122:125], v[78:81], v[170:173], v[122:125]
	v_mfma_f32_16x16x32_bf16 v[110:113], v[66:69], v[178:181], v[110:113]
	v_mfma_f32_16x16x32_bf16 v[106:109], v[78:81], v[178:181], v[106:109]
	v_mfma_f32_16x16x32_bf16 v[94:97], v[66:69], v[216:219], v[94:97]
	v_mfma_f32_16x16x32_bf16 v[90:93], v[78:81], v[216:219], v[90:93]
	v_mfma_f32_16x16x32_bf16 v[142:145], v[70:73], v[166:169], v[142:145]
	v_mfma_f32_16x16x32_bf16 v[138:141], v[86:89], v[166:169], v[138:141]
	v_mfma_f32_16x16x32_bf16 v[126:129], v[70:73], v[174:177], v[126:129]
	v_mfma_f32_16x16x32_bf16 v[122:125], v[86:89], v[174:177], v[122:125]
	v_mfma_f32_16x16x32_bf16 v[110:113], v[70:73], v[182:185], v[110:113]
	v_mfma_f32_16x16x32_bf16 v[106:109], v[86:89], v[182:185], v[106:109]
	v_mfma_f32_16x16x32_bf16 v[94:97], v[70:73], v[220:223], v[94:97]
	v_mfma_f32_16x16x32_bf16 v[90:93], v[86:89], v[220:223], v[90:93]
	v_mfma_f32_16x16x32_bf16 v[134:137], v[146:149], v[162:165], v[134:137]
	v_mfma_f32_16x16x32_bf16 v[130:133], v[154:157], v[162:165], v[130:133]
	v_mfma_f32_16x16x32_bf16 v[118:121], v[146:149], v[170:173], v[118:121]
	v_mfma_f32_16x16x32_bf16 v[114:117], v[154:157], v[170:173], v[114:117]
	v_mfma_f32_16x16x32_bf16 v[102:105], v[146:149], v[178:181], v[102:105]
	v_mfma_f32_16x16x32_bf16 v[98:101], v[154:157], v[178:181], v[98:101]
	v_mfma_f32_16x16x32_bf16 v[82:85], v[146:149], v[216:219], v[82:85]
	v_mfma_f32_16x16x32_bf16 v[74:77], v[154:157], v[216:219], v[74:77]
	v_mfma_f32_16x16x32_bf16 v[134:137], v[150:153], v[166:169], v[134:137]
	v_mfma_f32_16x16x32_bf16 v[130:133], v[158:161], v[166:169], v[130:133]
	v_mfma_f32_16x16x32_bf16 v[118:121], v[150:153], v[174:177], v[118:121]
	v_mfma_f32_16x16x32_bf16 v[114:117], v[158:161], v[174:177], v[114:117]
	v_mfma_f32_16x16x32_bf16 v[102:105], v[150:153], v[182:185], v[102:105]
	v_mfma_f32_16x16x32_bf16 v[98:101], v[158:161], v[182:185], v[98:101]
	v_mfma_f32_16x16x32_bf16 v[82:85], v[150:153], v[220:223], v[82:85]
	v_mfma_f32_16x16x32_bf16 v[74:77], v[158:161], v[220:223], v[74:77]
	s_barrier
; #define PG8_STAGE(bufoff, gbase, voff) do { _Pragma("unroll") for (int _i = 0; _i < 2; ++_i) \
;         __builtin_amdgcn_global_load_lds((const unsigned*)((const char*)(gbase) + (voff)[_i]), (PG8_LAS unsigned*)(lds + (bufoff) + ldsw + _i * 8192), 16, 0, 0); } while (0)
; #define PG8_LDA(dst, b, h) do { _Pragma("unroll") for (int m = 0; m < 4; ++m) _Pragma("unroll") for (int k = 0; k < 2; ++k) dst[m][k] = *(const PG8_LAS bf16x8*)(lds + PG8_SA(b, h) + aoff + m * 2048 + k * 1024); } while (0)
; #define PG8_LDB(dst, b, h) do { _Pragma("unroll") for (int n = 0; n < 2; ++n) _Pragma("unroll") for (int k = 0; k < 2; ++k) dst[n][k] = *(const PG8_LAS bf16x8*)(lds + PG8_SB(b, h) + boff + n * 2048 + k * 1024); } while (0)
; #define PG8_MMA(ai, bj, At, Bt) do { __builtin_amdgcn_s_setprio(1); _Pragma("unroll") for (int m = 0; m < 4; ++m) _Pragma("unroll") for (int n = 0; n < 2; ++n) _Pragma("unroll") for (int k = 0; k < 2; ++k) \
;         acc[ai][bj][m][n] = __builtin_amdgcn_mfma_f32_16x16x32_bf16(Bt[n][k], At[m][k], acc[ai][bj][m][n], 0, 0, 0); __builtin_amdgcn_s_setprio(0); } while (0)
; #define PG8_WAIT_V(n) asm volatile("s_waitcnt vmcnt(" #n ")" ::: "memory")
; #define PG8_WAIT_L(n) asm volatile("s_waitcnt lgkmcnt(" #n ")" ::: "memory")
; #define PG8_BAR __builtin_amdgcn_s_barrier()
; #define PG8_SCHED __builtin_amdgcn_sched_barrier(0)
; template <class Epi, class Sched, bool ALIGN_EPI = false, bool SP2 = false>
; __device__ __forceinline__ void gemm_phase(PG8_LAS unsigned char* lds, const Gemm g, const Sched& S, const Epi& E) {
;     ...
;             PG8_LDA(At, 0, 1); PG8_STAGE(PG8_SB(0, 0), b2, voffB); PG8_STAGE(PG8_SB(0, 1), b2 + hstepB, voffB); PG8_STAGE(PG8_SA(0, 0), a2, voffA);
;             PG8_WAIT_V(8); PG8_WAIT_L(0); PG8_BAR; PG8_MMA(1, 0, At, B0); PG8_MMA(1, 1, At, B1); PG8_BAR; PG8_SCHED;
;             PG8_LDB(B0, 1, 0); PG8_LDB(B1, 1, 1); PG8_SCHED; PG8_LDA(At, 1, 0); PG8_STAGE(PG8_SA(0, 1), a2 + hstep, voffA);
	ds_read_b128 v[162:165], v236 offset:16384
	ds_read_b128 v[166:169], v236 offset:17408
	ds_read_b128 v[170:173], v236 offset:18432
	ds_read_b128 v[174:177], v236 offset:19456
	ds_read_b128 v[178:181], v236 offset:20480
	ds_read_b128 v[182:185], v236 offset:21504
	ds_read_b128 v[216:219], v236 offset:22528
	ds_read_b128 v[220:223], v236 offset:23552
	s_add_i32 s10, s11, s25
	s_mov_b32 m0, s10
	s_nop 0
	global_load_lds_dwordx4 v190, s[46:47]
	s_add_i32 m0, s10, 0x2000
	s_add_u32 s10, s46, 0x20000
	s_addc_u32 s11, s47, 0
	s_add_i32 s9, s9, s25
	global_load_lds_dwordx4 v206, s[46:47]
	s_mov_b32 m0, s9
	s_nop 0
	global_load_lds_dwordx4 v190, s[10:11]
	s_add_i32 m0, s9, 0x2000
	s_nop 0
	global_load_lds_dwordx4 v206, s[10:11]
	s_mov_b32 m0, s66
	s_nop 0
	global_load_lds_dwordx4 v210, s[94:95]
	s_mov_b32 m0, s67
	s_nop 0
	global_load_lds_dwordx4 v208, s[94:95]
	s_waitcnt vmcnt(8)
	s_waitcnt lgkmcnt(0)
	s_barrier
	v_mfma_f32_16x16x32_bf16 v[62:65], v[66:69], v[162:165], v[62:65]
	v_mfma_f32_16x16x32_bf16 v[58:61], v[78:81], v[162:165], v[58:61]
	v_mfma_f32_16x16x32_bf16 v[46:49], v[66:69], v[170:173], v[46:49]
	v_mfma_f32_16x16x32_bf16 v[42:45], v[78:81], v[170:173], v[42:45]
	v_mfma_f32_16x16x32_bf16 v[30:33], v[66:69], v[178:181], v[30:33]
	v_mfma_f32_16x16x32_bf16 v[26:29], v[78:81], v[178:181], v[26:29]
	v_mfma_f32_16x16x32_bf16 v[14:17], v[66:69], v[216:219], v[14:17]
	v_mfma_f32_16x16x32_bf16 v[10:13], v[78:81], v[216:219], v[10:13]
	v_mfma_f32_16x16x32_bf16 v[62:65], v[70:73], v[166:169], v[62:65]
	v_mfma_f32_16x16x32_bf16 v[58:61], v[86:89], v[166:169], v[58:61]
	v_mfma_f32_16x16x32_bf16 v[46:49], v[70:73], v[174:177], v[46:49]
	v_mfma_f32_16x16x32_bf16 v[42:45], v[86:89], v[174:177], v[42:45]
	v_mfma_f32_16x16x32_bf16 v[30:33], v[70:73], v[182:185], v[30:33]
	v_mfma_f32_16x16x32_bf16 v[26:29], v[86:89], v[182:185], v[26:29]
	v_mfma_f32_16x16x32_bf16 v[14:17], v[70:73], v[220:223], v[14:17]
	v_mfma_f32_16x16x32_bf16 v[10:13], v[86:89], v[220:223], v[10:13]
	v_mfma_f32_16x16x32_bf16 v[54:57], v[146:149], v[162:165], v[54:57]
	v_mfma_f32_16x16x32_bf16 v[50:53], v[154:157], v[162:165], v[50:53]
	v_mfma_f32_16x16x32_bf16 v[38:41], v[146:149], v[170:173], v[38:41]
	v_mfma_f32_16x16x32_bf16 v[34:37], v[154:157], v[170:173], v[34:37]
	v_mfma_f32_16x16x32_bf16 v[22:25], v[146:149], v[178:181], v[22:25]
	v_mfma_f32_16x16x32_bf16 v[18:21], v[154:157], v[178:181], v[18:21]
	v_mfma_f32_16x16x32_bf16 v[6:9], v[146:149], v[216:219], v[6:9]
	v_mfma_f32_16x16x32_bf16 v[2:5], v[154:157], v[216:219], v[2:5]
	v_mfma_f32_16x16x32_bf16 v[54:57], v[150:153], v[166:169], v[54:57]
	v_mfma_f32_16x16x32_bf16 v[50:53], v[158:161], v[166:169], v[50:53]
	v_mfma_f32_16x16x32_bf16 v[38:41], v[150:153], v[174:177], v[38:41]
	v_mfma_f32_16x16x32_bf16 v[34:37], v[158:161], v[174:177], v[34:37]
	v_mfma_f32_16x16x32_bf16 v[22:25], v[150:153], v[182:185], v[22:25]
	v_mfma_f32_16x16x32_bf16 v[18:21], v[158:161], v[182:185], v[18:21]
	v_mfma_f32_16x16x32_bf16 v[6:9], v[150:153], v[220:223], v[6:9]
	v_mfma_f32_16x16x32_bf16 v[2:5], v[158:161], v[220:223], v[2:5]
	s_barrier
	ds_read_b128 v[66:69], v198
	ds_read_b128 v[70:73], v198 offset:1024
	ds_read_b128 v[78:81], v198 offset:2048
	ds_read_b128 v[86:89], v198 offset:3072
	ds_read_b128 v[146:149], v199
	ds_read_b128 v[150:153], v199 offset:1024
	ds_read_b128 v[154:157], v199 offset:2048
	ds_read_b128 v[158:161], v199 offset:3072
	ds_read_b128 v[162:165], v236 offset:32768
	ds_read_b128 v[166:169], v236 offset:33792
	ds_read_b128 v[170:173], v236 offset:34816
	ds_read_b128 v[174:177], v236 offset:35840
	ds_read_b128 v[178:181], v236 offset:36864
	ds_read_b128 v[182:185], v236 offset:37888
	ds_read_b128 v[216:219], v236 offset:38912
	ds_read_b128 v[220:223], v236 offset:39936
	s_add_i32 s9, 0, 0x18000
	s_add_i32 s12, 0, 0x1c000
	s_add_u32 s10, s94, 0x80000
	s_addc_u32 s11, s95, 0
	s_mov_b32 m0, s59
	s_nop 0
	global_load_lds_dwordx4 v210, s[10:11]
	s_mov_b32 m0, s74
	s_nop 0
	global_load_lds_dwordx4 v208, s[10:11]
	s_waitcnt vmcnt(8)
	s_waitcnt lgkmcnt(0)
	s_barrier
; #define PG8_STAGE(bufoff, gbase, voff) do { _Pragma("unroll") for (int _i = 0; _i < 2; ++_i) \
;         __builtin_amdgcn_global_load_lds((const unsigned*)((const char*)(gbase) + (voff)[_i]), (PG8_LAS unsigned*)(lds + (bufoff) + ldsw + _i * 8192), 16, 0, 0); } while (0)
; #define PG8_LDA(dst, b, h) do { _Pragma("unroll") for (int m = 0; m < 4; ++m) _Pragma("unroll") for (int k = 0; k < 2; ++k) dst[m][k] = *(const PG8_LAS bf16x8*)(lds + PG8_SA(b, h) + aoff + m * 2048 + k * 1024); } while (0)
; #define PG8_MMA(ai, bj, At, Bt) do { __builtin_amdgcn_s_setprio(1); _Pragma("unroll") for (int m = 0; m < 4; ++m) _Pragma("unroll") for (int n = 0; n < 2; ++n) _Pragma("unroll") for (int k = 0; k < 2; ++k) \
;         acc[ai][bj][m][n] = __builtin_amdgcn_mfma_f32_16x16x32_bf16(Bt[n][k], At[m][k], acc[ai][bj][m][n], 0, 0, 0); __builtin_amdgcn_s_setprio(0); } while (0)
; #define PG8_WAIT_V(n) asm volatile("s_waitcnt vmcnt(" #n ")" ::: "memory")
; #define PG8_WAIT_L(n) asm volatile("s_waitcnt lgkmcnt(" #n ")" ::: "memory")
; #define PG8_BAR __builtin_amdgcn_s_barrier()
; #define PG8_SCHED __builtin_amdgcn_sched_barrier(0)
; template <class Epi, class Sched, bool ALIGN_EPI = false, bool SP2 = false>
; __device__ __forceinline__ void gemm_phase(PG8_LAS unsigned char* lds, const Gemm g, const Sched& S, const Epi& E) {
;     ...
;             PG8_WAIT_V(8); PG8_WAIT_L(0); PG8_BAR; PG8_MMA(0, 0, At, B0); PG8_MMA(0, 1, At, B1); PG8_BAR; PG8_SCHED;
;             PG8_LDA(At, 1, 1); PG8_STAGE(PG8_SB(1, 0), b3, voffB); PG8_STAGE(PG8_SB(1, 1), b3 + hstepB, voffB); PG8_STAGE(PG8_SA(1, 0), a3, voffA);
;             PG8_WAIT_V(8); PG8_WAIT_L(0); PG8_BAR; PG8_MMA(1, 0, At, B0); PG8_MMA(1, 1, At, B1); PG8_BAR; PG8_SCHED;
	v_mfma_f32_16x16x32_bf16 v[142:145], v[66:69], v[162:165], v[142:145]
	v_mfma_f32_16x16x32_bf16 v[138:141], v[78:81], v[162:165], v[138:141]
	v_mfma_f32_16x16x32_bf16 v[126:129], v[66:69], v[170:173], v[126:129]
	v_mfma_f32_16x16x32_bf16 v[122:125], v[78:81], v[170:173], v[122:125]
	v_mfma_f32_16x16x32_bf16 v[110:113], v[66:69], v[178:181], v[110:113]
	v_mfma_f32_16x16x32_bf16 v[106:109], v[78:81], v[178:181], v[106:109]
	v_mfma_f32_16x16x32_bf16 v[94:97], v[66:69], v[216:219], v[94:97]
	v_mfma_f32_16x16x32_bf16 v[90:93], v[78:81], v[216:219], v[90:93]
	v_mfma_f32_16x16x32_bf16 v[142:145], v[70:73], v[166:169], v[142:145]
	v_mfma_f32_16x16x32_bf16 v[138:141], v[86:89], v[166:169], v[138:141]
	v_mfma_f32_16x16x32_bf16 v[126:129], v[70:73], v[174:177], v[126:129]
	v_mfma_f32_16x16x32_bf16 v[122:125], v[86:89], v[174:177], v[122:125]
	v_mfma_f32_16x16x32_bf16 v[110:113], v[70:73], v[182:185], v[110:113]
	v_mfma_f32_16x16x32_bf16 v[106:109], v[86:89], v[182:185], v[106:109]
	v_mfma_f32_16x16x32_bf16 v[94:97], v[70:73], v[220:223], v[94:97]
	v_mfma_f32_16x16x32_bf16 v[90:93], v[86:89], v[220:223], v[90:93]
	v_mfma_f32_16x16x32_bf16 v[134:137], v[146:149], v[162:165], v[134:137]
	v_mfma_f32_16x16x32_bf16 v[130:133], v[154:157], v[162:165], v[130:133]
	v_mfma_f32_16x16x32_bf16 v[118:121], v[146:149], v[170:173], v[118:121]
	v_mfma_f32_16x16x32_bf16 v[114:117], v[154:157], v[170:173], v[114:117]
	v_mfma_f32_16x16x32_bf16 v[102:105], v[146:149], v[178:181], v[102:105]
	v_mfma_f32_16x16x32_bf16 v[98:101], v[154:157], v[178:181], v[98:101]
	v_mfma_f32_16x16x32_bf16 v[82:85], v[146:149], v[216:219], v[82:85]
	v_mfma_f32_16x16x32_bf16 v[74:77], v[154:157], v[216:219], v[74:77]
	v_mfma_f32_16x16x32_bf16 v[134:137], v[150:153], v[166:169], v[134:137]
	v_mfma_f32_16x16x32_bf16 v[130:133], v[158:161], v[166:169], v[130:133]
	v_mfma_f32_16x16x32_bf16 v[118:121], v[150:153], v[174:177], v[118:121]
	v_mfma_f32_16x16x32_bf16 v[114:117], v[158:161], v[174:177], v[114:117]
	v_mfma_f32_16x16x32_bf16 v[102:105], v[150:153], v[182:185], v[102:105]
	v_mfma_f32_16x16x32_bf16 v[98:101], v[158:161], v[182:185], v[98:101]
	v_mfma_f32_16x16x32_bf16 v[82:85], v[150:153], v[220:223], v[82:85]
	v_mfma_f32_16x16x32_bf16 v[74:77], v[158:161], v[220:223], v[74:77]
	s_barrier
	ds_read_b128 v[162:165], v236 offset:49152
	ds_read_b128 v[166:169], v236 offset:50176
	ds_read_b128 v[170:173], v236 offset:51200
	ds_read_b128 v[174:177], v236 offset:52224
	ds_read_b128 v[178:181], v236 offset:53248
	ds_read_b128 v[182:185], v236 offset:54272
	ds_read_b128 v[216:219], v236 offset:55296
	ds_read_b128 v[220:223], v236 offset:56320
	s_add_i32 s9, s9, s25
	s_mov_b32 m0, s9
	s_add_u32 s100, s46, s60
	s_addc_u32 s101, s47, s61
	global_load_lds_dwordx4 v190, s[100:101]
	s_add_i32 m0, s9, 0x2000
	s_add_u32 s10, s46, 0x20080
	s_addc_u32 s11, s47, 0
	s_add_i32 s9, s12, s25
	global_load_lds_dwordx4 v206, s[100:101]
	s_mov_b32 m0, s9
	s_nop 0
	global_load_lds_dwordx4 v190, s[10:11]
	s_add_i32 m0, s9, 0x2000
	s_nop 0
	global_load_lds_dwordx4 v206, s[10:11]
	s_mov_b32 m0, s75
	s_add_u32 s100, s94, s60
	s_addc_u32 s101, s95, s61
	global_load_lds_dwordx4 v210, s[100:101]
	s_mov_b32 m0, s0
	s_nop 0
	global_load_lds_dwordx4 v208, s[100:101]
	s_waitcnt vmcnt(8)
	s_waitcnt lgkmcnt(0)
	s_barrier
	v_mfma_f32_16x16x32_bf16 v[62:65], v[66:69], v[162:165], v[62:65]
	v_mfma_f32_16x16x32_bf16 v[58:61], v[78:81], v[162:165], v[58:61]
	v_mfma_f32_16x16x32_bf16 v[46:49], v[66:69], v[170:173], v[46:49]
	v_mfma_f32_16x16x32_bf16 v[42:45], v[78:81], v[170:173], v[42:45]
	v_mfma_f32_16x16x32_bf16 v[30:33], v[66:69], v[178:181], v[30:33]
	v_mfma_f32_16x16x32_bf16 v[26:29], v[78:81], v[178:181], v[26:29]
	v_mfma_f32_16x16x32_bf16 v[14:17], v[66:69], v[216:219], v[14:17]
	v_mfma_f32_16x16x32_bf16 v[10:13], v[78:81], v[216:219], v[10:13]
	v_mfma_f32_16x16x32_bf16 v[62:65], v[70:73], v[166:169], v[62:65]
	v_mfma_f32_16x16x32_bf16 v[58:61], v[86:89], v[166:169], v[58:61]
	v_mfma_f32_16x16x32_bf16 v[46:49], v[70:73], v[174:177], v[46:49]
	v_mfma_f32_16x16x32_bf16 v[42:45], v[86:89], v[174:177], v[42:45]
	v_mfma_f32_16x16x32_bf16 v[30:33], v[70:73], v[182:185], v[30:33]
	v_mfma_f32_16x16x32_bf16 v[26:29], v[86:89], v[182:185], v[26:29]
	v_mfma_f32_16x16x32_bf16 v[14:17], v[70:73], v[220:223], v[14:17]
	v_mfma_f32_16x16x32_bf16 v[10:13], v[86:89], v[220:223], v[10:13]
	v_mfma_f32_16x16x32_bf16 v[54:57], v[146:149], v[162:165], v[54:57]
	v_mfma_f32_16x16x32_bf16 v[50:53], v[154:157], v[162:165], v[50:53]
	v_mfma_f32_16x16x32_bf16 v[38:41], v[146:149], v[170:173], v[38:41]
	v_mfma_f32_16x16x32_bf16 v[34:37], v[154:157], v[170:173], v[34:37]
	v_mfma_f32_16x16x32_bf16 v[22:25], v[146:149], v[178:181], v[22:25]
	v_mfma_f32_16x16x32_bf16 v[18:21], v[154:157], v[178:181], v[18:21]
	s_add_i32 s8, s8, 2
	v_mfma_f32_16x16x32_bf16 v[6:9], v[146:149], v[216:219], v[6:9]
	s_add_u32 s38, s38, 0x100
	s_addc_u32 s39, s39, 0
	v_mfma_f32_16x16x32_bf16 v[2:5], v[154:157], v[216:219], v[2:5]
	s_add_u32 s6, s6, 0x100
	s_addc_u32 s7, s7, 0
	v_mfma_f32_16x16x32_bf16 v[54:57], v[150:153], v[166:169], v[54:57]
	s_cmp_gt_u32 s8, 29
	v_mfma_f32_16x16x32_bf16 v[50:53], v[158:161], v[166:169], v[50:53]
	v_mfma_f32_16x16x32_bf16 v[38:41], v[150:153], v[174:177], v[38:41]
	v_mfma_f32_16x16x32_bf16 v[34:37], v[158:161], v[174:177], v[34:37]
	v_mfma_f32_16x16x32_bf16 v[22:25], v[150:153], v[182:185], v[22:25]
	v_mfma_f32_16x16x32_bf16 v[18:21], v[158:161], v[182:185], v[18:21]
	v_mfma_f32_16x16x32_bf16 v[6:9], v[150:153], v[220:223], v[6:9]
	v_mfma_f32_16x16x32_bf16 v[2:5], v[158:161], v[220:223], v[2:5]
	s_barrier
	s_cbranch_scc0 .LBB0_927
	s_and_b64 vcc, exec, s[70:71]
	s_cbranch_vccz .LBB0_930
	s_barrier

; #define PG8_STAGE(bufoff, gbase, voff) do { _Pragma("unroll") for (int _i = 0; _i < 2; ++_i) \
;         __builtin_amdgcn_global_load_lds((const unsigned*)((const char*)(gbase) + (voff)[_i]), (PG8_LAS unsigned*)(lds + (bufoff) + ldsw + _i * 8192), 16, 0, 0); } while (0)
; #define PG8_LDA(dst, b, h) do { _Pragma("unroll") for (int m = 0; m < 4; ++m) _Pragma("unroll") for (int k = 0; k < 2; ++k) dst[m][k] = *(const PG8_LAS bf16x8*)(lds + PG8_SA(b, h) + aoff + m * 2048 + k * 1024); } while (0)
; #define PG8_LDB(dst, b, h) do { _Pragma("unroll") for (int n = 0; n < 2; ++n) _Pragma("unroll") for (int k = 0; k < 2; ++k) dst[n][k] = *(const PG8_LAS bf16x8*)(lds + PG8_SB(b, h) + boff + n * 2048 + k * 1024); } while (0)
; #define PG8_WAIT_V(n) asm volatile("s_waitcnt vmcnt(" #n ")" ::: "memory")
; #define PG8_WAIT_L(n) asm volatile("s_waitcnt lgkmcnt(" #n ")" ::: "memory")
; #define PG8_BAR __builtin_amdgcn_s_barrier()
; #define PG8_SCHED __builtin_amdgcn_sched_barrier(0)
; template <class Epi, class Sched, bool ALIGN_EPI = false, bool SP2 = false>
; __device__ __forceinline__ void gemm_phase(PG8_LAS unsigned char* lds, const Gemm g, const Sched& S, const Epi& E) {
;     ...
;         const bool has_next = S.next(ui + 1, nxt);
;         const char* nA = has_next ? (const char*)g.A + (size_t)nxt.pm * tstep : cA; const char* nB = has_next ? (const char*)g.Bt + (size_t)nxt.pn * tstep : cB;
;         for (int t = 0; t < nt; t += 2) {
;             const bool last = (t == nt - 2);
;             const char* a1 = cA + (size_t)(t + 1) * kstep;
;             const char* a2 = last ? nA : cA + (size_t)(t + 2) * kstep; const char* b2 = last ? nB : cB + (size_t)(t + 2) * kstep;
;             const char* a3 = a2 + kstep; const char* b3 = b2 + kstep;
;             if (last && has_next) S.a_ready(nxt);
;             if constexpr (SP2) {
;             PG8_LDB(B0, 0, 0); PG8_LDB(B1, 0, 1); PG8_SCHED; PG8_LDA(At, 0, 0); PG8_STAGE(PG8_SA(1, 1), a1 + hstep, voffA);
;             PG8_WAIT_V(8); PG8_WAIT_L(0); PG8_BAR; PG8_MMA(0, 0, At, B0); PG8_MMA(0, 1, At, B1); PG8_BAR; PG8_SCHED;
;             PG8_LDA(At, 0, 1); PG8_STAGE(PG8_SB(0, 0), b2, voffB); PG8_STAGE(PG8_SB(0, 1), b2 + hstepB, voffB); PG8_STAGE(PG8_SA(0, 0), a2, voffA);
;             PG8_WAIT_V(8); PG8_WAIT_L(0); PG8_BAR; PG8_MMA(1, 0, At, B0); PG8_MMA(1, 1, At, B1); PG8_BAR; PG8_SCHED;
.LBB0_1070:
	s_ashr_i32 s97, s96, 31
	s_lshl_b64 s[4:5], s[96:97], 22
	s_add_u32 s26, s0, s4
	s_addc_u32 s27, s1, s5
	s_and_b64 s[4:5], s[92:93], exec
	s_cselect_b32 s97, s27, s39
	s_cselect_b32 s4, s26, s38
	s_ashr_i32 s85, s84, 31
	s_lshl_b64 s[6:7], s[84:85], 22
	s_add_u32 s94, s56, s6
	s_addc_u32 s95, s57, s7
	s_and_b64 s[6:7], s[92:93], exec
	s_cselect_b32 s5, s95, s47
	s_cselect_b32 s6, s94, s46
	s_add_u32 s38, s38, 0x200080
	s_addc_u32 s39, s39, 0
	s_add_u32 s7, s46, 0x100
	s_addc_u32 s8, s47, 0
	s_mov_b32 s9, -2
	s_waitcnt lgkmcnt(0)
	v_add_u32_e32 v186, 0x10000, v164
	v_add_u32_e32 v187, 0x14000, v164
	v_add_u32_e32 v198, 0x18000, v164
	v_add_u32_e32 v199, 0x1c000, v164
	s_add_u32 s10, s38, 0xffe00080
	s_addc_u32 s11, s39, -1
	s_add_i32 s12, 0, 0x10000
	s_cmpk_eq_i32 s9, 0x7c
	s_cselect_b32 vcc_hi, s97, s11
	s_cselect_b32 vcc_lo, s4, s10
	s_cselect_b32 s47, s5, s8
	s_cselect_b32 s46, s6, s7
	s_add_i32 s13, 0, 0x14000
	ds_read_b128 v[130:133], v186
	ds_read_b128 v[134:137], v186 offset:1024
	ds_read_b128 v[138:141], v186 offset:2048
	ds_read_b128 v[152:155], v186 offset:3072
	ds_read_b128 v[156:159], v187
	ds_read_b128 v[160:163], v187 offset:1024
	ds_read_b128 v[168:171], v187 offset:2048
	ds_read_b128 v[172:175], v187 offset:3072
	s_add_i32 m0, s74, 0xc000
	ds_read_b128 v[176:179], v166
	ds_read_b128 v[180:183], v166 offset:1024
	ds_read_b128 v[206:209], v166 offset:2048
	ds_read_b128 v[210:213], v166 offset:3072
	ds_read_b128 v[214:217], v166 offset:4096
	ds_read_b128 v[218:221], v166 offset:5120
	ds_read_b128 v[236:239], v166 offset:6144
	ds_read_b128 v[240:243], v166 offset:7168
	global_load_lds_dwordx4 v148, s[38:39]
	s_add_i32 m0, s74, 0xe000
	s_nop 0
	global_load_lds_dwordx4 v150, s[38:39]
	s_waitcnt vmcnt(8)
	s_waitcnt lgkmcnt(0)
	s_barrier
	v_mfma_f32_16x16x32_bf16 v[126:129], v[130:133], v[176:179], 0
	v_mfma_f32_16x16x32_bf16 v[122:125], v[138:141], v[176:179], 0
	v_mfma_f32_16x16x32_bf16 v[110:113], v[130:133], v[206:209], 0
	v_mfma_f32_16x16x32_bf16 v[106:109], v[138:141], v[206:209], 0
	v_mfma_f32_16x16x32_bf16 v[94:97], v[130:133], v[214:217], 0
	v_mfma_f32_16x16x32_bf16 v[90:93], v[138:141], v[214:217], 0
	v_mfma_f32_16x16x32_bf16 v[78:81], v[130:133], v[236:239], 0
	v_mfma_f32_16x16x32_bf16 v[74:77], v[138:141], v[236:239], 0
	v_mfma_f32_16x16x32_bf16 v[126:129], v[134:137], v[180:183], v[126:129]
	v_mfma_f32_16x16x32_bf16 v[122:125], v[152:155], v[180:183], v[122:125]
	v_mfma_f32_16x16x32_bf16 v[110:113], v[134:137], v[210:213], v[110:113]
	v_mfma_f32_16x16x32_bf16 v[106:109], v[152:155], v[210:213], v[106:109]
	v_mfma_f32_16x16x32_bf16 v[94:97], v[134:137], v[218:221], v[94:97]
	v_mfma_f32_16x16x32_bf16 v[90:93], v[152:155], v[218:221], v[90:93]
	v_mfma_f32_16x16x32_bf16 v[78:81], v[134:137], v[240:243], v[78:81]
	v_mfma_f32_16x16x32_bf16 v[74:77], v[152:155], v[240:243], v[74:77]
	v_mfma_f32_16x16x32_bf16 v[118:121], v[156:159], v[176:179], 0
	v_mfma_f32_16x16x32_bf16 v[114:117], v[168:171], v[176:179], 0
	v_mfma_f32_16x16x32_bf16 v[102:105], v[156:159], v[206:209], 0
	v_mfma_f32_16x16x32_bf16 v[98:101], v[168:171], v[206:209], 0
	v_mfma_f32_16x16x32_bf16 v[86:89], v[156:159], v[214:217], 0
	v_mfma_f32_16x16x32_bf16 v[82:85], v[168:171], v[214:217], 0
	v_mfma_f32_16x16x32_bf16 v[70:73], v[156:159], v[236:239], 0
	v_mfma_f32_16x16x32_bf16 v[66:69], v[168:171], v[236:239], 0
	v_mfma_f32_16x16x32_bf16 v[118:121], v[160:163], v[180:183], v[118:121]
	v_mfma_f32_16x16x32_bf16 v[114:117], v[172:175], v[180:183], v[114:117]
	v_mfma_f32_16x16x32_bf16 v[102:105], v[160:163], v[210:213], v[102:105]
	v_mfma_f32_16x16x32_bf16 v[98:101], v[172:175], v[210:213], v[98:101]
	v_mfma_f32_16x16x32_bf16 v[86:89], v[160:163], v[218:221], v[86:89]
	v_mfma_f32_16x16x32_bf16 v[82:85], v[172:175], v[218:221], v[82:85]
	v_mfma_f32_16x16x32_bf16 v[70:73], v[160:163], v[240:243], v[70:73]
	v_mfma_f32_16x16x32_bf16 v[66:69], v[172:175], v[240:243], v[66:69]
	s_barrier
	ds_read_b128 v[176:179], v166 offset:16384
	ds_read_b128 v[180:183], v166 offset:17408
	ds_read_b128 v[206:209], v166 offset:18432
	ds_read_b128 v[210:213], v166 offset:19456
	ds_read_b128 v[214:217], v166 offset:20480
	ds_read_b128 v[218:221], v166 offset:21504
	ds_read_b128 v[236:239], v166 offset:22528
	ds_read_b128 v[240:243], v166 offset:23552
	s_add_i32 s10, s12, s67
	s_mov_b32 m0, s10
	s_nop 0
	global_load_lds_dwordx4 v146, s[46:47]
	s_add_i32 m0, s10, 0x2000
	s_add_u32 s10, s46, 0x80000
	s_addc_u32 s11, s47, 0
	s_add_i32 s12, s13, s67
	global_load_lds_dwordx4 v142, s[46:47]
	s_mov_b32 m0, s12
	s_nop 0
	global_load_lds_dwordx4 v146, s[10:11]
	s_add_i32 m0, s12, 0x2000
	s_nop 0
	global_load_lds_dwordx4 v142, s[10:11]
	s_mov_b32 m0, s74
	s_nop 0
	global_load_lds_dwordx4 v190, vcc
	s_mov_b32 m0, s75
	s_nop 0
	global_load_lds_dwordx4 v144, vcc
	s_waitcnt vmcnt(8)
	s_waitcnt lgkmcnt(0)
	s_barrier
; #define PG8_STAGE(bufoff, gbase, voff) do { _Pragma("unroll") for (int _i = 0; _i < 2; ++_i) \
;         __builtin_amdgcn_global_load_lds((const unsigned*)((const char*)(gbase) + (voff)[_i]), (PG8_LAS unsigned*)(lds + (bufoff) + ldsw + _i * 8192), 16, 0, 0); } while (0)
; #define PG8_LDA(dst, b, h) do { _Pragma("unroll") for (int m = 0; m < 4; ++m) _Pragma("unroll") for (int k = 0; k < 2; ++k) dst[m][k] = *(const PG8_LAS bf16x8*)(lds + PG8_SA(b, h) + aoff + m * 2048 + k * 1024); } while (0)
; #define PG8_LDB(dst, b, h) do { _Pragma("unroll") for (int n = 0; n < 2; ++n) _Pragma("unroll") for (int k = 0; k < 2; ++k) dst[n][k] = *(const PG8_LAS bf16x8*)(lds + PG8_SB(b, h) + boff + n * 2048 + k * 1024); } while (0)
; #define PG8_MMA(ai, bj, At, Bt) do { __builtin_amdgcn_s_setprio(1); _Pragma("unroll") for (int m = 0; m < 4; ++m) _Pragma("unroll") for (int n = 0; n < 2; ++n) _Pragma("unroll") for (int k = 0; k < 2; ++k) \
;         acc[ai][bj][m][n] = __builtin_amdgcn_mfma_f32_16x16x32_bf16(Bt[n][k], At[m][k], acc[ai][bj][m][n], 0, 0, 0); __builtin_amdgcn_s_setprio(0); } while (0)
; #define PG8_WAIT_V(n) asm volatile("s_waitcnt vmcnt(" #n ")" ::: "memory")
; #define PG8_WAIT_L(n) asm volatile("s_waitcnt lgkmcnt(" #n ")" ::: "memory")
; #define PG8_BAR __builtin_amdgcn_s_barrier()
; #define PG8_SCHED __builtin_amdgcn_sched_barrier(0)
; template <class Epi, class Sched, bool ALIGN_EPI = false, bool SP2 = false>
; __device__ __forceinline__ void gemm_phase(PG8_LAS unsigned char* lds, const Gemm g, const Sched& S, const Epi& E) {
;     ...
;             PG8_WAIT_V(8); PG8_WAIT_L(0); PG8_BAR; PG8_MMA(1, 0, At, B0); PG8_MMA(1, 1, At, B1); PG8_BAR; PG8_SCHED;
;             PG8_LDB(B0, 1, 0); PG8_LDB(B1, 1, 1); PG8_SCHED; PG8_LDA(At, 1, 0); PG8_STAGE(PG8_SA(0, 1), a2 + hstep, voffA);
;             PG8_WAIT_V(8); PG8_WAIT_L(0); PG8_BAR; PG8_MMA(0, 0, At, B0); PG8_MMA(0, 1, At, B1); PG8_BAR; PG8_SCHED;
	v_mfma_f32_16x16x32_bf16 v[62:65], v[130:133], v[176:179], 0
	v_mfma_f32_16x16x32_bf16 v[58:61], v[138:141], v[176:179], 0
	v_mfma_f32_16x16x32_bf16 v[46:49], v[130:133], v[206:209], 0
	v_mfma_f32_16x16x32_bf16 v[42:45], v[138:141], v[206:209], 0
	v_mfma_f32_16x16x32_bf16 v[30:33], v[130:133], v[214:217], 0
	v_mfma_f32_16x16x32_bf16 v[26:29], v[138:141], v[214:217], 0
	v_mfma_f32_16x16x32_bf16 v[14:17], v[130:133], v[236:239], 0
	v_mfma_f32_16x16x32_bf16 v[10:13], v[138:141], v[236:239], 0
	v_mfma_f32_16x16x32_bf16 v[62:65], v[134:137], v[180:183], v[62:65]
	v_mfma_f32_16x16x32_bf16 v[58:61], v[152:155], v[180:183], v[58:61]
	v_mfma_f32_16x16x32_bf16 v[46:49], v[134:137], v[210:213], v[46:49]
	v_mfma_f32_16x16x32_bf16 v[42:45], v[152:155], v[210:213], v[42:45]
	v_mfma_f32_16x16x32_bf16 v[30:33], v[134:137], v[218:221], v[30:33]
	v_mfma_f32_16x16x32_bf16 v[26:29], v[152:155], v[218:221], v[26:29]
	v_mfma_f32_16x16x32_bf16 v[14:17], v[134:137], v[240:243], v[14:17]
	v_mfma_f32_16x16x32_bf16 v[10:13], v[152:155], v[240:243], v[10:13]
	v_mfma_f32_16x16x32_bf16 v[54:57], v[156:159], v[176:179], 0
	v_mfma_f32_16x16x32_bf16 v[50:53], v[168:171], v[176:179], 0
	v_mfma_f32_16x16x32_bf16 v[38:41], v[156:159], v[206:209], 0
	v_mfma_f32_16x16x32_bf16 v[34:37], v[168:171], v[206:209], 0
	v_mfma_f32_16x16x32_bf16 v[22:25], v[156:159], v[214:217], 0
	v_mfma_f32_16x16x32_bf16 v[18:21], v[168:171], v[214:217], 0
	v_mfma_f32_16x16x32_bf16 v[6:9], v[156:159], v[236:239], 0
	v_mfma_f32_16x16x32_bf16 v[2:5], v[168:171], v[236:239], 0
	v_mfma_f32_16x16x32_bf16 v[54:57], v[160:163], v[180:183], v[54:57]
	v_mfma_f32_16x16x32_bf16 v[50:53], v[172:175], v[180:183], v[50:53]
	v_mfma_f32_16x16x32_bf16 v[38:41], v[160:163], v[210:213], v[38:41]
	v_mfma_f32_16x16x32_bf16 v[34:37], v[172:175], v[210:213], v[34:37]
	v_mfma_f32_16x16x32_bf16 v[22:25], v[160:163], v[218:221], v[22:25]
	v_mfma_f32_16x16x32_bf16 v[18:21], v[172:175], v[218:221], v[18:21]
	v_mfma_f32_16x16x32_bf16 v[6:9], v[160:163], v[240:243], v[6:9]
	v_mfma_f32_16x16x32_bf16 v[2:5], v[172:175], v[240:243], v[2:5]
	s_barrier
	ds_read_b128 v[130:133], v198
	ds_read_b128 v[134:137], v198 offset:1024
	ds_read_b128 v[138:141], v198 offset:2048
	ds_read_b128 v[152:155], v198 offset:3072
	ds_read_b128 v[156:159], v199
	ds_read_b128 v[160:163], v199 offset:1024
	ds_read_b128 v[168:171], v199 offset:2048
	ds_read_b128 v[172:175], v199 offset:3072
	ds_read_b128 v[176:179], v166 offset:32768
	ds_read_b128 v[180:183], v166 offset:33792
	ds_read_b128 v[206:209], v166 offset:34816
	ds_read_b128 v[210:213], v166 offset:35840
	ds_read_b128 v[214:217], v166 offset:36864
	ds_read_b128 v[218:221], v166 offset:37888
	ds_read_b128 v[236:239], v166 offset:38912
	ds_read_b128 v[240:243], v166 offset:39936
	s_add_i32 s12, 0, 0x18000
	s_add_i32 s13, 0, 0x1c000
	s_add_u32 s10, vcc_lo, 0x200000
	s_addc_u32 s11, vcc_hi, 0
	s_mov_b32 m0, s86
	s_nop 0
	global_load_lds_dwordx4 v190, s[10:11]
	s_mov_b32 m0, s87
	s_nop 0
	global_load_lds_dwordx4 v144, s[10:11]
	s_waitcnt vmcnt(8)
	s_waitcnt lgkmcnt(0)
	s_barrier
	v_mfma_f32_16x16x32_bf16 v[126:129], v[130:133], v[176:179], v[126:129]
	v_mfma_f32_16x16x32_bf16 v[122:125], v[138:141], v[176:179], v[122:125]
	v_mfma_f32_16x16x32_bf16 v[110:113], v[130:133], v[206:209], v[110:113]
	v_mfma_f32_16x16x32_bf16 v[106:109], v[138:141], v[206:209], v[106:109]
	v_mfma_f32_16x16x32_bf16 v[94:97], v[130:133], v[214:217], v[94:97]
	v_mfma_f32_16x16x32_bf16 v[90:93], v[138:141], v[214:217], v[90:93]
	v_mfma_f32_16x16x32_bf16 v[78:81], v[130:133], v[236:239], v[78:81]
	v_mfma_f32_16x16x32_bf16 v[74:77], v[138:141], v[236:239], v[74:77]
	v_mfma_f32_16x16x32_bf16 v[126:129], v[134:137], v[180:183], v[126:129]
	v_mfma_f32_16x16x32_bf16 v[122:125], v[152:155], v[180:183], v[122:125]
	v_mfma_f32_16x16x32_bf16 v[110:113], v[134:137], v[210:213], v[110:113]
	v_mfma_f32_16x16x32_bf16 v[106:109], v[152:155], v[210:213], v[106:109]
	v_mfma_f32_16x16x32_bf16 v[94:97], v[134:137], v[218:221], v[94:97]
	v_mfma_f32_16x16x32_bf16 v[90:93], v[152:155], v[218:221], v[90:93]
	v_mfma_f32_16x16x32_bf16 v[78:81], v[134:137], v[240:243], v[78:81]
	v_mfma_f32_16x16x32_bf16 v[74:77], v[152:155], v[240:243], v[74:77]
	v_mfma_f32_16x16x32_bf16 v[118:121], v[156:159], v[176:179], v[118:121]
	v_mfma_f32_16x16x32_bf16 v[114:117], v[168:171], v[176:179], v[114:117]
	v_mfma_f32_16x16x32_bf16 v[102:105], v[156:159], v[206:209], v[102:105]
	v_mfma_f32_16x16x32_bf16 v[98:101], v[168:171], v[206:209], v[98:101]
	v_mfma_f32_16x16x32_bf16 v[86:89], v[156:159], v[214:217], v[86:89]
	v_mfma_f32_16x16x32_bf16 v[82:85], v[168:171], v[214:217], v[82:85]
	v_mfma_f32_16x16x32_bf16 v[70:73], v[156:159], v[236:239], v[70:73]
	v_mfma_f32_16x16x32_bf16 v[66:69], v[168:171], v[236:239], v[66:69]
	v_mfma_f32_16x16x32_bf16 v[118:121], v[160:163], v[180:183], v[118:121]
	v_mfma_f32_16x16x32_bf16 v[114:117], v[172:175], v[180:183], v[114:117]
	v_mfma_f32_16x16x32_bf16 v[102:105], v[160:163], v[210:213], v[102:105]
	v_mfma_f32_16x16x32_bf16 v[98:101], v[172:175], v[210:213], v[98:101]
	v_mfma_f32_16x16x32_bf16 v[86:89], v[160:163], v[218:221], v[86:89]
	v_mfma_f32_16x16x32_bf16 v[82:85], v[172:175], v[218:221], v[82:85]
	v_mfma_f32_16x16x32_bf16 v[70:73], v[160:163], v[240:243], v[70:73]
	v_mfma_f32_16x16x32_bf16 v[66:69], v[172:175], v[240:243], v[66:69]
	s_barrier
; #define PG8_STAGE(bufoff, gbase, voff) do { _Pragma("unroll") for (int _i = 0; _i < 2; ++_i) \
;         __builtin_amdgcn_global_load_lds((const unsigned*)((const char*)(gbase) + (voff)[_i]), (PG8_LAS unsigned*)(lds + (bufoff) + ldsw + _i * 8192), 16, 0, 0); } while (0)
; #define PG8_LDA(dst, b, h) do { _Pragma("unroll") for (int m = 0; m < 4; ++m) _Pragma("unroll") for (int k = 0; k < 2; ++k) dst[m][k] = *(const PG8_LAS bf16x8*)(lds + PG8_SA(b, h) + aoff + m * 2048 + k * 1024); } while (0)
; #define PG8_LDB(dst, b, h) do { _Pragma("unroll") for (int n = 0; n < 2; ++n) _Pragma("unroll") for (int k = 0; k < 2; ++k) dst[n][k] = *(const PG8_LAS bf16x8*)(lds + PG8_SB(b, h) + boff + n * 2048 + k * 1024); } while (0)
; #define PG8_MMA(ai, bj, At, Bt) do { __builtin_amdgcn_s_setprio(1); _Pragma("unroll") for (int m = 0; m < 4; ++m) _Pragma("unroll") for (int n = 0; n < 2; ++n) _Pragma("unroll") for (int k = 0; k < 2; ++k) \
;         acc[ai][bj][m][n] = __builtin_amdgcn_mfma_f32_16x16x32_bf16(Bt[n][k], At[m][k], acc[ai][bj][m][n], 0, 0, 0); __builtin_amdgcn_s_setprio(0); } while (0)
; #define PG8_WAIT_V(n) asm volatile("s_waitcnt vmcnt(" #n ")" ::: "memory")
; #define PG8_WAIT_L(n) asm volatile("s_waitcnt lgkmcnt(" #n ")" ::: "memory")
; #define PG8_BAR __builtin_amdgcn_s_barrier()
; template <class Epi, class Sched, bool ALIGN_EPI = false, bool SP2 = false>
; __device__ __forceinline__ void gemm_phase(PG8_LAS unsigned char* lds, const Gemm g, const Sched& S, const Epi& E) {
;     ...
;             const char* a1 = cA + (size_t)(t + 1) * kstep;
;             const char* a2 = last ? nA : cA + (size_t)(t + 2) * kstep; const char* b2 = last ? nB : cB + (size_t)(t + 2) * kstep;
;             const char* a3 = a2 + kstep; const char* b3 = b2 + kstep;
;             if (last && has_next) S.a_ready(nxt);
;             if constexpr (SP2) {
;             PG8_LDB(B0, 0, 0); PG8_LDB(B1, 0, 1); PG8_SCHED; PG8_LDA(At, 0, 0); PG8_STAGE(PG8_SA(1, 1), a1 + hstep, voffA);
;             PG8_WAIT_V(8); PG8_WAIT_L(0); PG8_BAR; PG8_MMA(0, 0, At, B0); PG8_MMA(0, 1, At, B1); PG8_BAR; PG8_SCHED;
;     ...
;             PG8_LDA(At, 1, 1); PG8_STAGE(PG8_SB(1, 0), b3, voffB); PG8_STAGE(PG8_SB(1, 1), b3 + hstepB, voffB); PG8_STAGE(PG8_SA(1, 0), a3, voffA);
;             PG8_WAIT_V(8); PG8_WAIT_L(0); PG8_BAR; PG8_MMA(1, 0, At, B0); PG8_MMA(1, 1, At, B1); PG8_BAR; PG8_SCHED;
	ds_read_b128 v[176:179], v166 offset:49152
	ds_read_b128 v[180:183], v166 offset:50176
	ds_read_b128 v[206:209], v166 offset:51200
	ds_read_b128 v[210:213], v166 offset:52224
	ds_read_b128 v[214:217], v166 offset:53248
	ds_read_b128 v[218:221], v166 offset:54272
	ds_read_b128 v[236:239], v166 offset:55296
	ds_read_b128 v[240:243], v166 offset:56320
	s_add_i32 s10, s12, s67
	s_mov_b32 m0, s10
	s_add_u32 s100, s46, s60
	s_addc_u32 s101, s47, s61
	global_load_lds_dwordx4 v146, s[100:101]
	s_add_i32 m0, s10, 0x2000
	s_add_u32 s10, s46, 0x80080
	s_addc_u32 s11, s47, 0
	s_add_i32 s12, s13, s67
	global_load_lds_dwordx4 v142, s[100:101]
	s_mov_b32 m0, s12
	s_nop 0
	global_load_lds_dwordx4 v146, s[10:11]
	s_add_i32 m0, s12, 0x2000
	s_nop 0
	global_load_lds_dwordx4 v142, s[10:11]
	s_mov_b32 m0, s82
	s_add_u32 s100, vcc_lo, s60
	s_addc_u32 s101, vcc_hi, s61
	global_load_lds_dwordx4 v190, s[100:101]
	s_mov_b32 m0, s42
	s_nop 0
	global_load_lds_dwordx4 v144, s[100:101]
	s_waitcnt vmcnt(8)
	s_waitcnt lgkmcnt(0)
	s_barrier
	v_mfma_f32_16x16x32_bf16 v[62:65], v[130:133], v[176:179], v[62:65]
	v_mfma_f32_16x16x32_bf16 v[58:61], v[138:141], v[176:179], v[58:61]
	v_mfma_f32_16x16x32_bf16 v[46:49], v[130:133], v[206:209], v[46:49]
	v_mfma_f32_16x16x32_bf16 v[42:45], v[138:141], v[206:209], v[42:45]
	v_mfma_f32_16x16x32_bf16 v[30:33], v[130:133], v[214:217], v[30:33]
	v_mfma_f32_16x16x32_bf16 v[26:29], v[138:141], v[214:217], v[26:29]
	v_mfma_f32_16x16x32_bf16 v[14:17], v[130:133], v[236:239], v[14:17]
	v_mfma_f32_16x16x32_bf16 v[10:13], v[138:141], v[236:239], v[10:13]
	v_mfma_f32_16x16x32_bf16 v[62:65], v[134:137], v[180:183], v[62:65]
	v_mfma_f32_16x16x32_bf16 v[58:61], v[152:155], v[180:183], v[58:61]
	v_mfma_f32_16x16x32_bf16 v[46:49], v[134:137], v[210:213], v[46:49]
	v_mfma_f32_16x16x32_bf16 v[42:45], v[152:155], v[210:213], v[42:45]
	v_mfma_f32_16x16x32_bf16 v[30:33], v[134:137], v[218:221], v[30:33]
	v_mfma_f32_16x16x32_bf16 v[26:29], v[152:155], v[218:221], v[26:29]
	v_mfma_f32_16x16x32_bf16 v[14:17], v[134:137], v[240:243], v[14:17]
	v_mfma_f32_16x16x32_bf16 v[10:13], v[152:155], v[240:243], v[10:13]
	v_mfma_f32_16x16x32_bf16 v[54:57], v[156:159], v[176:179], v[54:57]
	v_mfma_f32_16x16x32_bf16 v[50:53], v[168:171], v[176:179], v[50:53]
	v_mfma_f32_16x16x32_bf16 v[38:41], v[156:159], v[206:209], v[38:41]
	v_mfma_f32_16x16x32_bf16 v[34:37], v[168:171], v[206:209], v[34:37]
	v_mfma_f32_16x16x32_bf16 v[22:25], v[156:159], v[214:217], v[22:25]
	v_mfma_f32_16x16x32_bf16 v[18:21], v[168:171], v[214:217], v[18:21]
	s_add_i32 s9, s9, 2
	v_mfma_f32_16x16x32_bf16 v[6:9], v[156:159], v[236:239], v[6:9]
	s_add_u32 s38, s38, 0x100
	s_addc_u32 s39, s39, 0
	v_mfma_f32_16x16x32_bf16 v[2:5], v[168:171], v[236:239], v[2:5]
	s_add_u32 s7, s7, 0x100
	s_addc_u32 s8, s8, 0
	v_mfma_f32_16x16x32_bf16 v[54:57], v[160:163], v[180:183], v[54:57]
	s_cmpk_gt_u32 s9, 0x7d
	v_mfma_f32_16x16x32_bf16 v[50:53], v[172:175], v[180:183], v[50:53]
	v_mfma_f32_16x16x32_bf16 v[38:41], v[160:163], v[210:213], v[38:41]
	v_mfma_f32_16x16x32_bf16 v[34:37], v[172:175], v[210:213], v[34:37]
	v_mfma_f32_16x16x32_bf16 v[22:25], v[160:163], v[218:221], v[22:25]
	v_mfma_f32_16x16x32_bf16 v[18:21], v[172:175], v[218:221], v[18:21]
	v_mfma_f32_16x16x32_bf16 v[6:9], v[160:163], v[240:243], v[6:9]
	v_mfma_f32_16x16x32_bf16 v[2:5], v[172:175], v[240:243], v[2:5]
	s_barrier
.LBB0_1071:
	ds_read_b128 v[130:133], v186
	ds_read_b128 v[134:137], v186 offset:1024
	ds_read_b128 v[138:141], v186 offset:2048
	ds_read_b128 v[152:155], v186 offset:3072
	ds_read_b128 v[156:159], v187
	ds_read_b128 v[160:163], v187 offset:1024
	ds_read_b128 v[168:171], v187 offset:2048
	ds_read_b128 v[172:175], v187 offset:3072
	ds_read_b128 v[176:179], v166
	ds_read_b128 v[180:183], v166 offset:1024
	ds_read_b128 v[206:209], v166 offset:2048
	ds_read_b128 v[210:213], v166 offset:3072
	ds_read_b128 v[214:217], v166 offset:4096
	ds_read_b128 v[218:221], v166 offset:5120
	ds_read_b128 v[236:239], v166 offset:6144
	ds_read_b128 v[240:243], v166 offset:7168
	s_add_u32 s10, s38, 0xffe00080
	s_addc_u32 s11, s39, -1
	s_add_i32 s12, 0, 0x10000
	s_cmpk_eq_i32 s9, 0x7c
	s_cselect_b32 vcc_hi, s97, s11
	s_cselect_b32 vcc_lo, s4, s10
	s_cselect_b32 s47, s5, s8
	s_cselect_b32 s46, s6, s7
	s_add_i32 s13, 0, 0x14000
	s_add_i32 m0, s74, 0xc000
	s_nop 0
	global_load_lds_dwordx4 v148, s[38:39]
	s_add_i32 m0, s74, 0xe000
	s_nop 0
	global_load_lds_dwordx4 v150, s[38:39]
	s_waitcnt vmcnt(8)
	s_waitcnt lgkmcnt(0)
	s_barrier
	v_mfma_f32_16x16x32_bf16 v[126:129], v[130:133], v[176:179], v[126:129]
	v_mfma_f32_16x16x32_bf16 v[122:125], v[138:141], v[176:179], v[122:125]
	v_mfma_f32_16x16x32_bf16 v[110:113], v[130:133], v[206:209], v[110:113]
	v_mfma_f32_16x16x32_bf16 v[106:109], v[138:141], v[206:209], v[106:109]
	v_mfma_f32_16x16x32_bf16 v[94:97], v[130:133], v[214:217], v[94:97]
	v_mfma_f32_16x16x32_bf16 v[90:93], v[138:141], v[214:217], v[90:93]
	v_mfma_f32_16x16x32_bf16 v[78:81], v[130:133], v[236:239], v[78:81]
	v_mfma_f32_16x16x32_bf16 v[74:77], v[138:141], v[236:239], v[74:77]
	v_mfma_f32_16x16x32_bf16 v[126:129], v[134:137], v[180:183], v[126:129]
	v_mfma_f32_16x16x32_bf16 v[122:125], v[152:155], v[180:183], v[122:125]
	v_mfma_f32_16x16x32_bf16 v[110:113], v[134:137], v[210:213], v[110:113]
	v_mfma_f32_16x16x32_bf16 v[106:109], v[152:155], v[210:213], v[106:109]
	v_mfma_f32_16x16x32_bf16 v[94:97], v[134:137], v[218:221], v[94:97]
	v_mfma_f32_16x16x32_bf16 v[90:93], v[152:155], v[218:221], v[90:93]
	v_mfma_f32_16x16x32_bf16 v[78:81], v[134:137], v[240:243], v[78:81]
	v_mfma_f32_16x16x32_bf16 v[74:77], v[152:155], v[240:243], v[74:77]
	v_mfma_f32_16x16x32_bf16 v[118:121], v[156:159], v[176:179], v[118:121]
	v_mfma_f32_16x16x32_bf16 v[114:117], v[168:171], v[176:179], v[114:117]
	v_mfma_f32_16x16x32_bf16 v[102:105], v[156:159], v[206:209], v[102:105]
	v_mfma_f32_16x16x32_bf16 v[98:101], v[168:171], v[206:209], v[98:101]
	v_mfma_f32_16x16x32_bf16 v[86:89], v[156:159], v[214:217], v[86:89]
	v_mfma_f32_16x16x32_bf16 v[82:85], v[168:171], v[214:217], v[82:85]
	v_mfma_f32_16x16x32_bf16 v[70:73], v[156:159], v[236:239], v[70:73]
	v_mfma_f32_16x16x32_bf16 v[66:69], v[168:171], v[236:239], v[66:69]
	v_mfma_f32_16x16x32_bf16 v[118:121], v[160:163], v[180:183], v[118:121]
	v_mfma_f32_16x16x32_bf16 v[114:117], v[172:175], v[180:183], v[114:117]
	v_mfma_f32_16x16x32_bf16 v[102:105], v[160:163], v[210:213], v[102:105]
	v_mfma_f32_16x16x32_bf16 v[98:101], v[172:175], v[210:213], v[98:101]
	v_mfma_f32_16x16x32_bf16 v[86:89], v[160:163], v[218:221], v[86:89]
	v_mfma_f32_16x16x32_bf16 v[82:85], v[172:175], v[218:221], v[82:85]
	v_mfma_f32_16x16x32_bf16 v[70:73], v[160:163], v[240:243], v[70:73]
	v_mfma_f32_16x16x32_bf16 v[66:69], v[172:175], v[240:243], v[66:69]
	s_barrier
; #define PG8_STAGE(bufoff, gbase, voff) do { _Pragma("unroll") for (int _i = 0; _i < 2; ++_i) \
;         __builtin_amdgcn_global_load_lds((const unsigned*)((const char*)(gbase) + (voff)[_i]), (PG8_LAS unsigned*)(lds + (bufoff) + ldsw + _i * 8192), 16, 0, 0); } while (0)
; #define PG8_LDA(dst, b, h) do { _Pragma("unroll") for (int m = 0; m < 4; ++m) _Pragma("unroll") for (int k = 0; k < 2; ++k) dst[m][k] = *(const PG8_LAS bf16x8*)(lds + PG8_SA(b, h) + aoff + m * 2048 + k * 1024); } while (0)
; #define PG8_LDB(dst, b, h) do { _Pragma("unroll") for (int n = 0; n < 2; ++n) _Pragma("unroll") for (int k = 0; k < 2; ++k) dst[n][k] = *(const PG8_LAS bf16x8*)(lds + PG8_SB(b, h) + boff + n * 2048 + k * 1024); } while (0)
; #define PG8_MMA(ai, bj, At, Bt) do { __builtin_amdgcn_s_setprio(1); _Pragma("unroll") for (int m = 0; m < 4; ++m) _Pragma("unroll") for (int n = 0; n < 2; ++n) _Pragma("unroll") for (int k = 0; k < 2; ++k) \
;         acc[ai][bj][m][n] = __builtin_amdgcn_mfma_f32_16x16x32_bf16(Bt[n][k], At[m][k], acc[ai][bj][m][n], 0, 0, 0); __builtin_amdgcn_s_setprio(0); } while (0)
; #define PG8_WAIT_V(n) asm volatile("s_waitcnt vmcnt(" #n ")" ::: "memory")
; #define PG8_WAIT_L(n) asm volatile("s_waitcnt lgkmcnt(" #n ")" ::: "memory")
; #define PG8_BAR __builtin_amdgcn_s_barrier()
; #define PG8_SCHED __builtin_amdgcn_sched_barrier(0)
; template <class Epi, class Sched, bool ALIGN_EPI = false, bool SP2 = false>
; __device__ __forceinline__ void gemm_phase(PG8_LAS unsigned char* lds, const Gemm g, const Sched& S, const Epi& E) {
;     ...
;             PG8_LDA(At, 0, 1); PG8_STAGE(PG8_SB(0, 0), b2, voffB); PG8_STAGE(PG8_SB(0, 1), b2 + hstepB, voffB); PG8_STAGE(PG8_SA(0, 0), a2, voffA);
;             PG8_WAIT_V(8); PG8_WAIT_L(0); PG8_BAR; PG8_MMA(1, 0, At, B0); PG8_MMA(1, 1, At, B1); PG8_BAR; PG8_SCHED;
;             PG8_LDB(B0, 1, 0); PG8_LDB(B1, 1, 1); PG8_SCHED; PG8_LDA(At, 1, 0); PG8_STAGE(PG8_SA(0, 1), a2 + hstep, voffA);
	ds_read_b128 v[176:179], v166 offset:16384
	ds_read_b128 v[180:183], v166 offset:17408
	ds_read_b128 v[206:209], v166 offset:18432
	ds_read_b128 v[210:213], v166 offset:19456
	ds_read_b128 v[214:217], v166 offset:20480
	ds_read_b128 v[218:221], v166 offset:21504
	ds_read_b128 v[236:239], v166 offset:22528
	ds_read_b128 v[240:243], v166 offset:23552
	s_add_i32 s10, s12, s67
	s_mov_b32 m0, s10
	s_nop 0
	global_load_lds_dwordx4 v146, s[46:47]
	s_add_i32 m0, s10, 0x2000
	s_add_u32 s10, s46, 0x80000
	s_addc_u32 s11, s47, 0
	s_add_i32 s12, s13, s67
	global_load_lds_dwordx4 v142, s[46:47]
	s_mov_b32 m0, s12
	s_nop 0
	global_load_lds_dwordx4 v146, s[10:11]
	s_add_i32 m0, s12, 0x2000
	s_nop 0
	global_load_lds_dwordx4 v142, s[10:11]
	s_mov_b32 m0, s74
	s_nop 0
	global_load_lds_dwordx4 v190, vcc
	s_mov_b32 m0, s75
	s_nop 0
	global_load_lds_dwordx4 v144, vcc
	s_waitcnt vmcnt(8)
	s_waitcnt lgkmcnt(0)
	s_barrier
	v_mfma_f32_16x16x32_bf16 v[62:65], v[130:133], v[176:179], v[62:65]
	v_mfma_f32_16x16x32_bf16 v[58:61], v[138:141], v[176:179], v[58:61]
	v_mfma_f32_16x16x32_bf16 v[46:49], v[130:133], v[206:209], v[46:49]
	v_mfma_f32_16x16x32_bf16 v[42:45], v[138:141], v[206:209], v[42:45]
	v_mfma_f32_16x16x32_bf16 v[30:33], v[130:133], v[214:217], v[30:33]
	v_mfma_f32_16x16x32_bf16 v[26:29], v[138:141], v[214:217], v[26:29]
	v_mfma_f32_16x16x32_bf16 v[14:17], v[130:133], v[236:239], v[14:17]
	v_mfma_f32_16x16x32_bf16 v[10:13], v[138:141], v[236:239], v[10:13]
	v_mfma_f32_16x16x32_bf16 v[62:65], v[134:137], v[180:183], v[62:65]
	v_mfma_f32_16x16x32_bf16 v[58:61], v[152:155], v[180:183], v[58:61]
	v_mfma_f32_16x16x32_bf16 v[46:49], v[134:137], v[210:213], v[46:49]
	v_mfma_f32_16x16x32_bf16 v[42:45], v[152:155], v[210:213], v[42:45]
	v_mfma_f32_16x16x32_bf16 v[30:33], v[134:137], v[218:221], v[30:33]
	v_mfma_f32_16x16x32_bf16 v[26:29], v[152:155], v[218:221], v[26:29]
	v_mfma_f32_16x16x32_bf16 v[14:17], v[134:137], v[240:243], v[14:17]
	v_mfma_f32_16x16x32_bf16 v[10:13], v[152:155], v[240:243], v[10:13]
	v_mfma_f32_16x16x32_bf16 v[54:57], v[156:159], v[176:179], v[54:57]
	v_mfma_f32_16x16x32_bf16 v[50:53], v[168:171], v[176:179], v[50:53]
	v_mfma_f32_16x16x32_bf16 v[38:41], v[156:159], v[206:209], v[38:41]
	v_mfma_f32_16x16x32_bf16 v[34:37], v[168:171], v[206:209], v[34:37]
	v_mfma_f32_16x16x32_bf16 v[22:25], v[156:159], v[214:217], v[22:25]
	v_mfma_f32_16x16x32_bf16 v[18:21], v[168:171], v[214:217], v[18:21]
	v_mfma_f32_16x16x32_bf16 v[6:9], v[156:159], v[236:239], v[6:9]
	v_mfma_f32_16x16x32_bf16 v[2:5], v[168:171], v[236:239], v[2:5]
	v_mfma_f32_16x16x32_bf16 v[54:57], v[160:163], v[180:183], v[54:57]
	v_mfma_f32_16x16x32_bf16 v[50:53], v[172:175], v[180:183], v[50:53]
	v_mfma_f32_16x16x32_bf16 v[38:41], v[160:163], v[210:213], v[38:41]
	v_mfma_f32_16x16x32_bf16 v[34:37], v[172:175], v[210:213], v[34:37]
	v_mfma_f32_16x16x32_bf16 v[22:25], v[160:163], v[218:221], v[22:25]
	v_mfma_f32_16x16x32_bf16 v[18:21], v[172:175], v[218:221], v[18:21]
	v_mfma_f32_16x16x32_bf16 v[6:9], v[160:163], v[240:243], v[6:9]
	v_mfma_f32_16x16x32_bf16 v[2:5], v[172:175], v[240:243], v[2:5]
	s_barrier
	ds_read_b128 v[130:133], v198
	ds_read_b128 v[134:137], v198 offset:1024
	ds_read_b128 v[138:141], v198 offset:2048
	ds_read_b128 v[152:155], v198 offset:3072
	ds_read_b128 v[156:159], v199
	ds_read_b128 v[160:163], v199 offset:1024
	ds_read_b128 v[168:171], v199 offset:2048
	ds_read_b128 v[172:175], v199 offset:3072
	ds_read_b128 v[176:179], v166 offset:32768
	ds_read_b128 v[180:183], v166 offset:33792
	ds_read_b128 v[206:209], v166 offset:34816
	ds_read_b128 v[210:213], v166 offset:35840
	ds_read_b128 v[214:217], v166 offset:36864
	ds_read_b128 v[218:221], v166 offset:37888
	ds_read_b128 v[236:239], v166 offset:38912
	ds_read_b128 v[240:243], v166 offset:39936
	s_add_i32 s12, 0, 0x18000
	s_add_i32 s13, 0, 0x1c000
	s_add_u32 s10, vcc_lo, 0x200000
	s_addc_u32 s11, vcc_hi, 0
	s_mov_b32 m0, s86
	s_nop 0
	global_load_lds_dwordx4 v190, s[10:11]
	s_mov_b32 m0, s87
	s_nop 0
	global_load_lds_dwordx4 v144, s[10:11]
	s_waitcnt vmcnt(8)
	s_waitcnt lgkmcnt(0)
	s_barrier
; #define PG8_STAGE(bufoff, gbase, voff) do { _Pragma("unroll") for (int _i = 0; _i < 2; ++_i) \
;         __builtin_amdgcn_global_load_lds((const unsigned*)((const char*)(gbase) + (voff)[_i]), (PG8_LAS unsigned*)(lds + (bufoff) + ldsw + _i * 8192), 16, 0, 0); } while (0)
; #define PG8_LDA(dst, b, h) do { _Pragma("unroll") for (int m = 0; m < 4; ++m) _Pragma("unroll") for (int k = 0; k < 2; ++k) dst[m][k] = *(const PG8_LAS bf16x8*)(lds + PG8_SA(b, h) + aoff + m * 2048 + k * 1024); } while (0)
; #define PG8_MMA(ai, bj, At, Bt) do { __builtin_amdgcn_s_setprio(1); _Pragma("unroll") for (int m = 0; m < 4; ++m) _Pragma("unroll") for (int n = 0; n < 2; ++n) _Pragma("unroll") for (int k = 0; k < 2; ++k) \
;         acc[ai][bj][m][n] = __builtin_amdgcn_mfma_f32_16x16x32_bf16(Bt[n][k], At[m][k], acc[ai][bj][m][n], 0, 0, 0); __builtin_amdgcn_s_setprio(0); } while (0)
; #define PG8_WAIT_V(n) asm volatile("s_waitcnt vmcnt(" #n ")" ::: "memory")
; #define PG8_WAIT_L(n) asm volatile("s_waitcnt lgkmcnt(" #n ")" ::: "memory")
; #define PG8_BAR __builtin_amdgcn_s_barrier()
; #define PG8_SCHED __builtin_amdgcn_sched_barrier(0)
; template <class Epi, class Sched, bool ALIGN_EPI = false, bool SP2 = false>
; __device__ __forceinline__ void gemm_phase(PG8_LAS unsigned char* lds, const Gemm g, const Sched& S, const Epi& E) {
;     ...
;             PG8_WAIT_V(8); PG8_WAIT_L(0); PG8_BAR; PG8_MMA(0, 0, At, B0); PG8_MMA(0, 1, At, B1); PG8_BAR; PG8_SCHED;
;             PG8_LDA(At, 1, 1); PG8_STAGE(PG8_SB(1, 0), b3, voffB); PG8_STAGE(PG8_SB(1, 1), b3 + hstepB, voffB); PG8_STAGE(PG8_SA(1, 0), a3, voffA);
;             PG8_WAIT_V(8); PG8_WAIT_L(0); PG8_BAR; PG8_MMA(1, 0, At, B0); PG8_MMA(1, 1, At, B1); PG8_BAR; PG8_SCHED;
	v_mfma_f32_16x16x32_bf16 v[126:129], v[130:133], v[176:179], v[126:129]
	v_mfma_f32_16x16x32_bf16 v[122:125], v[138:141], v[176:179], v[122:125]
	v_mfma_f32_16x16x32_bf16 v[110:113], v[130:133], v[206:209], v[110:113]
	v_mfma_f32_16x16x32_bf16 v[106:109], v[138:141], v[206:209], v[106:109]
	v_mfma_f32_16x16x32_bf16 v[94:97], v[130:133], v[214:217], v[94:97]
	v_mfma_f32_16x16x32_bf16 v[90:93], v[138:141], v[214:217], v[90:93]
	v_mfma_f32_16x16x32_bf16 v[78:81], v[130:133], v[236:239], v[78:81]
	v_mfma_f32_16x16x32_bf16 v[74:77], v[138:141], v[236:239], v[74:77]
	v_mfma_f32_16x16x32_bf16 v[126:129], v[134:137], v[180:183], v[126:129]
	v_mfma_f32_16x16x32_bf16 v[122:125], v[152:155], v[180:183], v[122:125]
	v_mfma_f32_16x16x32_bf16 v[110:113], v[134:137], v[210:213], v[110:113]
	v_mfma_f32_16x16x32_bf16 v[106:109], v[152:155], v[210:213], v[106:109]
	v_mfma_f32_16x16x32_bf16 v[94:97], v[134:137], v[218:221], v[94:97]
	v_mfma_f32_16x16x32_bf16 v[90:93], v[152:155], v[218:221], v[90:93]
	v_mfma_f32_16x16x32_bf16 v[78:81], v[134:137], v[240:243], v[78:81]
	v_mfma_f32_16x16x32_bf16 v[74:77], v[152:155], v[240:243], v[74:77]
	v_mfma_f32_16x16x32_bf16 v[118:121], v[156:159], v[176:179], v[118:121]
	v_mfma_f32_16x16x32_bf16 v[114:117], v[168:171], v[176:179], v[114:117]
	v_mfma_f32_16x16x32_bf16 v[102:105], v[156:159], v[206:209], v[102:105]
	v_mfma_f32_16x16x32_bf16 v[98:101], v[168:171], v[206:209], v[98:101]
	v_mfma_f32_16x16x32_bf16 v[86:89], v[156:159], v[214:217], v[86:89]
	v_mfma_f32_16x16x32_bf16 v[82:85], v[168:171], v[214:217], v[82:85]
	v_mfma_f32_16x16x32_bf16 v[70:73], v[156:159], v[236:239], v[70:73]
	v_mfma_f32_16x16x32_bf16 v[66:69], v[168:171], v[236:239], v[66:69]
	v_mfma_f32_16x16x32_bf16 v[118:121], v[160:163], v[180:183], v[118:121]
	v_mfma_f32_16x16x32_bf16 v[114:117], v[172:175], v[180:183], v[114:117]
	v_mfma_f32_16x16x32_bf16 v[102:105], v[160:163], v[210:213], v[102:105]
	v_mfma_f32_16x16x32_bf16 v[98:101], v[172:175], v[210:213], v[98:101]
	v_mfma_f32_16x16x32_bf16 v[86:89], v[160:163], v[218:221], v[86:89]
	v_mfma_f32_16x16x32_bf16 v[82:85], v[172:175], v[218:221], v[82:85]
	v_mfma_f32_16x16x32_bf16 v[70:73], v[160:163], v[240:243], v[70:73]
	v_mfma_f32_16x16x32_bf16 v[66:69], v[172:175], v[240:243], v[66:69]
	s_barrier
	ds_read_b128 v[176:179], v166 offset:49152
	ds_read_b128 v[180:183], v166 offset:50176
	ds_read_b128 v[206:209], v166 offset:51200
	ds_read_b128 v[210:213], v166 offset:52224
	ds_read_b128 v[214:217], v166 offset:53248
	ds_read_b128 v[218:221], v166 offset:54272
	ds_read_b128 v[236:239], v166 offset:55296
	ds_read_b128 v[240:243], v166 offset:56320
	s_add_i32 s10, s12, s67
	s_mov_b32 m0, s10
	s_add_u32 s100, s46, s60
	s_addc_u32 s101, s47, s61
	global_load_lds_dwordx4 v146, s[100:101]
	s_add_i32 m0, s10, 0x2000
	s_add_u32 s10, s46, 0x80080
	s_addc_u32 s11, s47, 0
	s_add_i32 s12, s13, s67
	global_load_lds_dwordx4 v142, s[100:101]
	s_mov_b32 m0, s12
	s_nop 0
	global_load_lds_dwordx4 v146, s[10:11]
	s_add_i32 m0, s12, 0x2000
	s_nop 0
	global_load_lds_dwordx4 v142, s[10:11]
	s_mov_b32 m0, s82
	s_add_u32 s100, vcc_lo, s60
	s_addc_u32 s101, vcc_hi, s61
	global_load_lds_dwordx4 v190, s[100:101]
	s_mov_b32 m0, s42
	s_nop 0
	global_load_lds_dwordx4 v144, s[100:101]
	s_waitcnt vmcnt(8)
	s_waitcnt lgkmcnt(0)
	s_barrier
	v_mfma_f32_16x16x32_bf16 v[62:65], v[130:133], v[176:179], v[62:65]
	v_mfma_f32_16x16x32_bf16 v[58:61], v[138:141], v[176:179], v[58:61]
	v_mfma_f32_16x16x32_bf16 v[46:49], v[130:133], v[206:209], v[46:49]
	v_mfma_f32_16x16x32_bf16 v[42:45], v[138:141], v[206:209], v[42:45]
	v_mfma_f32_16x16x32_bf16 v[30:33], v[130:133], v[214:217], v[30:33]
	v_mfma_f32_16x16x32_bf16 v[26:29], v[138:141], v[214:217], v[26:29]
	v_mfma_f32_16x16x32_bf16 v[14:17], v[130:133], v[236:239], v[14:17]
	v_mfma_f32_16x16x32_bf16 v[10:13], v[138:141], v[236:239], v[10:13]
	v_mfma_f32_16x16x32_bf16 v[62:65], v[134:137], v[180:183], v[62:65]
	v_mfma_f32_16x16x32_bf16 v[58:61], v[152:155], v[180:183], v[58:61]
	v_mfma_f32_16x16x32_bf16 v[46:49], v[134:137], v[210:213], v[46:49]
	v_mfma_f32_16x16x32_bf16 v[42:45], v[152:155], v[210:213], v[42:45]
	v_mfma_f32_16x16x32_bf16 v[30:33], v[134:137], v[218:221], v[30:33]
	v_mfma_f32_16x16x32_bf16 v[26:29], v[152:155], v[218:221], v[26:29]
	v_mfma_f32_16x16x32_bf16 v[14:17], v[134:137], v[240:243], v[14:17]
	v_mfma_f32_16x16x32_bf16 v[10:13], v[152:155], v[240:243], v[10:13]
	v_mfma_f32_16x16x32_bf16 v[54:57], v[156:159], v[176:179], v[54:57]
	v_mfma_f32_16x16x32_bf16 v[50:53], v[168:171], v[176:179], v[50:53]
	v_mfma_f32_16x16x32_bf16 v[38:41], v[156:159], v[206:209], v[38:41]
	v_mfma_f32_16x16x32_bf16 v[34:37], v[168:171], v[206:209], v[34:37]
	v_mfma_f32_16x16x32_bf16 v[22:25], v[156:159], v[214:217], v[22:25]
	v_mfma_f32_16x16x32_bf16 v[18:21], v[168:171], v[214:217], v[18:21]
	s_add_i32 s9, s9, 2
	v_mfma_f32_16x16x32_bf16 v[6:9], v[156:159], v[236:239], v[6:9]
	s_add_u32 s38, s38, 0x100
	s_addc_u32 s39, s39, 0
	v_mfma_f32_16x16x32_bf16 v[2:5], v[168:171], v[236:239], v[2:5]
	s_add_u32 s7, s7, 0x100
	s_addc_u32 s8, s8, 0
	v_mfma_f32_16x16x32_bf16 v[54:57], v[160:163], v[180:183], v[54:57]
	s_cmpk_gt_u32 s9, 0x7d
	v_mfma_f32_16x16x32_bf16 v[50:53], v[172:175], v[180:183], v[50:53]
	v_mfma_f32_16x16x32_bf16 v[38:41], v[160:163], v[210:213], v[38:41]
	v_mfma_f32_16x16x32_bf16 v[34:37], v[172:175], v[210:213], v[34:37]
	v_mfma_f32_16x16x32_bf16 v[22:25], v[160:163], v[218:221], v[22:25]
	v_mfma_f32_16x16x32_bf16 v[18:21], v[172:175], v[218:221], v[18:21]
	v_mfma_f32_16x16x32_bf16 v[6:9], v[160:163], v[240:243], v[6:9]
	v_mfma_f32_16x16x32_bf16 v[2:5], v[172:175], v[240:243], v[2:5]
	s_barrier
	s_cbranch_scc0 .LBB0_1071
	s_and_b64 vcc, exec, s[72:73]
	s_cbranch_vccz .LBB0_1074
	s_barrier

; #define PG8_STAGE(bufoff, gbase, voff) do { _Pragma("unroll") for (int _i = 0; _i < 2; ++_i) \
;         __builtin_amdgcn_global_load_lds((const unsigned*)((const char*)(gbase) + (voff)[_i]), (PG8_LAS unsigned*)(lds + (bufoff) + ldsw + _i * 8192), 16, 0, 0); } while (0)
; #define PG8_LDA(dst, b, h) do { _Pragma("unroll") for (int m = 0; m < 4; ++m) _Pragma("unroll") for (int k = 0; k < 2; ++k) dst[m][k] = *(const PG8_LAS bf16x8*)(lds + PG8_SA(b, h) + aoff + m * 2048 + k * 1024); } while (0)
; #define PG8_LDB(dst, b, h) do { _Pragma("unroll") for (int n = 0; n < 2; ++n) _Pragma("unroll") for (int k = 0; k < 2; ++k) dst[n][k] = *(const PG8_LAS bf16x8*)(lds + PG8_SB(b, h) + boff + n * 2048 + k * 1024); } while (0)
; #define PG8_WAIT_V(n) asm volatile("s_waitcnt vmcnt(" #n ")" ::: "memory")
; #define PG8_WAIT_L(n) asm volatile("s_waitcnt lgkmcnt(" #n ")" ::: "memory")
; #define PG8_BAR __builtin_amdgcn_s_barrier()
; #define PG8_SCHED __builtin_amdgcn_sched_barrier(0)
; template <class Epi, class Sched, bool ALIGN_EPI = false, bool SP2 = false>
; __device__ __forceinline__ void gemm_phase(PG8_LAS unsigned char* lds, const Gemm g, const Sched& S, const Epi& E) {
;     ...
;         const bool has_next = S.next(ui + 1, nxt);
;         const char* nA = has_next ? (const char*)g.A + (size_t)nxt.pm * tstep : cA; const char* nB = has_next ? (const char*)g.Bt + (size_t)nxt.pn * tstep : cB;
;         for (int t = 0; t < nt; t += 2) {
;             const bool last = (t == nt - 2);
;             const char* a1 = cA + (size_t)(t + 1) * kstep;
;             const char* a2 = last ? nA : cA + (size_t)(t + 2) * kstep; const char* b2 = last ? nB : cB + (size_t)(t + 2) * kstep;
;             const char* a3 = a2 + kstep; const char* b3 = b2 + kstep;
;             if (last && has_next) S.a_ready(nxt);
;             if constexpr (SP2) {
;             PG8_LDB(B0, 0, 0); PG8_LDB(B1, 0, 1); PG8_SCHED; PG8_LDA(At, 0, 0); PG8_STAGE(PG8_SA(1, 1), a1 + hstep, voffA);
;             PG8_WAIT_V(8); PG8_WAIT_L(0); PG8_BAR; PG8_MMA(0, 0, At, B0); PG8_MMA(0, 1, At, B1); PG8_BAR; PG8_SCHED;
;             PG8_LDA(At, 0, 1); PG8_STAGE(PG8_SB(0, 0), b2, voffB); PG8_STAGE(PG8_SB(0, 1), b2 + hstepB, voffB); PG8_STAGE(PG8_SA(0, 0), a2, voffA);
;             PG8_WAIT_V(8); PG8_WAIT_L(0); PG8_BAR; PG8_MMA(1, 0, At, B0); PG8_MMA(1, 1, At, B1); PG8_BAR; PG8_SCHED;
.LBB0_1232:
	s_add_u32 s36, s80, 0x100
	s_addc_u32 s37, s81, 0
	s_ashr_i32 s73, s72, 31
	s_lshl_b64 s[4:5], s[72:73], 20
	s_add_u32 s78, s0, s4
	s_addc_u32 s79, s1, s5
	s_and_b64 s[4:5], s[46:47], exec
	s_cselect_b32 s4, s79, s69
	s_cselect_b32 s5, s78, s68
	s_ashr_i32 s71, s70, 31
	s_lshl_b64 s[6:7], s[70:71], 20
	s_add_u32 s76, s34, s6
	s_addc_u32 s77, s35, s7
	s_and_b64 s[6:7], s[46:47], exec
	s_cselect_b32 s6, s77, s81
	s_cselect_b32 s7, s76, s80
	s_add_u32 s8, s68, 0x80080
	s_addc_u32 s9, s69, 0
	v_lshl_add_u64 v[140:141], s[8:9], 0, v[136:137]
	v_lshl_add_u64 v[142:143], s[8:9], 0, v[138:139]
	s_mov_b32 s8, -2
	s_mov_b64 s[80:81], 0
	v_add_u32_e32 v186, 0x10000, v145
	v_add_u32_e32 v187, 0x14000, v145
	v_add_u32_e32 v198, 0x18000, v145
	v_add_u32_e32 v199, 0x1c000, v145
	s_add_u32 s9, s68, s80
	s_addc_u32 s10, s69, s81
	s_add_u32 s9, s9, 0x100
	s_addc_u32 s10, s10, 0
	s_add_u32 s100, s9, 0x7ff80
	s_addc_u32 s101, s10, 0
	s_add_u32 s11, s36, s80
	s_addc_u32 s12, s37, s81
	s_add_i32 s13, 0, 0x10000
	s_cmpk_eq_i32 s80, 0xf00
	s_cselect_b32 s93, s4, s10
	s_cselect_b32 s92, s5, s9
	s_cselect_b32 s85, s6, s12
	s_cselect_b32 s84, s7, s11
	s_add_i32 s9, 0, 0x14000
	ds_read_b128 v[152:155], v186
	ds_read_b128 v[156:159], v186 offset:1024
	ds_read_b128 v[160:163], v186 offset:2048
	ds_read_b128 v[164:167], v186 offset:3072
	ds_read_b128 v[168:171], v187
	ds_read_b128 v[172:175], v187 offset:1024
	ds_read_b128 v[176:179], v187 offset:2048
	ds_read_b128 v[180:183], v187 offset:3072
	s_add_i32 m0, s51, 0xc000
	ds_read_b128 v[206:209], v151
	ds_read_b128 v[210:213], v151 offset:1024
	ds_read_b128 v[214:217], v151 offset:2048
	ds_read_b128 v[218:221], v151 offset:3072
	ds_read_b128 v[236:239], v151 offset:4096
	ds_read_b128 v[240:243], v151 offset:5120
	ds_read_b128 v[244:247], v151 offset:6144
	ds_read_b128 v[194:197], v151 offset:7168
	global_load_lds_dwordx4 v136, s[100:101]
	s_add_i32 m0, s51, 0xe000
	s_nop 0
	global_load_lds_dwordx4 v138, s[100:101]
	s_waitcnt vmcnt(8)
	s_waitcnt lgkmcnt(0)
	s_barrier
	v_mfma_f32_16x16x32_bf16 v[126:129], v[152:155], v[206:209], 0
	v_mfma_f32_16x16x32_bf16 v[122:125], v[160:163], v[206:209], 0
	v_mfma_f32_16x16x32_bf16 v[118:121], v[152:155], v[214:217], 0
	v_mfma_f32_16x16x32_bf16 v[114:117], v[160:163], v[214:217], 0
	v_mfma_f32_16x16x32_bf16 v[110:113], v[152:155], v[236:239], 0
	v_mfma_f32_16x16x32_bf16 v[106:109], v[160:163], v[236:239], 0
	v_mfma_f32_16x16x32_bf16 v[102:105], v[152:155], v[244:247], 0
	v_mfma_f32_16x16x32_bf16 v[98:101], v[160:163], v[244:247], 0
	v_mfma_f32_16x16x32_bf16 v[126:129], v[156:159], v[210:213], v[126:129]
	v_mfma_f32_16x16x32_bf16 v[122:125], v[164:167], v[210:213], v[122:125]
	v_mfma_f32_16x16x32_bf16 v[118:121], v[156:159], v[218:221], v[118:121]
	v_mfma_f32_16x16x32_bf16 v[114:117], v[164:167], v[218:221], v[114:117]
	v_mfma_f32_16x16x32_bf16 v[110:113], v[156:159], v[240:243], v[110:113]
	v_mfma_f32_16x16x32_bf16 v[106:109], v[164:167], v[240:243], v[106:109]
	v_mfma_f32_16x16x32_bf16 v[102:105], v[156:159], v[194:197], v[102:105]
	v_mfma_f32_16x16x32_bf16 v[98:101], v[164:167], v[194:197], v[98:101]
	v_mfma_f32_16x16x32_bf16 v[94:97], v[168:171], v[206:209], 0
	v_mfma_f32_16x16x32_bf16 v[90:93], v[176:179], v[206:209], 0
	v_mfma_f32_16x16x32_bf16 v[86:89], v[168:171], v[214:217], 0
	v_mfma_f32_16x16x32_bf16 v[82:85], v[176:179], v[214:217], 0
	v_mfma_f32_16x16x32_bf16 v[78:81], v[168:171], v[236:239], 0
	v_mfma_f32_16x16x32_bf16 v[74:77], v[176:179], v[236:239], 0
	v_mfma_f32_16x16x32_bf16 v[70:73], v[168:171], v[244:247], 0
	v_mfma_f32_16x16x32_bf16 v[66:69], v[176:179], v[244:247], 0
	v_mfma_f32_16x16x32_bf16 v[94:97], v[172:175], v[210:213], v[94:97]
	v_mfma_f32_16x16x32_bf16 v[90:93], v[180:183], v[210:213], v[90:93]
	v_mfma_f32_16x16x32_bf16 v[86:89], v[172:175], v[218:221], v[86:89]
	v_mfma_f32_16x16x32_bf16 v[82:85], v[180:183], v[218:221], v[82:85]
	v_mfma_f32_16x16x32_bf16 v[78:81], v[172:175], v[240:243], v[78:81]
	v_mfma_f32_16x16x32_bf16 v[74:77], v[180:183], v[240:243], v[74:77]
	v_mfma_f32_16x16x32_bf16 v[70:73], v[172:175], v[194:197], v[70:73]
	v_mfma_f32_16x16x32_bf16 v[66:69], v[180:183], v[194:197], v[66:69]
	s_barrier
	ds_read_b128 v[194:197], v151 offset:16384
	ds_read_b128 v[206:209], v151 offset:17408
	ds_read_b128 v[210:213], v151 offset:18432
	ds_read_b128 v[214:217], v151 offset:19456
	ds_read_b128 v[218:221], v151 offset:20480
	ds_read_b128 v[236:239], v151 offset:21504
	ds_read_b128 v[240:243], v151 offset:22528
	ds_read_b128 v[244:247], v151 offset:23552
	s_add_i32 s10, s13, s42
	s_mov_b32 m0, s10
	s_nop 0
	global_load_lds_dwordx4 v130, s[84:85]
	s_add_i32 m0, s10, 0x2000
	s_add_u32 s10, s84, 0x20000
	s_addc_u32 s11, s85, 0
	s_add_i32 s9, s9, s42
	global_load_lds_dwordx4 v134, s[84:85]
	s_mov_b32 m0, s9
	s_nop 0
	global_load_lds_dwordx4 v130, s[10:11]
	s_add_i32 m0, s9, 0x2000
	s_nop 0
	global_load_lds_dwordx4 v134, s[10:11]
	s_mov_b32 m0, s51
	s_nop 0
	global_load_lds_dwordx4 v190, s[92:93]
	s_mov_b32 m0, s67
	s_nop 0
	global_load_lds_dwordx4 v132, s[92:93]
	s_waitcnt vmcnt(8)
	s_waitcnt lgkmcnt(0)
	s_barrier
; #define PG8_STAGE(bufoff, gbase, voff) do { _Pragma("unroll") for (int _i = 0; _i < 2; ++_i) \
;         __builtin_amdgcn_global_load_lds((const unsigned*)((const char*)(gbase) + (voff)[_i]), (PG8_LAS unsigned*)(lds + (bufoff) + ldsw + _i * 8192), 16, 0, 0); } while (0)
; #define PG8_LDA(dst, b, h) do { _Pragma("unroll") for (int m = 0; m < 4; ++m) _Pragma("unroll") for (int k = 0; k < 2; ++k) dst[m][k] = *(const PG8_LAS bf16x8*)(lds + PG8_SA(b, h) + aoff + m * 2048 + k * 1024); } while (0)
; #define PG8_LDB(dst, b, h) do { _Pragma("unroll") for (int n = 0; n < 2; ++n) _Pragma("unroll") for (int k = 0; k < 2; ++k) dst[n][k] = *(const PG8_LAS bf16x8*)(lds + PG8_SB(b, h) + boff + n * 2048 + k * 1024); } while (0)
; #define PG8_MMA(ai, bj, At, Bt) do { __builtin_amdgcn_s_setprio(1); _Pragma("unroll") for (int m = 0; m < 4; ++m) _Pragma("unroll") for (int n = 0; n < 2; ++n) _Pragma("unroll") for (int k = 0; k < 2; ++k) \
;         acc[ai][bj][m][n] = __builtin_amdgcn_mfma_f32_16x16x32_bf16(Bt[n][k], At[m][k], acc[ai][bj][m][n], 0, 0, 0); __builtin_amdgcn_s_setprio(0); } while (0)
; #define PG8_WAIT_V(n) asm volatile("s_waitcnt vmcnt(" #n ")" ::: "memory")
; #define PG8_WAIT_L(n) asm volatile("s_waitcnt lgkmcnt(" #n ")" ::: "memory")
; #define PG8_BAR __builtin_amdgcn_s_barrier()
; #define PG8_SCHED __builtin_amdgcn_sched_barrier(0)
; template <class Epi, class Sched, bool ALIGN_EPI = false, bool SP2 = false>
; __device__ __forceinline__ void gemm_phase(PG8_LAS unsigned char* lds, const Gemm g, const Sched& S, const Epi& E) {
;     ...
;             PG8_WAIT_V(8); PG8_WAIT_L(0); PG8_BAR; PG8_MMA(1, 0, At, B0); PG8_MMA(1, 1, At, B1); PG8_BAR; PG8_SCHED;
;             PG8_LDB(B0, 1, 0); PG8_LDB(B1, 1, 1); PG8_SCHED; PG8_LDA(At, 1, 0); PG8_STAGE(PG8_SA(0, 1), a2 + hstep, voffA);
;             PG8_WAIT_V(8); PG8_WAIT_L(0); PG8_BAR; PG8_MMA(0, 0, At, B0); PG8_MMA(0, 1, At, B1); PG8_BAR; PG8_SCHED;
	v_mfma_f32_16x16x32_bf16 v[62:65], v[152:155], v[194:197], 0
	v_mfma_f32_16x16x32_bf16 v[58:61], v[160:163], v[194:197], 0
	v_mfma_f32_16x16x32_bf16 v[54:57], v[152:155], v[210:213], 0
	v_mfma_f32_16x16x32_bf16 v[50:53], v[160:163], v[210:213], 0
	v_mfma_f32_16x16x32_bf16 v[46:49], v[152:155], v[218:221], 0
	v_mfma_f32_16x16x32_bf16 v[42:45], v[160:163], v[218:221], 0
	v_mfma_f32_16x16x32_bf16 v[38:41], v[152:155], v[240:243], 0
	v_mfma_f32_16x16x32_bf16 v[34:37], v[160:163], v[240:243], 0
	v_mfma_f32_16x16x32_bf16 v[62:65], v[156:159], v[206:209], v[62:65]
	v_mfma_f32_16x16x32_bf16 v[58:61], v[164:167], v[206:209], v[58:61]
	v_mfma_f32_16x16x32_bf16 v[54:57], v[156:159], v[214:217], v[54:57]
	v_mfma_f32_16x16x32_bf16 v[50:53], v[164:167], v[214:217], v[50:53]
	v_mfma_f32_16x16x32_bf16 v[46:49], v[156:159], v[236:239], v[46:49]
	v_mfma_f32_16x16x32_bf16 v[42:45], v[164:167], v[236:239], v[42:45]
	v_mfma_f32_16x16x32_bf16 v[38:41], v[156:159], v[244:247], v[38:41]
	v_mfma_f32_16x16x32_bf16 v[34:37], v[164:167], v[244:247], v[34:37]
	v_mfma_f32_16x16x32_bf16 v[30:33], v[168:171], v[194:197], 0
	v_mfma_f32_16x16x32_bf16 v[26:29], v[176:179], v[194:197], 0
	v_mfma_f32_16x16x32_bf16 v[22:25], v[168:171], v[210:213], 0
	v_mfma_f32_16x16x32_bf16 v[18:21], v[176:179], v[210:213], 0
	v_mfma_f32_16x16x32_bf16 v[14:17], v[168:171], v[218:221], 0
	v_mfma_f32_16x16x32_bf16 v[10:13], v[176:179], v[218:221], 0
	v_mfma_f32_16x16x32_bf16 v[6:9], v[168:171], v[240:243], 0
	v_mfma_f32_16x16x32_bf16 v[2:5], v[176:179], v[240:243], 0
	v_mfma_f32_16x16x32_bf16 v[30:33], v[172:175], v[206:209], v[30:33]
	v_mfma_f32_16x16x32_bf16 v[26:29], v[180:183], v[206:209], v[26:29]
	v_mfma_f32_16x16x32_bf16 v[22:25], v[172:175], v[214:217], v[22:25]
	v_mfma_f32_16x16x32_bf16 v[18:21], v[180:183], v[214:217], v[18:21]
	v_mfma_f32_16x16x32_bf16 v[14:17], v[172:175], v[236:239], v[14:17]
	v_mfma_f32_16x16x32_bf16 v[10:13], v[180:183], v[236:239], v[10:13]
	v_mfma_f32_16x16x32_bf16 v[6:9], v[172:175], v[244:247], v[6:9]
	v_mfma_f32_16x16x32_bf16 v[2:5], v[180:183], v[244:247], v[2:5]
	s_barrier
	ds_read_b128 v[152:155], v198
	ds_read_b128 v[156:159], v198 offset:1024
	ds_read_b128 v[160:163], v198 offset:2048
	ds_read_b128 v[164:167], v198 offset:3072
	ds_read_b128 v[168:171], v199
	ds_read_b128 v[172:175], v199 offset:1024
	ds_read_b128 v[176:179], v199 offset:2048
	ds_read_b128 v[180:183], v199 offset:3072
	ds_read_b128 v[194:197], v151 offset:32768
	ds_read_b128 v[206:209], v151 offset:33792
	ds_read_b128 v[210:213], v151 offset:34816
	ds_read_b128 v[214:217], v151 offset:35840
	ds_read_b128 v[218:221], v151 offset:36864
	ds_read_b128 v[236:239], v151 offset:37888
	ds_read_b128 v[240:243], v151 offset:38912
	ds_read_b128 v[244:247], v151 offset:39936
	s_add_i32 s9, 0, 0x18000
	s_add_i32 s12, 0, 0x1c000
	s_add_u32 s10, s92, 0x80000
	s_addc_u32 s11, s93, 0
	s_mov_b32 m0, s74
	s_nop 0
	global_load_lds_dwordx4 v190, s[10:11]
	s_mov_b32 m0, s75
	s_nop 0
	global_load_lds_dwordx4 v132, s[10:11]
	s_waitcnt vmcnt(8)
	s_waitcnt lgkmcnt(0)
	s_barrier
	v_mfma_f32_16x16x32_bf16 v[126:129], v[152:155], v[194:197], v[126:129]
	v_mfma_f32_16x16x32_bf16 v[122:125], v[160:163], v[194:197], v[122:125]
	v_mfma_f32_16x16x32_bf16 v[118:121], v[152:155], v[210:213], v[118:121]
	v_mfma_f32_16x16x32_bf16 v[114:117], v[160:163], v[210:213], v[114:117]
	v_mfma_f32_16x16x32_bf16 v[110:113], v[152:155], v[218:221], v[110:113]
	v_mfma_f32_16x16x32_bf16 v[106:109], v[160:163], v[218:221], v[106:109]
	v_mfma_f32_16x16x32_bf16 v[102:105], v[152:155], v[240:243], v[102:105]
	v_mfma_f32_16x16x32_bf16 v[98:101], v[160:163], v[240:243], v[98:101]
	v_mfma_f32_16x16x32_bf16 v[126:129], v[156:159], v[206:209], v[126:129]
	v_mfma_f32_16x16x32_bf16 v[122:125], v[164:167], v[206:209], v[122:125]
	v_mfma_f32_16x16x32_bf16 v[118:121], v[156:159], v[214:217], v[118:121]
	v_mfma_f32_16x16x32_bf16 v[114:117], v[164:167], v[214:217], v[114:117]
	v_mfma_f32_16x16x32_bf16 v[110:113], v[156:159], v[236:239], v[110:113]
	v_mfma_f32_16x16x32_bf16 v[106:109], v[164:167], v[236:239], v[106:109]
	v_mfma_f32_16x16x32_bf16 v[102:105], v[156:159], v[244:247], v[102:105]
	v_mfma_f32_16x16x32_bf16 v[98:101], v[164:167], v[244:247], v[98:101]
	v_mfma_f32_16x16x32_bf16 v[94:97], v[168:171], v[194:197], v[94:97]
	v_mfma_f32_16x16x32_bf16 v[90:93], v[176:179], v[194:197], v[90:93]
	v_mfma_f32_16x16x32_bf16 v[86:89], v[168:171], v[210:213], v[86:89]
	v_mfma_f32_16x16x32_bf16 v[82:85], v[176:179], v[210:213], v[82:85]
	v_mfma_f32_16x16x32_bf16 v[78:81], v[168:171], v[218:221], v[78:81]
	v_mfma_f32_16x16x32_bf16 v[74:77], v[176:179], v[218:221], v[74:77]
	v_mfma_f32_16x16x32_bf16 v[70:73], v[168:171], v[240:243], v[70:73]
	v_mfma_f32_16x16x32_bf16 v[66:69], v[176:179], v[240:243], v[66:69]
	v_mfma_f32_16x16x32_bf16 v[94:97], v[172:175], v[206:209], v[94:97]
	v_mfma_f32_16x16x32_bf16 v[90:93], v[180:183], v[206:209], v[90:93]
	v_mfma_f32_16x16x32_bf16 v[86:89], v[172:175], v[214:217], v[86:89]
	v_mfma_f32_16x16x32_bf16 v[82:85], v[180:183], v[214:217], v[82:85]
	v_mfma_f32_16x16x32_bf16 v[78:81], v[172:175], v[236:239], v[78:81]
	v_mfma_f32_16x16x32_bf16 v[74:77], v[180:183], v[236:239], v[74:77]
	v_mfma_f32_16x16x32_bf16 v[70:73], v[172:175], v[244:247], v[70:73]
	v_mfma_f32_16x16x32_bf16 v[66:69], v[180:183], v[244:247], v[66:69]
	s_barrier
; #define PG8_STAGE(bufoff, gbase, voff) do { _Pragma("unroll") for (int _i = 0; _i < 2; ++_i) \
;         __builtin_amdgcn_global_load_lds((const unsigned*)((const char*)(gbase) + (voff)[_i]), (PG8_LAS unsigned*)(lds + (bufoff) + ldsw + _i * 8192), 16, 0, 0); } while (0)
; #define PG8_LDA(dst, b, h) do { _Pragma("unroll") for (int m = 0; m < 4; ++m) _Pragma("unroll") for (int k = 0; k < 2; ++k) dst[m][k] = *(const PG8_LAS bf16x8*)(lds + PG8_SA(b, h) + aoff + m * 2048 + k * 1024); } while (0)
; #define PG8_LDB(dst, b, h) do { _Pragma("unroll") for (int n = 0; n < 2; ++n) _Pragma("unroll") for (int k = 0; k < 2; ++k) dst[n][k] = *(const PG8_LAS bf16x8*)(lds + PG8_SB(b, h) + boff + n * 2048 + k * 1024); } while (0)
; #define PG8_MMA(ai, bj, At, Bt) do { __builtin_amdgcn_s_setprio(1); _Pragma("unroll") for (int m = 0; m < 4; ++m) _Pragma("unroll") for (int n = 0; n < 2; ++n) _Pragma("unroll") for (int k = 0; k < 2; ++k) \
;         acc[ai][bj][m][n] = __builtin_amdgcn_mfma_f32_16x16x32_bf16(Bt[n][k], At[m][k], acc[ai][bj][m][n], 0, 0, 0); __builtin_amdgcn_s_setprio(0); } while (0)
; #define PG8_WAIT_V(n) asm volatile("s_waitcnt vmcnt(" #n ")" ::: "memory")
; #define PG8_WAIT_L(n) asm volatile("s_waitcnt lgkmcnt(" #n ")" ::: "memory")
; #define PG8_BAR __builtin_amdgcn_s_barrier()
; #define PG8_SCHED __builtin_amdgcn_sched_barrier(0)
; template <class Epi, class Sched, bool ALIGN_EPI = false, bool SP2 = false>
; __device__ __forceinline__ void gemm_phase(PG8_LAS unsigned char* lds, const Gemm g, const Sched& S, const Epi& E) {
;     ...
;             const char* a1 = cA + (size_t)(t + 1) * kstep;
;             const char* a2 = last ? nA : cA + (size_t)(t + 2) * kstep; const char* b2 = last ? nB : cB + (size_t)(t + 2) * kstep;
;             const char* a3 = a2 + kstep; const char* b3 = b2 + kstep;
;             if (last && has_next) S.a_ready(nxt);
;             if constexpr (SP2) {
;             PG8_LDB(B0, 0, 0); PG8_LDB(B1, 0, 1); PG8_SCHED; PG8_LDA(At, 0, 0); PG8_STAGE(PG8_SA(1, 1), a1 + hstep, voffA);
;     ...
;             PG8_LDA(At, 1, 1); PG8_STAGE(PG8_SB(1, 0), b3, voffB); PG8_STAGE(PG8_SB(1, 1), b3 + hstepB, voffB); PG8_STAGE(PG8_SA(1, 0), a3, voffA);
;             PG8_WAIT_V(8); PG8_WAIT_L(0); PG8_BAR; PG8_MMA(1, 0, At, B0); PG8_MMA(1, 1, At, B1); PG8_BAR; PG8_SCHED;
	ds_read_b128 v[194:197], v151 offset:49152
	ds_read_b128 v[206:209], v151 offset:50176
	ds_read_b128 v[210:213], v151 offset:51200
	ds_read_b128 v[214:217], v151 offset:52224
	ds_read_b128 v[218:221], v151 offset:53248
	ds_read_b128 v[236:239], v151 offset:54272
	ds_read_b128 v[240:243], v151 offset:55296
	ds_read_b128 v[244:247], v151 offset:56320
	s_add_i32 s9, s9, s42
	s_mov_b32 m0, s9
	s_add_u32 s100, s84, s60
	s_addc_u32 s101, s85, s61
	global_load_lds_dwordx4 v130, s[100:101]
	s_add_i32 m0, s9, 0x2000
	s_add_u32 s10, s84, 0x20080
	s_addc_u32 s11, s85, 0
	s_add_i32 s9, s12, s42
	global_load_lds_dwordx4 v134, s[100:101]
	s_mov_b32 m0, s9
	s_nop 0
	global_load_lds_dwordx4 v130, s[10:11]
	s_add_i32 m0, s9, 0x2000
	s_nop 0
	global_load_lds_dwordx4 v134, s[10:11]
	s_mov_b32 m0, s82
	s_add_u32 s100, s92, s60
	s_addc_u32 s101, s93, s61
	global_load_lds_dwordx4 v190, s[100:101]
	s_mov_b32 m0, s86
	s_nop 0
	global_load_lds_dwordx4 v132, s[100:101]
	s_waitcnt vmcnt(8)
	s_waitcnt lgkmcnt(0)
	s_barrier
	v_mfma_f32_16x16x32_bf16 v[62:65], v[152:155], v[194:197], v[62:65]
	v_mfma_f32_16x16x32_bf16 v[58:61], v[160:163], v[194:197], v[58:61]
	v_mfma_f32_16x16x32_bf16 v[54:57], v[152:155], v[210:213], v[54:57]
	v_mfma_f32_16x16x32_bf16 v[50:53], v[160:163], v[210:213], v[50:53]
	v_mfma_f32_16x16x32_bf16 v[46:49], v[152:155], v[218:221], v[46:49]
	v_mfma_f32_16x16x32_bf16 v[42:45], v[160:163], v[218:221], v[42:45]
	v_mfma_f32_16x16x32_bf16 v[38:41], v[152:155], v[240:243], v[38:41]
	v_mfma_f32_16x16x32_bf16 v[34:37], v[160:163], v[240:243], v[34:37]
	v_mfma_f32_16x16x32_bf16 v[62:65], v[156:159], v[206:209], v[62:65]
	v_mfma_f32_16x16x32_bf16 v[58:61], v[164:167], v[206:209], v[58:61]
	v_mfma_f32_16x16x32_bf16 v[54:57], v[156:159], v[214:217], v[54:57]
	v_mfma_f32_16x16x32_bf16 v[50:53], v[164:167], v[214:217], v[50:53]
	v_mfma_f32_16x16x32_bf16 v[46:49], v[156:159], v[236:239], v[46:49]
	v_mfma_f32_16x16x32_bf16 v[42:45], v[164:167], v[236:239], v[42:45]
	v_mfma_f32_16x16x32_bf16 v[38:41], v[156:159], v[244:247], v[38:41]
	v_mfma_f32_16x16x32_bf16 v[34:37], v[164:167], v[244:247], v[34:37]
	v_mfma_f32_16x16x32_bf16 v[30:33], v[168:171], v[194:197], v[30:33]
	v_mfma_f32_16x16x32_bf16 v[26:29], v[176:179], v[194:197], v[26:29]
	v_mfma_f32_16x16x32_bf16 v[22:25], v[168:171], v[210:213], v[22:25]
	v_mfma_f32_16x16x32_bf16 v[18:21], v[176:179], v[210:213], v[18:21]
	v_mfma_f32_16x16x32_bf16 v[14:17], v[168:171], v[218:221], v[14:17]
	v_mfma_f32_16x16x32_bf16 v[10:13], v[176:179], v[218:221], v[10:13]
	s_add_i32 s8, s8, 2
	v_mfma_f32_16x16x32_bf16 v[6:9], v[168:171], v[240:243], v[6:9]
	s_add_u32 s80, s80, 0x100
	s_addc_u32 s81, s81, 0
	v_mfma_f32_16x16x32_bf16 v[2:5], v[176:179], v[240:243], v[2:5]
	s_cmp_gt_u32 s8, 29
	v_mfma_f32_16x16x32_bf16 v[30:33], v[172:175], v[206:209], v[30:33]
	v_mfma_f32_16x16x32_bf16 v[26:29], v[180:183], v[206:209], v[26:29]
	v_mfma_f32_16x16x32_bf16 v[22:25], v[172:175], v[214:217], v[22:25]
	v_mfma_f32_16x16x32_bf16 v[18:21], v[180:183], v[214:217], v[18:21]
	v_mfma_f32_16x16x32_bf16 v[14:17], v[172:175], v[236:239], v[14:17]
	v_mfma_f32_16x16x32_bf16 v[10:13], v[180:183], v[236:239], v[10:13]
	v_mfma_f32_16x16x32_bf16 v[6:9], v[172:175], v[244:247], v[6:9]
	v_mfma_f32_16x16x32_bf16 v[2:5], v[180:183], v[244:247], v[2:5]
	s_barrier
.LBB0_1233:
	ds_read_b128 v[152:155], v186
	ds_read_b128 v[156:159], v186 offset:1024
	ds_read_b128 v[160:163], v186 offset:2048
	ds_read_b128 v[164:167], v186 offset:3072
	ds_read_b128 v[168:171], v187
	ds_read_b128 v[172:175], v187 offset:1024
	ds_read_b128 v[176:179], v187 offset:2048
	ds_read_b128 v[180:183], v187 offset:3072
	ds_read_b128 v[206:209], v151
	ds_read_b128 v[210:213], v151 offset:1024
	ds_read_b128 v[214:217], v151 offset:2048
	ds_read_b128 v[218:221], v151 offset:3072
	ds_read_b128 v[236:239], v151 offset:4096
	ds_read_b128 v[240:243], v151 offset:5120
	ds_read_b128 v[244:247], v151 offset:6144
	ds_read_b128 v[194:197], v151 offset:7168
	s_add_u32 s9, s68, s80
	s_addc_u32 s10, s69, s81
	s_add_u32 s9, s9, 0x100
	s_addc_u32 s10, s10, 0
	s_add_u32 s100, s9, 0x7ff80
	s_addc_u32 s101, s10, 0
	s_add_u32 s11, s36, s80
	s_addc_u32 s12, s37, s81
	s_add_i32 s13, 0, 0x10000
	s_cmpk_eq_i32 s80, 0xf00
	s_cselect_b32 s93, s4, s10
	s_cselect_b32 s92, s5, s9
	s_cselect_b32 s85, s6, s12
	s_cselect_b32 s84, s7, s11
	s_add_i32 s9, 0, 0x14000
	s_add_i32 m0, s51, 0xc000
	s_nop 0
	global_load_lds_dwordx4 v136, s[100:101]
	s_add_i32 m0, s51, 0xe000
	s_nop 0
	global_load_lds_dwordx4 v138, s[100:101]
	s_waitcnt vmcnt(8)
	s_waitcnt lgkmcnt(0)
	s_barrier
; #define PG8_STAGE(bufoff, gbase, voff) do { _Pragma("unroll") for (int _i = 0; _i < 2; ++_i) \
;         __builtin_amdgcn_global_load_lds((const unsigned*)((const char*)(gbase) + (voff)[_i]), (PG8_LAS unsigned*)(lds + (bufoff) + ldsw + _i * 8192), 16, 0, 0); } while (0)
; #define PG8_LDA(dst, b, h) do { _Pragma("unroll") for (int m = 0; m < 4; ++m) _Pragma("unroll") for (int k = 0; k < 2; ++k) dst[m][k] = *(const PG8_LAS bf16x8*)(lds + PG8_SA(b, h) + aoff + m * 2048 + k * 1024); } while (0)
; #define PG8_MMA(ai, bj, At, Bt) do { __builtin_amdgcn_s_setprio(1); _Pragma("unroll") for (int m = 0; m < 4; ++m) _Pragma("unroll") for (int n = 0; n < 2; ++n) _Pragma("unroll") for (int k = 0; k < 2; ++k) \
;         acc[ai][bj][m][n] = __builtin_amdgcn_mfma_f32_16x16x32_bf16(Bt[n][k], At[m][k], acc[ai][bj][m][n], 0, 0, 0); __builtin_amdgcn_s_setprio(0); } while (0)
; #define PG8_WAIT_V(n) asm volatile("s_waitcnt vmcnt(" #n ")" ::: "memory")
; #define PG8_WAIT_L(n) asm volatile("s_waitcnt lgkmcnt(" #n ")" ::: "memory")
; #define PG8_BAR __builtin_amdgcn_s_barrier()
; #define PG8_SCHED __builtin_amdgcn_sched_barrier(0)
; template <class Epi, class Sched, bool ALIGN_EPI = false, bool SP2 = false>
; __device__ __forceinline__ void gemm_phase(PG8_LAS unsigned char* lds, const Gemm g, const Sched& S, const Epi& E) {
;     ...
;             PG8_WAIT_V(8); PG8_WAIT_L(0); PG8_BAR; PG8_MMA(0, 0, At, B0); PG8_MMA(0, 1, At, B1); PG8_BAR; PG8_SCHED;
;             PG8_LDA(At, 0, 1); PG8_STAGE(PG8_SB(0, 0), b2, voffB); PG8_STAGE(PG8_SB(0, 1), b2 + hstepB, voffB); PG8_STAGE(PG8_SA(0, 0), a2, voffA);
;             PG8_WAIT_V(8); PG8_WAIT_L(0); PG8_BAR; PG8_MMA(1, 0, At, B0); PG8_MMA(1, 1, At, B1); PG8_BAR; PG8_SCHED;
	v_mfma_f32_16x16x32_bf16 v[126:129], v[152:155], v[206:209], v[126:129]
	v_mfma_f32_16x16x32_bf16 v[122:125], v[160:163], v[206:209], v[122:125]
	v_mfma_f32_16x16x32_bf16 v[118:121], v[152:155], v[214:217], v[118:121]
	v_mfma_f32_16x16x32_bf16 v[114:117], v[160:163], v[214:217], v[114:117]
	v_mfma_f32_16x16x32_bf16 v[110:113], v[152:155], v[236:239], v[110:113]
	v_mfma_f32_16x16x32_bf16 v[106:109], v[160:163], v[236:239], v[106:109]
	v_mfma_f32_16x16x32_bf16 v[102:105], v[152:155], v[244:247], v[102:105]
	v_mfma_f32_16x16x32_bf16 v[98:101], v[160:163], v[244:247], v[98:101]
	v_mfma_f32_16x16x32_bf16 v[126:129], v[156:159], v[210:213], v[126:129]
	v_mfma_f32_16x16x32_bf16 v[122:125], v[164:167], v[210:213], v[122:125]
	v_mfma_f32_16x16x32_bf16 v[118:121], v[156:159], v[218:221], v[118:121]
	v_mfma_f32_16x16x32_bf16 v[114:117], v[164:167], v[218:221], v[114:117]
	v_mfma_f32_16x16x32_bf16 v[110:113], v[156:159], v[240:243], v[110:113]
	v_mfma_f32_16x16x32_bf16 v[106:109], v[164:167], v[240:243], v[106:109]
	v_mfma_f32_16x16x32_bf16 v[102:105], v[156:159], v[194:197], v[102:105]
	v_mfma_f32_16x16x32_bf16 v[98:101], v[164:167], v[194:197], v[98:101]
	v_mfma_f32_16x16x32_bf16 v[94:97], v[168:171], v[206:209], v[94:97]
	v_mfma_f32_16x16x32_bf16 v[90:93], v[176:179], v[206:209], v[90:93]
	v_mfma_f32_16x16x32_bf16 v[86:89], v[168:171], v[214:217], v[86:89]
	v_mfma_f32_16x16x32_bf16 v[82:85], v[176:179], v[214:217], v[82:85]
	v_mfma_f32_16x16x32_bf16 v[78:81], v[168:171], v[236:239], v[78:81]
	v_mfma_f32_16x16x32_bf16 v[74:77], v[176:179], v[236:239], v[74:77]
	v_mfma_f32_16x16x32_bf16 v[70:73], v[168:171], v[244:247], v[70:73]
	v_mfma_f32_16x16x32_bf16 v[66:69], v[176:179], v[244:247], v[66:69]
	v_mfma_f32_16x16x32_bf16 v[94:97], v[172:175], v[210:213], v[94:97]
	v_mfma_f32_16x16x32_bf16 v[90:93], v[180:183], v[210:213], v[90:93]
	v_mfma_f32_16x16x32_bf16 v[86:89], v[172:175], v[218:221], v[86:89]
	v_mfma_f32_16x16x32_bf16 v[82:85], v[180:183], v[218:221], v[82:85]
	v_mfma_f32_16x16x32_bf16 v[78:81], v[172:175], v[240:243], v[78:81]
	v_mfma_f32_16x16x32_bf16 v[74:77], v[180:183], v[240:243], v[74:77]
	v_mfma_f32_16x16x32_bf16 v[70:73], v[172:175], v[194:197], v[70:73]
	v_mfma_f32_16x16x32_bf16 v[66:69], v[180:183], v[194:197], v[66:69]
	s_barrier
	ds_read_b128 v[194:197], v151 offset:16384
	ds_read_b128 v[206:209], v151 offset:17408
	ds_read_b128 v[210:213], v151 offset:18432
	ds_read_b128 v[214:217], v151 offset:19456
	ds_read_b128 v[218:221], v151 offset:20480
	ds_read_b128 v[236:239], v151 offset:21504
	ds_read_b128 v[240:243], v151 offset:22528
	ds_read_b128 v[244:247], v151 offset:23552
	s_add_i32 s10, s13, s42
	s_mov_b32 m0, s10
	s_nop 0
	global_load_lds_dwordx4 v130, s[84:85]
	s_add_i32 m0, s10, 0x2000
	s_add_u32 s10, s84, 0x20000
	s_addc_u32 s11, s85, 0
	s_add_i32 s9, s9, s42
	global_load_lds_dwordx4 v134, s[84:85]
	s_mov_b32 m0, s9
	s_nop 0
	global_load_lds_dwordx4 v130, s[10:11]
	s_add_i32 m0, s9, 0x2000
	s_nop 0
	global_load_lds_dwordx4 v134, s[10:11]
	s_mov_b32 m0, s51
	s_nop 0
	global_load_lds_dwordx4 v190, s[92:93]
	s_mov_b32 m0, s67
	s_nop 0
	global_load_lds_dwordx4 v132, s[92:93]
	s_waitcnt vmcnt(8)
	s_waitcnt lgkmcnt(0)
	s_barrier
	v_mfma_f32_16x16x32_bf16 v[62:65], v[152:155], v[194:197], v[62:65]
	v_mfma_f32_16x16x32_bf16 v[58:61], v[160:163], v[194:197], v[58:61]
	v_mfma_f32_16x16x32_bf16 v[54:57], v[152:155], v[210:213], v[54:57]
	v_mfma_f32_16x16x32_bf16 v[50:53], v[160:163], v[210:213], v[50:53]
	v_mfma_f32_16x16x32_bf16 v[46:49], v[152:155], v[218:221], v[46:49]
	v_mfma_f32_16x16x32_bf16 v[42:45], v[160:163], v[218:221], v[42:45]
	v_mfma_f32_16x16x32_bf16 v[38:41], v[152:155], v[240:243], v[38:41]
	v_mfma_f32_16x16x32_bf16 v[34:37], v[160:163], v[240:243], v[34:37]
	v_mfma_f32_16x16x32_bf16 v[62:65], v[156:159], v[206:209], v[62:65]
	v_mfma_f32_16x16x32_bf16 v[58:61], v[164:167], v[206:209], v[58:61]
	v_mfma_f32_16x16x32_bf16 v[54:57], v[156:159], v[214:217], v[54:57]
	v_mfma_f32_16x16x32_bf16 v[50:53], v[164:167], v[214:217], v[50:53]
	v_mfma_f32_16x16x32_bf16 v[46:49], v[156:159], v[236:239], v[46:49]
	v_mfma_f32_16x16x32_bf16 v[42:45], v[164:167], v[236:239], v[42:45]
	v_mfma_f32_16x16x32_bf16 v[38:41], v[156:159], v[244:247], v[38:41]
	v_mfma_f32_16x16x32_bf16 v[34:37], v[164:167], v[244:247], v[34:37]
	v_mfma_f32_16x16x32_bf16 v[30:33], v[168:171], v[194:197], v[30:33]
	v_mfma_f32_16x16x32_bf16 v[26:29], v[176:179], v[194:197], v[26:29]
	v_mfma_f32_16x16x32_bf16 v[22:25], v[168:171], v[210:213], v[22:25]
	v_mfma_f32_16x16x32_bf16 v[18:21], v[176:179], v[210:213], v[18:21]
	v_mfma_f32_16x16x32_bf16 v[14:17], v[168:171], v[218:221], v[14:17]
	v_mfma_f32_16x16x32_bf16 v[10:13], v[176:179], v[218:221], v[10:13]
	v_mfma_f32_16x16x32_bf16 v[6:9], v[168:171], v[240:243], v[6:9]
	v_mfma_f32_16x16x32_bf16 v[2:5], v[176:179], v[240:243], v[2:5]
	v_mfma_f32_16x16x32_bf16 v[30:33], v[172:175], v[206:209], v[30:33]
	v_mfma_f32_16x16x32_bf16 v[26:29], v[180:183], v[206:209], v[26:29]
	v_mfma_f32_16x16x32_bf16 v[22:25], v[172:175], v[214:217], v[22:25]
	v_mfma_f32_16x16x32_bf16 v[18:21], v[180:183], v[214:217], v[18:21]
	v_mfma_f32_16x16x32_bf16 v[14:17], v[172:175], v[236:239], v[14:17]
	v_mfma_f32_16x16x32_bf16 v[10:13], v[180:183], v[236:239], v[10:13]
	v_mfma_f32_16x16x32_bf16 v[6:9], v[172:175], v[244:247], v[6:9]
	v_mfma_f32_16x16x32_bf16 v[2:5], v[180:183], v[244:247], v[2:5]
	s_barrier
; #define PG8_STAGE(bufoff, gbase, voff) do { _Pragma("unroll") for (int _i = 0; _i < 2; ++_i) \
;         __builtin_amdgcn_global_load_lds((const unsigned*)((const char*)(gbase) + (voff)[_i]), (PG8_LAS unsigned*)(lds + (bufoff) + ldsw + _i * 8192), 16, 0, 0); } while (0)
; #define PG8_LDA(dst, b, h) do { _Pragma("unroll") for (int m = 0; m < 4; ++m) _Pragma("unroll") for (int k = 0; k < 2; ++k) dst[m][k] = *(const PG8_LAS bf16x8*)(lds + PG8_SA(b, h) + aoff + m * 2048 + k * 1024); } while (0)
; #define PG8_LDB(dst, b, h) do { _Pragma("unroll") for (int n = 0; n < 2; ++n) _Pragma("unroll") for (int k = 0; k < 2; ++k) dst[n][k] = *(const PG8_LAS bf16x8*)(lds + PG8_SB(b, h) + boff + n * 2048 + k * 1024); } while (0)
; #define PG8_MMA(ai, bj, At, Bt) do { __builtin_amdgcn_s_setprio(1); _Pragma("unroll") for (int m = 0; m < 4; ++m) _Pragma("unroll") for (int n = 0; n < 2; ++n) _Pragma("unroll") for (int k = 0; k < 2; ++k) \
;         acc[ai][bj][m][n] = __builtin_amdgcn_mfma_f32_16x16x32_bf16(Bt[n][k], At[m][k], acc[ai][bj][m][n], 0, 0, 0); __builtin_amdgcn_s_setprio(0); } while (0)
; #define PG8_WAIT_V(n) asm volatile("s_waitcnt vmcnt(" #n ")" ::: "memory")
; #define PG8_WAIT_L(n) asm volatile("s_waitcnt lgkmcnt(" #n ")" ::: "memory")
; #define PG8_BAR __builtin_amdgcn_s_barrier()
; #define PG8_SCHED __builtin_amdgcn_sched_barrier(0)
; template <class Epi, class Sched, bool ALIGN_EPI = false, bool SP2 = false>
; __device__ __forceinline__ void gemm_phase(PG8_LAS unsigned char* lds, const Gemm g, const Sched& S, const Epi& E) {
;     ...
;             PG8_LDB(B0, 1, 0); PG8_LDB(B1, 1, 1); PG8_SCHED; PG8_LDA(At, 1, 0); PG8_STAGE(PG8_SA(0, 1), a2 + hstep, voffA);
;             PG8_WAIT_V(8); PG8_WAIT_L(0); PG8_BAR; PG8_MMA(0, 0, At, B0); PG8_MMA(0, 1, At, B1); PG8_BAR; PG8_SCHED;
;             PG8_LDA(At, 1, 1); PG8_STAGE(PG8_SB(1, 0), b3, voffB); PG8_STAGE(PG8_SB(1, 1), b3 + hstepB, voffB); PG8_STAGE(PG8_SA(1, 0), a3, voffA);
;             PG8_WAIT_V(8); PG8_WAIT_L(0); PG8_BAR; PG8_MMA(1, 0, At, B0); PG8_MMA(1, 1, At, B1); PG8_BAR; PG8_SCHED;
	ds_read_b128 v[152:155], v198
	ds_read_b128 v[156:159], v198 offset:1024
	ds_read_b128 v[160:163], v198 offset:2048
	ds_read_b128 v[164:167], v198 offset:3072
	ds_read_b128 v[168:171], v199
	ds_read_b128 v[172:175], v199 offset:1024
	ds_read_b128 v[176:179], v199 offset:2048
	ds_read_b128 v[180:183], v199 offset:3072
	ds_read_b128 v[194:197], v151 offset:32768
	ds_read_b128 v[206:209], v151 offset:33792
	ds_read_b128 v[210:213], v151 offset:34816
	ds_read_b128 v[214:217], v151 offset:35840
	ds_read_b128 v[218:221], v151 offset:36864
	ds_read_b128 v[236:239], v151 offset:37888
	ds_read_b128 v[240:243], v151 offset:38912
	ds_read_b128 v[244:247], v151 offset:39936
	s_add_i32 s9, 0, 0x18000
	s_add_i32 s12, 0, 0x1c000
	s_add_u32 s10, s92, 0x80000
	s_addc_u32 s11, s93, 0
	s_mov_b32 m0, s74
	s_nop 0
	global_load_lds_dwordx4 v190, s[10:11]
	s_mov_b32 m0, s75
	s_nop 0
	global_load_lds_dwordx4 v132, s[10:11]
	s_waitcnt vmcnt(8)
	s_waitcnt lgkmcnt(0)
	s_barrier
	v_mfma_f32_16x16x32_bf16 v[126:129], v[152:155], v[194:197], v[126:129]
	v_mfma_f32_16x16x32_bf16 v[122:125], v[160:163], v[194:197], v[122:125]
	v_mfma_f32_16x16x32_bf16 v[118:121], v[152:155], v[210:213], v[118:121]
	v_mfma_f32_16x16x32_bf16 v[114:117], v[160:163], v[210:213], v[114:117]
	v_mfma_f32_16x16x32_bf16 v[110:113], v[152:155], v[218:221], v[110:113]
	v_mfma_f32_16x16x32_bf16 v[106:109], v[160:163], v[218:221], v[106:109]
	v_mfma_f32_16x16x32_bf16 v[102:105], v[152:155], v[240:243], v[102:105]
	v_mfma_f32_16x16x32_bf16 v[98:101], v[160:163], v[240:243], v[98:101]
	v_mfma_f32_16x16x32_bf16 v[126:129], v[156:159], v[206:209], v[126:129]
	v_mfma_f32_16x16x32_bf16 v[122:125], v[164:167], v[206:209], v[122:125]
	v_mfma_f32_16x16x32_bf16 v[118:121], v[156:159], v[214:217], v[118:121]
	v_mfma_f32_16x16x32_bf16 v[114:117], v[164:167], v[214:217], v[114:117]
	v_mfma_f32_16x16x32_bf16 v[110:113], v[156:159], v[236:239], v[110:113]
	v_mfma_f32_16x16x32_bf16 v[106:109], v[164:167], v[236:239], v[106:109]
	v_mfma_f32_16x16x32_bf16 v[102:105], v[156:159], v[244:247], v[102:105]
	v_mfma_f32_16x16x32_bf16 v[98:101], v[164:167], v[244:247], v[98:101]
	v_mfma_f32_16x16x32_bf16 v[94:97], v[168:171], v[194:197], v[94:97]
	v_mfma_f32_16x16x32_bf16 v[90:93], v[176:179], v[194:197], v[90:93]
	v_mfma_f32_16x16x32_bf16 v[86:89], v[168:171], v[210:213], v[86:89]
	v_mfma_f32_16x16x32_bf16 v[82:85], v[176:179], v[210:213], v[82:85]
	v_mfma_f32_16x16x32_bf16 v[78:81], v[168:171], v[218:221], v[78:81]
	v_mfma_f32_16x16x32_bf16 v[74:77], v[176:179], v[218:221], v[74:77]
	v_mfma_f32_16x16x32_bf16 v[70:73], v[168:171], v[240:243], v[70:73]
	v_mfma_f32_16x16x32_bf16 v[66:69], v[176:179], v[240:243], v[66:69]
	v_mfma_f32_16x16x32_bf16 v[94:97], v[172:175], v[206:209], v[94:97]
	v_mfma_f32_16x16x32_bf16 v[90:93], v[180:183], v[206:209], v[90:93]
	v_mfma_f32_16x16x32_bf16 v[86:89], v[172:175], v[214:217], v[86:89]
	v_mfma_f32_16x16x32_bf16 v[82:85], v[180:183], v[214:217], v[82:85]
	v_mfma_f32_16x16x32_bf16 v[78:81], v[172:175], v[236:239], v[78:81]
	v_mfma_f32_16x16x32_bf16 v[74:77], v[180:183], v[236:239], v[74:77]
	v_mfma_f32_16x16x32_bf16 v[70:73], v[172:175], v[244:247], v[70:73]
	v_mfma_f32_16x16x32_bf16 v[66:69], v[180:183], v[244:247], v[66:69]
	s_barrier
	ds_read_b128 v[194:197], v151 offset:49152
	ds_read_b128 v[206:209], v151 offset:50176
	ds_read_b128 v[210:213], v151 offset:51200
	ds_read_b128 v[214:217], v151 offset:52224
	ds_read_b128 v[218:221], v151 offset:53248
	ds_read_b128 v[236:239], v151 offset:54272
	ds_read_b128 v[240:243], v151 offset:55296
	ds_read_b128 v[244:247], v151 offset:56320
	s_add_i32 s9, s9, s42
	s_mov_b32 m0, s9
	s_add_u32 s100, s84, s60
	s_addc_u32 s101, s85, s61
	global_load_lds_dwordx4 v130, s[100:101]
	s_add_i32 m0, s9, 0x2000
	s_add_u32 s10, s84, 0x20080
	s_addc_u32 s11, s85, 0
	s_add_i32 s9, s12, s42
	global_load_lds_dwordx4 v134, s[100:101]
	s_mov_b32 m0, s9
	s_nop 0
	global_load_lds_dwordx4 v130, s[10:11]
	s_add_i32 m0, s9, 0x2000
	s_nop 0
	global_load_lds_dwordx4 v134, s[10:11]
	s_mov_b32 m0, s82
	s_add_u32 s100, s92, s60
	s_addc_u32 s101, s93, s61
	global_load_lds_dwordx4 v190, s[100:101]
	s_mov_b32 m0, s86
	s_nop 0
	global_load_lds_dwordx4 v132, s[100:101]
	s_waitcnt vmcnt(8)
	s_waitcnt lgkmcnt(0)
	s_barrier
	v_mfma_f32_16x16x32_bf16 v[62:65], v[152:155], v[194:197], v[62:65]
	v_mfma_f32_16x16x32_bf16 v[58:61], v[160:163], v[194:197], v[58:61]
	v_mfma_f32_16x16x32_bf16 v[54:57], v[152:155], v[210:213], v[54:57]
	v_mfma_f32_16x16x32_bf16 v[50:53], v[160:163], v[210:213], v[50:53]
	v_mfma_f32_16x16x32_bf16 v[46:49], v[152:155], v[218:221], v[46:49]
	v_mfma_f32_16x16x32_bf16 v[42:45], v[160:163], v[218:221], v[42:45]
	v_mfma_f32_16x16x32_bf16 v[38:41], v[152:155], v[240:243], v[38:41]
	v_mfma_f32_16x16x32_bf16 v[34:37], v[160:163], v[240:243], v[34:37]
	v_mfma_f32_16x16x32_bf16 v[62:65], v[156:159], v[206:209], v[62:65]
	v_mfma_f32_16x16x32_bf16 v[58:61], v[164:167], v[206:209], v[58:61]
	v_mfma_f32_16x16x32_bf16 v[54:57], v[156:159], v[214:217], v[54:57]
	v_mfma_f32_16x16x32_bf16 v[50:53], v[164:167], v[214:217], v[50:53]
	v_mfma_f32_16x16x32_bf16 v[46:49], v[156:159], v[236:239], v[46:49]
	v_mfma_f32_16x16x32_bf16 v[42:45], v[164:167], v[236:239], v[42:45]
	v_mfma_f32_16x16x32_bf16 v[38:41], v[156:159], v[244:247], v[38:41]
	v_mfma_f32_16x16x32_bf16 v[34:37], v[164:167], v[244:247], v[34:37]
	v_mfma_f32_16x16x32_bf16 v[30:33], v[168:171], v[194:197], v[30:33]
	v_mfma_f32_16x16x32_bf16 v[26:29], v[176:179], v[194:197], v[26:29]
	v_mfma_f32_16x16x32_bf16 v[22:25], v[168:171], v[210:213], v[22:25]
	v_mfma_f32_16x16x32_bf16 v[18:21], v[176:179], v[210:213], v[18:21]
	v_mfma_f32_16x16x32_bf16 v[14:17], v[168:171], v[218:221], v[14:17]
	v_mfma_f32_16x16x32_bf16 v[10:13], v[176:179], v[218:221], v[10:13]
	s_add_i32 s8, s8, 2
	v_mfma_f32_16x16x32_bf16 v[6:9], v[168:171], v[240:243], v[6:9]
	s_add_u32 s80, s80, 0x100
	s_addc_u32 s81, s81, 0
	v_mfma_f32_16x16x32_bf16 v[2:5], v[176:179], v[240:243], v[2:5]
	s_cmp_gt_u32 s8, 29
	v_mfma_f32_16x16x32_bf16 v[30:33], v[172:175], v[206:209], v[30:33]
	v_mfma_f32_16x16x32_bf16 v[26:29], v[180:183], v[206:209], v[26:29]
	v_mfma_f32_16x16x32_bf16 v[22:25], v[172:175], v[214:217], v[22:25]
	v_mfma_f32_16x16x32_bf16 v[18:21], v[180:183], v[214:217], v[18:21]
	v_mfma_f32_16x16x32_bf16 v[14:17], v[172:175], v[236:239], v[14:17]
	v_mfma_f32_16x16x32_bf16 v[10:13], v[180:183], v[236:239], v[10:13]
	v_mfma_f32_16x16x32_bf16 v[6:9], v[172:175], v[244:247], v[6:9]
	v_mfma_f32_16x16x32_bf16 v[2:5], v[180:183], v[244:247], v[2:5]
	s_barrier
	s_cbranch_scc0 .LBB0_1233
	s_and_b64 vcc, exec, s[62:63]
	s_cbranch_vccz .LBB0_1236
	s_barrier
